# stacked: setprio raised before the pre-MFMA barrier and redundant lgkmcnt wait dropped in all GEMM K-loops; same-accumulator MFMA pairs made adjacent; M-major tile order for the down-proj GEMM; nt sto
# speedup vs baseline: 1.0173x; 1.0108x over previous
; #define PG8_STAGE(bufoff, gbase, voff) do { _Pragma("unroll") for (int _i = 0; _i < 2; ++_i) \
;         __builtin_amdgcn_global_load_lds((const unsigned*)((const char*)(gbase) + (voff)[_i]), (LAS unsigned*)(lds + (bufoff) + ldsw + _i * 8192), 16, 0, 0); } while (0)
; #define PG8_LDA(dst, b, h) do { _Pragma("unroll") for (int m = 0; m < 4; ++m) _Pragma("unroll") for (int k = 0; k < 2; ++k) dst[m][k] = *(const LAS bf16x8*)(lds + PG8_SA(b, h) + aoff + m * 2048 + k * 1024); } while (0)
; #define PG8_LDB(dst, b, h) do { _Pragma("unroll") for (int n = 0; n < 2; ++n) _Pragma("unroll") for (int k = 0; k < 2; ++k) dst[n][k] = *(const LAS bf16x8*)(lds + PG8_SB(b, h) + boff + n * 2048 + k * 1024); } while (0)
; #define PG8_MMA(ai, bj, At, Bt) do { __builtin_amdgcn_s_setprio(1); _Pragma("unroll") for (int m = 0; m < 4; ++m) _Pragma("unroll") for (int n = 0; n < 2; ++n) _Pragma("unroll") for (int k = 0; k < 2; ++k) \
;         acc[ai][bj][m][n] = __builtin_amdgcn_mfma_f32_16x16x32_bf16(Bt[n][k], At[m][k], acc[ai][bj][m][n], 0, 0, 0); __builtin_amdgcn_s_setprio(0); } while (0)
; #define PG8_WAIT_V(n) asm volatile("s_waitcnt vmcnt(" #n ")" ::: "memory")
; template <class Epi>
; DI void gemm_phase(LAS unsigned char* lds, const Gemm g, const StaticOrder& S, const Epi& E) {
;     ...
;         for (int t = 0; t < nt; t += 2) {
;             const bool last = (t == nt - 2);
;             const char* a1 = cA + (size_t)(t + 1) * kstep;
;             const char* a2 = last ? nA : cA + (size_t)(t + 2) * kstep; const char* b2 = last ? nB : cB + (size_t)(t + 2) * kstep;
;             const char* a3 = a2 + kstep; const char* b3 = b2 + kstep;
;             PG8_LDB(B0, 0, 0); PG8_LDB(B1, 0, 1); PG8_SCHED; PG8_LDA(At, 0, 0); PG8_STAGE(PG8_SA(1, 1), a1 + hstepA, voffA);
;             PG8_WAIT_V(8); PG8_WAIT_L(0); PG8_BAR; PG8_MMA(0, 0, At, B0); PG8_MMA(0, 1, At, B1); PG8_BAR; PG8_SCHED;
;             PG8_LDA(At, 0, 1); PG8_STAGE(PG8_SB(0, 0), b2, voffB); PG8_STAGE(PG8_SB(0, 1), b2 + hstepB, voffB); PG8_STAGE(PG8_SA(0, 0), a2, voffA);
;             PG8_WAIT_V(8); PG8_WAIT_L(0); PG8_BAR; PG8_MMA(1, 0, At, B0); PG8_MMA(1, 1, At, B1); PG8_BAR; PG8_SCHED;
;             PG8_LDB(B0, 1, 0); PG8_LDB(B1, 1, 1); PG8_SCHED; PG8_LDA(At, 1, 0); PG8_STAGE(PG8_SA(0, 1), a2 + hstepA, voffA);
;             PG8_WAIT_V(8); PG8_WAIT_L(0); PG8_BAR; PG8_MMA(0, 0, At, B0); PG8_MMA(0, 1, At, B1); PG8_BAR; PG8_SCHED;
.LBB0_161:
	ds_read_b128 v[154:157], v150
	ds_read_b128 v[158:161], v150 offset:1024
	ds_read_b128 v[162:165], v150 offset:2048
	ds_read_b128 v[166:169], v150 offset:3072
	ds_read_b128 v[170:173], v151
	ds_read_b128 v[174:177], v151 offset:1024
	ds_read_b128 v[182:185], v151 offset:2048
	ds_read_b128 v[186:189], v151 offset:3072
	s_add_i32 s64, s34, 2
	s_add_u32 s35, s30, 0xfff00080
	s_addc_u32 s38, s31, -1
	s_cmp_eq_u32 s53, s34
	s_cselect_b32 s34, s29, s62
	s_cselect_b32 s39, s19, s38
	s_cselect_b32 s38, s21, s35
	s_cselect_b32 s35, s27, s63
	v_lshl_add_u64 v[146:147], s[30:31], 0, v[138:139]
	s_add_i32 m0, s41, 0xc000
	ds_read_b128 v[190:193], v152
	ds_read_b128 v[194:197], v152 offset:1024
	ds_read_b128 v[198:201], v152 offset:2048
	ds_read_b128 v[202:205], v152 offset:3072
	ds_read_b128 v[206:209], v152 offset:4096
	ds_read_b128 v[210:213], v152 offset:5120
	ds_read_b128 v[214:217], v152 offset:6144
	ds_read_b128 v[218:221], v152 offset:7168
	global_load_lds_dwordx4 v[146:147], off
	v_lshl_add_u64 v[146:147], s[30:31], 0, v[140:141]
	s_add_i32 m0, s41, 0xe000
	s_nop 0
	global_load_lds_dwordx4 v[146:147], off
	s_waitcnt vmcnt(8)
	s_waitcnt lgkmcnt(0)
	s_setprio 1
	s_barrier
	v_mfma_f32_16x16x32_bf16 v[124:127], v[154:157], v[190:193], v[124:127]
	v_mfma_f32_16x16x32_bf16 v[124:127], v[158:161], v[194:197], v[124:127]
	v_mfma_f32_16x16x32_bf16 v[120:123], v[162:165], v[190:193], v[120:123]
	v_mfma_f32_16x16x32_bf16 v[120:123], v[166:169], v[194:197], v[120:123]
	v_mfma_f32_16x16x32_bf16 v[108:111], v[154:157], v[198:201], v[108:111]
	v_mfma_f32_16x16x32_bf16 v[108:111], v[158:161], v[202:205], v[108:111]
	v_mfma_f32_16x16x32_bf16 v[104:107], v[162:165], v[198:201], v[104:107]
	v_mfma_f32_16x16x32_bf16 v[104:107], v[166:169], v[202:205], v[104:107]
	v_mfma_f32_16x16x32_bf16 v[92:95], v[154:157], v[206:209], v[92:95]
	v_mfma_f32_16x16x32_bf16 v[92:95], v[158:161], v[210:213], v[92:95]
	v_mfma_f32_16x16x32_bf16 v[88:91], v[162:165], v[206:209], v[88:91]
	v_mfma_f32_16x16x32_bf16 v[88:91], v[166:169], v[210:213], v[88:91]
	v_mfma_f32_16x16x32_bf16 v[76:79], v[154:157], v[214:217], v[76:79]
	v_mfma_f32_16x16x32_bf16 v[76:79], v[158:161], v[218:221], v[76:79]
	v_mfma_f32_16x16x32_bf16 v[72:75], v[162:165], v[214:217], v[72:75]
	v_mfma_f32_16x16x32_bf16 v[72:75], v[166:169], v[218:221], v[72:75]
	s_setprio 0
	s_setprio 1
	v_mfma_f32_16x16x32_bf16 v[116:119], v[170:173], v[190:193], v[116:119]
	v_mfma_f32_16x16x32_bf16 v[116:119], v[174:177], v[194:197], v[116:119]
	v_mfma_f32_16x16x32_bf16 v[112:115], v[182:185], v[190:193], v[112:115]
	v_mfma_f32_16x16x32_bf16 v[112:115], v[186:189], v[194:197], v[112:115]
	v_mfma_f32_16x16x32_bf16 v[100:103], v[170:173], v[198:201], v[100:103]
	v_mfma_f32_16x16x32_bf16 v[100:103], v[174:177], v[202:205], v[100:103]
	v_mfma_f32_16x16x32_bf16 v[96:99], v[182:185], v[198:201], v[96:99]
	v_mfma_f32_16x16x32_bf16 v[96:99], v[186:189], v[202:205], v[96:99]
	v_mfma_f32_16x16x32_bf16 v[84:87], v[170:173], v[206:209], v[84:87]
	v_mfma_f32_16x16x32_bf16 v[84:87], v[174:177], v[210:213], v[84:87]
	v_mfma_f32_16x16x32_bf16 v[80:83], v[182:185], v[206:209], v[80:83]
	v_mfma_f32_16x16x32_bf16 v[80:83], v[186:189], v[210:213], v[80:83]
	v_mfma_f32_16x16x32_bf16 v[68:71], v[170:173], v[214:217], v[68:71]
	v_mfma_f32_16x16x32_bf16 v[68:71], v[174:177], v[218:221], v[68:71]
	v_mfma_f32_16x16x32_bf16 v[64:67], v[182:185], v[214:217], v[64:67]
	v_mfma_f32_16x16x32_bf16 v[64:67], v[186:189], v[218:221], v[64:67]
	s_setprio 0
	s_barrier
	s_add_i32 s65, s58, s40
	v_lshl_add_u64 v[146:147], s[34:35], 0, v[130:131]
	s_mov_b32 m0, s65
	ds_read_b128 v[190:193], v152 offset:16384
	ds_read_b128 v[194:197], v152 offset:17408
	ds_read_b128 v[198:201], v152 offset:18432
	ds_read_b128 v[202:205], v152 offset:19456
	ds_read_b128 v[206:209], v152 offset:20480
	ds_read_b128 v[210:213], v152 offset:21504
	ds_read_b128 v[214:217], v152 offset:22528
	ds_read_b128 v[218:221], v152 offset:23552
	global_load_lds_dwordx4 v[146:147], off
	s_add_i32 m0, s65, 0x2000
	s_add_u32 s66, s34, 0x100000
	v_lshl_add_u64 v[178:179], s[34:35], 0, v[134:135]
	s_addc_u32 s67, s35, 0
	s_add_i32 s65, s59, s40
	global_load_lds_dwordx4 v[178:179], off
	v_lshl_add_u64 v[222:223], s[66:67], 0, v[130:131]
	s_mov_b32 m0, s65
	v_lshl_add_u64 v[224:225], s[38:39], 0, v[132:133]
	global_load_lds_dwordx4 v[222:223], off
	v_lshl_add_u64 v[222:223], s[66:67], 0, v[134:135]
	s_add_i32 m0, s65, 0x2000
	s_nop 0
	global_load_lds_dwordx4 v[222:223], off
	v_lshl_add_u64 v[222:223], s[38:39], 0, v[128:129]
	s_mov_b32 m0, s41
	s_nop 0
	global_load_lds_dwordx4 v[222:223], off
	s_mov_b32 m0, s42
	s_nop 0
	global_load_lds_dwordx4 v[224:225], off
	s_waitcnt vmcnt(8)
	s_waitcnt lgkmcnt(0)
	s_setprio 1
	s_barrier
; #define PG8_STAGE(bufoff, gbase, voff) do { _Pragma("unroll") for (int _i = 0; _i < 2; ++_i) \
;         __builtin_amdgcn_global_load_lds((const unsigned*)((const char*)(gbase) + (voff)[_i]), (LAS unsigned*)(lds + (bufoff) + ldsw + _i * 8192), 16, 0, 0); } while (0)
; #define PG8_LDA(dst, b, h) do { _Pragma("unroll") for (int m = 0; m < 4; ++m) _Pragma("unroll") for (int k = 0; k < 2; ++k) dst[m][k] = *(const LAS bf16x8*)(lds + PG8_SA(b, h) + aoff + m * 2048 + k * 1024); } while (0)
; #define PG8_LDB(dst, b, h) do { _Pragma("unroll") for (int n = 0; n < 2; ++n) _Pragma("unroll") for (int k = 0; k < 2; ++k) dst[n][k] = *(const LAS bf16x8*)(lds + PG8_SB(b, h) + boff + n * 2048 + k * 1024); } while (0)
; #define PG8_MMA(ai, bj, At, Bt) do { __builtin_amdgcn_s_setprio(1); _Pragma("unroll") for (int m = 0; m < 4; ++m) _Pragma("unroll") for (int n = 0; n < 2; ++n) _Pragma("unroll") for (int k = 0; k < 2; ++k) \
;         acc[ai][bj][m][n] = __builtin_amdgcn_mfma_f32_16x16x32_bf16(Bt[n][k], At[m][k], acc[ai][bj][m][n], 0, 0, 0); __builtin_amdgcn_s_setprio(0); } while (0)
; #define PG8_WAIT_V(n) asm volatile("s_waitcnt vmcnt(" #n ")" ::: "memory")
; #define PG8_WAIT_L(n) asm volatile("s_waitcnt lgkmcnt(" #n ")" ::: "memory")
; template <class Epi>
; DI void gemm_phase(LAS unsigned char* lds, const Gemm g, const StaticOrder& S, const Epi& E) {
;     ...
;             PG8_LDB(B0, 0, 0); PG8_LDB(B1, 0, 1); PG8_SCHED; PG8_LDA(At, 0, 0); PG8_STAGE(PG8_SA(1, 1), a1 + hstepA, voffA);
;             PG8_WAIT_V(8); PG8_WAIT_L(0); PG8_BAR; PG8_MMA(0, 0, At, B0); PG8_MMA(0, 1, At, B1); PG8_BAR; PG8_SCHED;
;             PG8_LDA(At, 0, 1); PG8_STAGE(PG8_SB(0, 0), b2, voffB); PG8_STAGE(PG8_SB(0, 1), b2 + hstepB, voffB); PG8_STAGE(PG8_SA(0, 0), a2, voffA);
;             PG8_WAIT_V(8); PG8_WAIT_L(0); PG8_BAR; PG8_MMA(1, 0, At, B0); PG8_MMA(1, 1, At, B1); PG8_BAR; PG8_SCHED;
;             PG8_LDB(B0, 1, 0); PG8_LDB(B1, 1, 1); PG8_SCHED; PG8_LDA(At, 1, 0); PG8_STAGE(PG8_SA(0, 1), a2 + hstepA, voffA);
;             PG8_WAIT_V(8); PG8_WAIT_L(0); PG8_BAR; PG8_MMA(0, 0, At, B0); PG8_MMA(0, 1, At, B1); PG8_BAR; PG8_SCHED;
;             PG8_LDA(At, 1, 1); PG8_STAGE(PG8_SB(1, 0), b3, voffB); PG8_STAGE(PG8_SB(1, 1), b3 + hstepB, voffB); PG8_STAGE(PG8_SA(1, 0), a3, voffA);
;             PG8_WAIT_V(8); PG8_WAIT_L(0); PG8_BAR; PG8_MMA(1, 0, At, B0); PG8_MMA(1, 1, At, B1); PG8_BAR; PG8_SCHED;
	v_mfma_f32_16x16x32_bf16 v[60:63], v[154:157], v[190:193], v[60:63]
	v_mfma_f32_16x16x32_bf16 v[60:63], v[158:161], v[194:197], v[60:63]
	v_mfma_f32_16x16x32_bf16 v[56:59], v[162:165], v[190:193], v[56:59]
	v_mfma_f32_16x16x32_bf16 v[56:59], v[166:169], v[194:197], v[56:59]
	v_mfma_f32_16x16x32_bf16 v[44:47], v[154:157], v[198:201], v[44:47]
	v_mfma_f32_16x16x32_bf16 v[44:47], v[158:161], v[202:205], v[44:47]
	v_mfma_f32_16x16x32_bf16 v[40:43], v[162:165], v[198:201], v[40:43]
	v_mfma_f32_16x16x32_bf16 v[40:43], v[166:169], v[202:205], v[40:43]
	v_mfma_f32_16x16x32_bf16 v[28:31], v[154:157], v[206:209], v[28:31]
	v_mfma_f32_16x16x32_bf16 v[28:31], v[158:161], v[210:213], v[28:31]
	v_mfma_f32_16x16x32_bf16 v[24:27], v[162:165], v[206:209], v[24:27]
	v_mfma_f32_16x16x32_bf16 v[24:27], v[166:169], v[210:213], v[24:27]
	v_mfma_f32_16x16x32_bf16 v[12:15], v[154:157], v[214:217], v[12:15]
	v_mfma_f32_16x16x32_bf16 v[12:15], v[158:161], v[218:221], v[12:15]
	v_mfma_f32_16x16x32_bf16 v[8:11], v[162:165], v[214:217], v[8:11]
	v_mfma_f32_16x16x32_bf16 v[8:11], v[166:169], v[218:221], v[8:11]
	s_setprio 0
	s_setprio 1
	v_mfma_f32_16x16x32_bf16 v[52:55], v[170:173], v[190:193], v[52:55]
	v_mfma_f32_16x16x32_bf16 v[52:55], v[174:177], v[194:197], v[52:55]
	v_mfma_f32_16x16x32_bf16 v[48:51], v[182:185], v[190:193], v[48:51]
	v_mfma_f32_16x16x32_bf16 v[48:51], v[186:189], v[194:197], v[48:51]
	v_mfma_f32_16x16x32_bf16 v[36:39], v[170:173], v[198:201], v[36:39]
	v_mfma_f32_16x16x32_bf16 v[36:39], v[174:177], v[202:205], v[36:39]
	v_mfma_f32_16x16x32_bf16 v[32:35], v[182:185], v[198:201], v[32:35]
	v_mfma_f32_16x16x32_bf16 v[32:35], v[186:189], v[202:205], v[32:35]
	v_mfma_f32_16x16x32_bf16 v[20:23], v[170:173], v[206:209], v[20:23]
	v_mfma_f32_16x16x32_bf16 v[20:23], v[174:177], v[210:213], v[20:23]
	v_mfma_f32_16x16x32_bf16 v[16:19], v[182:185], v[206:209], v[16:19]
	v_mfma_f32_16x16x32_bf16 v[16:19], v[186:189], v[210:213], v[16:19]
	v_mfma_f32_16x16x32_bf16 v[4:7], v[170:173], v[214:217], v[4:7]
	v_mfma_f32_16x16x32_bf16 v[4:7], v[174:177], v[218:221], v[4:7]
	v_mfma_f32_16x16x32_bf16 v[0:3], v[182:185], v[214:217], v[0:3]
	v_mfma_f32_16x16x32_bf16 v[0:3], v[186:189], v[218:221], v[0:3]
	s_setprio 0
	s_barrier
	s_add_i32 s65, 0, 0x18000
	s_add_i32 s66, 0, 0x1c000
	v_add_u32_e32 v166, s65, v149
	v_add_u32_e32 v181, s66, v149
	ds_read_b128 v[154:157], v166
	ds_read_b128 v[158:161], v166 offset:1024
	ds_read_b128 v[162:165], v166 offset:2048
	ds_read_b128 v[166:169], v166 offset:3072
	ds_read_b128 v[170:173], v181
	ds_read_b128 v[174:177], v181 offset:1024
	ds_read_b128 v[182:185], v181 offset:2048
	ds_read_b128 v[186:189], v181 offset:3072
	s_add_u32 s38, s38, 0x100000
	s_addc_u32 s39, s39, 0
	s_mov_b32 m0, s43
	v_lshl_add_u64 v[226:227], s[38:39], 0, v[128:129]
	ds_read_b128 v[190:193], v152 offset:32768
	ds_read_b128 v[194:197], v152 offset:33792
	ds_read_b128 v[198:201], v152 offset:34816
	ds_read_b128 v[202:205], v152 offset:35840
	ds_read_b128 v[206:209], v152 offset:36864
	ds_read_b128 v[210:213], v152 offset:37888
	ds_read_b128 v[214:217], v152 offset:38912
	ds_read_b128 v[218:221], v152 offset:39936
	global_load_lds_dwordx4 v[226:227], off
	v_lshl_add_u64 v[226:227], s[38:39], 0, v[132:133]
	s_mov_b32 m0, s46
	s_nop 0
	global_load_lds_dwordx4 v[226:227], off
	s_waitcnt vmcnt(8)
	s_waitcnt lgkmcnt(0)
	s_setprio 1
	s_barrier
	v_mfma_f32_16x16x32_bf16 v[124:127], v[154:157], v[190:193], v[124:127]
	v_mfma_f32_16x16x32_bf16 v[124:127], v[158:161], v[194:197], v[124:127]
	v_mfma_f32_16x16x32_bf16 v[120:123], v[162:165], v[190:193], v[120:123]
	v_mfma_f32_16x16x32_bf16 v[120:123], v[166:169], v[194:197], v[120:123]
	v_mfma_f32_16x16x32_bf16 v[108:111], v[154:157], v[198:201], v[108:111]
	v_mfma_f32_16x16x32_bf16 v[108:111], v[158:161], v[202:205], v[108:111]
	v_mfma_f32_16x16x32_bf16 v[104:107], v[162:165], v[198:201], v[104:107]
	v_mfma_f32_16x16x32_bf16 v[104:107], v[166:169], v[202:205], v[104:107]
	v_mfma_f32_16x16x32_bf16 v[92:95], v[154:157], v[206:209], v[92:95]
	v_mfma_f32_16x16x32_bf16 v[92:95], v[158:161], v[210:213], v[92:95]
	v_mfma_f32_16x16x32_bf16 v[88:91], v[162:165], v[206:209], v[88:91]
	v_mfma_f32_16x16x32_bf16 v[88:91], v[166:169], v[210:213], v[88:91]
	v_mfma_f32_16x16x32_bf16 v[76:79], v[154:157], v[214:217], v[76:79]
	v_mfma_f32_16x16x32_bf16 v[76:79], v[158:161], v[218:221], v[76:79]
	v_mfma_f32_16x16x32_bf16 v[72:75], v[162:165], v[214:217], v[72:75]
	v_mfma_f32_16x16x32_bf16 v[72:75], v[166:169], v[218:221], v[72:75]
	s_setprio 0
	s_setprio 1
	v_mfma_f32_16x16x32_bf16 v[116:119], v[170:173], v[190:193], v[116:119]
	v_mfma_f32_16x16x32_bf16 v[116:119], v[174:177], v[194:197], v[116:119]
	v_mfma_f32_16x16x32_bf16 v[112:115], v[182:185], v[190:193], v[112:115]
	v_mfma_f32_16x16x32_bf16 v[112:115], v[186:189], v[194:197], v[112:115]
	v_mfma_f32_16x16x32_bf16 v[100:103], v[170:173], v[198:201], v[100:103]
	v_mfma_f32_16x16x32_bf16 v[100:103], v[174:177], v[202:205], v[100:103]
	v_mfma_f32_16x16x32_bf16 v[96:99], v[182:185], v[198:201], v[96:99]
	v_mfma_f32_16x16x32_bf16 v[96:99], v[186:189], v[202:205], v[96:99]
	v_mfma_f32_16x16x32_bf16 v[84:87], v[170:173], v[206:209], v[84:87]
	v_mfma_f32_16x16x32_bf16 v[84:87], v[174:177], v[210:213], v[84:87]
	v_mfma_f32_16x16x32_bf16 v[80:83], v[182:185], v[206:209], v[80:83]
	v_mfma_f32_16x16x32_bf16 v[80:83], v[186:189], v[210:213], v[80:83]
	v_mfma_f32_16x16x32_bf16 v[68:71], v[170:173], v[214:217], v[68:71]
	v_mfma_f32_16x16x32_bf16 v[68:71], v[174:177], v[218:221], v[68:71]
	v_mfma_f32_16x16x32_bf16 v[64:67], v[182:185], v[214:217], v[64:67]
	v_mfma_f32_16x16x32_bf16 v[64:67], v[186:189], v[218:221], v[64:67]
	s_setprio 0
	s_barrier
; #define PG8_STAGE(bufoff, gbase, voff) do { _Pragma("unroll") for (int _i = 0; _i < 2; ++_i) \
;         __builtin_amdgcn_global_load_lds((const unsigned*)((const char*)(gbase) + (voff)[_i]), (LAS unsigned*)(lds + (bufoff) + ldsw + _i * 8192), 16, 0, 0); } while (0)
; #define PG8_LDA(dst, b, h) do { _Pragma("unroll") for (int m = 0; m < 4; ++m) _Pragma("unroll") for (int k = 0; k < 2; ++k) dst[m][k] = *(const LAS bf16x8*)(lds + PG8_SA(b, h) + aoff + m * 2048 + k * 1024); } while (0)
; #define PG8_MMA(ai, bj, At, Bt) do { __builtin_amdgcn_s_setprio(1); _Pragma("unroll") for (int m = 0; m < 4; ++m) _Pragma("unroll") for (int n = 0; n < 2; ++n) _Pragma("unroll") for (int k = 0; k < 2; ++k) \
;         acc[ai][bj][m][n] = __builtin_amdgcn_mfma_f32_16x16x32_bf16(Bt[n][k], At[m][k], acc[ai][bj][m][n], 0, 0, 0); __builtin_amdgcn_s_setprio(0); } while (0)
; #define PG8_WAIT_V(n) asm volatile("s_waitcnt vmcnt(" #n ")" ::: "memory")
; #define PG8_WAIT_L(n) asm volatile("s_waitcnt lgkmcnt(" #n ")" ::: "memory")
; #define PG8_BAR __builtin_amdgcn_s_barrier()
; #define PG8_SCHED __builtin_amdgcn_sched_barrier(0)
; template <class Epi>
; DI void gemm_phase(LAS unsigned char* lds, const Gemm g, const StaticOrder& S, const Epi& E) {
;     ...
;         for (int t = 0; t < nt; t += 2) {
;     ...
;             PG8_LDA(At, 1, 1); PG8_STAGE(PG8_SB(1, 0), b3, voffB); PG8_STAGE(PG8_SB(1, 1), b3 + hstepB, voffB); PG8_STAGE(PG8_SA(1, 0), a3, voffA);
;             PG8_WAIT_V(8); PG8_WAIT_L(0); PG8_BAR; PG8_MMA(1, 0, At, B0); PG8_MMA(1, 1, At, B1); PG8_BAR; PG8_SCHED;
	s_add_i32 s38, s65, s40
	v_lshl_add_u64 v[146:147], v[146:147], 0, s[14:15]
	s_mov_b32 m0, s38
	ds_read_b128 v[190:193], v152 offset:49152
	ds_read_b128 v[194:197], v152 offset:50176
	ds_read_b128 v[198:201], v152 offset:51200
	ds_read_b128 v[202:205], v152 offset:52224
	ds_read_b128 v[206:209], v152 offset:53248
	ds_read_b128 v[210:213], v152 offset:54272
	ds_read_b128 v[214:217], v152 offset:55296
	ds_read_b128 v[218:221], v152 offset:56320
	global_load_lds_dwordx4 v[146:147], off
	s_add_i32 m0, s38, 0x2000
	s_add_u32 s34, s34, 0x100080
	v_lshl_add_u64 v[146:147], v[178:179], 0, s[14:15]
	s_addc_u32 s35, s35, 0
	s_add_i32 s38, s66, s40
	global_load_lds_dwordx4 v[146:147], off
	v_lshl_add_u64 v[146:147], s[34:35], 0, v[130:131]
	s_mov_b32 m0, s38
	s_nop 0
	global_load_lds_dwordx4 v[146:147], off
	v_lshl_add_u64 v[146:147], s[34:35], 0, v[134:135]
	s_add_i32 m0, s38, 0x2000
	s_nop 0
	global_load_lds_dwordx4 v[146:147], off
	v_lshl_add_u64 v[146:147], v[222:223], 0, s[14:15]
	s_mov_b32 m0, s51
	s_nop 0
	global_load_lds_dwordx4 v[146:147], off
	v_lshl_add_u64 v[146:147], v[224:225], 0, s[14:15]
	s_mov_b32 m0, s52
	s_nop 0
	global_load_lds_dwordx4 v[146:147], off
	s_waitcnt vmcnt(8)
	s_waitcnt lgkmcnt(0)
	s_setprio 1
	s_barrier
	v_mfma_f32_16x16x32_bf16 v[60:63], v[154:157], v[190:193], v[60:63]
	v_mfma_f32_16x16x32_bf16 v[60:63], v[158:161], v[194:197], v[60:63]
	v_mfma_f32_16x16x32_bf16 v[56:59], v[162:165], v[190:193], v[56:59]
	v_mfma_f32_16x16x32_bf16 v[56:59], v[166:169], v[194:197], v[56:59]
	v_mfma_f32_16x16x32_bf16 v[44:47], v[154:157], v[198:201], v[44:47]
	v_mfma_f32_16x16x32_bf16 v[44:47], v[158:161], v[202:205], v[44:47]
	v_mfma_f32_16x16x32_bf16 v[40:43], v[162:165], v[198:201], v[40:43]
	v_mfma_f32_16x16x32_bf16 v[40:43], v[166:169], v[202:205], v[40:43]
	v_mfma_f32_16x16x32_bf16 v[28:31], v[154:157], v[206:209], v[28:31]
	v_mfma_f32_16x16x32_bf16 v[28:31], v[158:161], v[210:213], v[28:31]
	v_mfma_f32_16x16x32_bf16 v[24:27], v[162:165], v[206:209], v[24:27]
	v_mfma_f32_16x16x32_bf16 v[24:27], v[166:169], v[210:213], v[24:27]
	v_mfma_f32_16x16x32_bf16 v[12:15], v[154:157], v[214:217], v[12:15]
	v_mfma_f32_16x16x32_bf16 v[12:15], v[158:161], v[218:221], v[12:15]
	v_mfma_f32_16x16x32_bf16 v[8:11], v[162:165], v[214:217], v[8:11]
	v_mfma_f32_16x16x32_bf16 v[8:11], v[166:169], v[218:221], v[8:11]
	s_setprio 0
	s_setprio 1
	v_mfma_f32_16x16x32_bf16 v[52:55], v[170:173], v[190:193], v[52:55]
	v_mfma_f32_16x16x32_bf16 v[52:55], v[174:177], v[194:197], v[52:55]
	v_mfma_f32_16x16x32_bf16 v[48:51], v[182:185], v[190:193], v[48:51]
	v_mfma_f32_16x16x32_bf16 v[48:51], v[186:189], v[194:197], v[48:51]
	v_mfma_f32_16x16x32_bf16 v[36:39], v[170:173], v[198:201], v[36:39]
	v_mfma_f32_16x16x32_bf16 v[36:39], v[174:177], v[202:205], v[36:39]
	v_mfma_f32_16x16x32_bf16 v[32:35], v[182:185], v[198:201], v[32:35]
	v_mfma_f32_16x16x32_bf16 v[32:35], v[186:189], v[202:205], v[32:35]
	v_mfma_f32_16x16x32_bf16 v[20:23], v[170:173], v[206:209], v[20:23]
	v_mfma_f32_16x16x32_bf16 v[20:23], v[174:177], v[210:213], v[20:23]
	v_mfma_f32_16x16x32_bf16 v[16:19], v[182:185], v[206:209], v[16:19]
	v_mfma_f32_16x16x32_bf16 v[16:19], v[186:189], v[210:213], v[16:19]
	v_mfma_f32_16x16x32_bf16 v[4:7], v[170:173], v[214:217], v[4:7]
	v_mfma_f32_16x16x32_bf16 v[4:7], v[174:177], v[218:221], v[4:7]
	v_mfma_f32_16x16x32_bf16 v[0:3], v[182:185], v[214:217], v[0:3]
	v_mfma_f32_16x16x32_bf16 v[0:3], v[186:189], v[218:221], v[0:3]
	s_setprio 0
	s_barrier
	s_add_u32 s30, s30, 0x100
	s_addc_u32 s31, s31, 0
	s_add_u32 s62, s62, 0x100
	s_addc_u32 s63, s63, 0
	s_cmp_ge_i32 s64, s50
	s_mov_b32 s34, s64
	s_cbranch_scc0 .LBB0_161

; #define PG8_STAGE(bufoff, gbase, voff) do { _Pragma("unroll") for (int _i = 0; _i < 2; ++_i) \
;         __builtin_amdgcn_global_load_lds((const unsigned*)((const char*)(gbase) + (voff)[_i]), (LAS unsigned*)(lds + (bufoff) + ldsw + _i * 8192), 16, 0, 0); } while (0)
; #define PG8_LDA(dst, b, h) do { _Pragma("unroll") for (int m = 0; m < 4; ++m) _Pragma("unroll") for (int k = 0; k < 2; ++k) dst[m][k] = *(const LAS bf16x8*)(lds + PG8_SA(b, h) + aoff + m * 2048 + k * 1024); } while (0)
; #define PG8_LDB(dst, b, h) do { _Pragma("unroll") for (int n = 0; n < 2; ++n) _Pragma("unroll") for (int k = 0; k < 2; ++k) dst[n][k] = *(const LAS bf16x8*)(lds + PG8_SB(b, h) + boff + n * 2048 + k * 1024); } while (0)
; #define PG8_MMA(ai, bj, At, Bt) do { __builtin_amdgcn_s_setprio(1); _Pragma("unroll") for (int m = 0; m < 4; ++m) _Pragma("unroll") for (int n = 0; n < 2; ++n) _Pragma("unroll") for (int k = 0; k < 2; ++k) \
;         acc[ai][bj][m][n] = __builtin_amdgcn_mfma_f32_16x16x32_bf16(Bt[n][k], At[m][k], acc[ai][bj][m][n], 0, 0, 0); __builtin_amdgcn_s_setprio(0); } while (0)
; #define PG8_WAIT_V(n) asm volatile("s_waitcnt vmcnt(" #n ")" ::: "memory")
; template <class Epi>
; DI void gemm_phase(LAS unsigned char* lds, const Gemm g, const StaticOrder& S, const Epi& E) {
;     ...
;         for (int t = 0; t < nt; t += 2) {
;             const bool last = (t == nt - 2);
;             const char* a1 = cA + (size_t)(t + 1) * kstep;
;             const char* a2 = last ? nA : cA + (size_t)(t + 2) * kstep; const char* b2 = last ? nB : cB + (size_t)(t + 2) * kstep;
;             const char* a3 = a2 + kstep; const char* b3 = b2 + kstep;
;             PG8_LDB(B0, 0, 0); PG8_LDB(B1, 0, 1); PG8_SCHED; PG8_LDA(At, 0, 0); PG8_STAGE(PG8_SA(1, 1), a1 + hstepA, voffA);
;             PG8_WAIT_V(8); PG8_WAIT_L(0); PG8_BAR; PG8_MMA(0, 0, At, B0); PG8_MMA(0, 1, At, B1); PG8_BAR; PG8_SCHED;
;             PG8_LDA(At, 0, 1); PG8_STAGE(PG8_SB(0, 0), b2, voffB); PG8_STAGE(PG8_SB(0, 1), b2 + hstepB, voffB); PG8_STAGE(PG8_SA(0, 0), a2, voffA);
;             PG8_WAIT_V(8); PG8_WAIT_L(0); PG8_BAR; PG8_MMA(1, 0, At, B0); PG8_MMA(1, 1, At, B1); PG8_BAR; PG8_SCHED;
;             PG8_LDB(B0, 1, 0); PG8_LDB(B1, 1, 1); PG8_SCHED; PG8_LDA(At, 1, 0); PG8_STAGE(PG8_SA(0, 1), a2 + hstepA, voffA);
;             PG8_WAIT_V(8); PG8_WAIT_L(0); PG8_BAR; PG8_MMA(0, 0, At, B0); PG8_MMA(0, 1, At, B1); PG8_BAR; PG8_SCHED;
.LBB0_201:
	ds_read_b128 v[148:151], v145
	ds_read_b128 v[152:155], v145 offset:1024
	ds_read_b128 v[156:159], v145 offset:2048
	ds_read_b128 v[160:163], v145 offset:3072
	ds_read_b128 v[164:167], v146
	ds_read_b128 v[168:171], v146 offset:1024
	ds_read_b128 v[172:175], v146 offset:2048
	ds_read_b128 v[176:179], v146 offset:3072
	s_add_i32 s65, s28, 2
	s_add_u32 s29, s26, 0xfff00080
	s_addc_u32 s30, s27, -1
	s_cmp_eq_u32 s50, s28
	s_cselect_b32 s28, s62, s63
	s_cselect_b32 s31, s19, s30
	s_cselect_b32 s30, s21, s29
	s_cselect_b32 s29, s61, s64
	v_lshl_add_u64 v[214:215], s[26:27], 0, v[138:139]
	s_add_i32 m0, s38, 0xc000
	ds_read_b128 v[182:185], v147
	ds_read_b128 v[186:189], v147 offset:1024
	ds_read_b128 v[190:193], v147 offset:2048
	ds_read_b128 v[194:197], v147 offset:3072
	ds_read_b128 v[198:201], v147 offset:4096
	ds_read_b128 v[202:205], v147 offset:5120
	ds_read_b128 v[206:209], v147 offset:6144
	ds_read_b128 v[210:213], v147 offset:7168
	global_load_lds_dwordx4 v[214:215], off
	v_lshl_add_u64 v[214:215], s[26:27], 0, v[140:141]
	s_add_i32 m0, s38, 0xe000
	s_nop 0
	global_load_lds_dwordx4 v[214:215], off
	s_waitcnt vmcnt(8)
	s_waitcnt lgkmcnt(0)
	s_setprio 1
	s_barrier
	v_mfma_f32_16x16x32_bf16 v[120:123], v[148:151], v[182:185], v[120:123]
	v_mfma_f32_16x16x32_bf16 v[120:123], v[152:155], v[186:189], v[120:123]
	v_mfma_f32_16x16x32_bf16 v[124:127], v[156:159], v[182:185], v[124:127]
	v_mfma_f32_16x16x32_bf16 v[124:127], v[160:163], v[186:189], v[124:127]
	v_mfma_f32_16x16x32_bf16 v[108:111], v[148:151], v[190:193], v[108:111]
	v_mfma_f32_16x16x32_bf16 v[108:111], v[152:155], v[194:197], v[108:111]
	v_mfma_f32_16x16x32_bf16 v[104:107], v[156:159], v[190:193], v[104:107]
	v_mfma_f32_16x16x32_bf16 v[104:107], v[160:163], v[194:197], v[104:107]
	v_mfma_f32_16x16x32_bf16 v[92:95], v[148:151], v[198:201], v[92:95]
	v_mfma_f32_16x16x32_bf16 v[92:95], v[152:155], v[202:205], v[92:95]
	v_mfma_f32_16x16x32_bf16 v[88:91], v[156:159], v[198:201], v[88:91]
	v_mfma_f32_16x16x32_bf16 v[88:91], v[160:163], v[202:205], v[88:91]
	v_mfma_f32_16x16x32_bf16 v[76:79], v[148:151], v[206:209], v[76:79]
	v_mfma_f32_16x16x32_bf16 v[76:79], v[152:155], v[210:213], v[76:79]
	v_mfma_f32_16x16x32_bf16 v[72:75], v[156:159], v[206:209], v[72:75]
	v_mfma_f32_16x16x32_bf16 v[72:75], v[160:163], v[210:213], v[72:75]
	s_setprio 0
	s_setprio 1
	v_mfma_f32_16x16x32_bf16 v[116:119], v[164:167], v[182:185], v[116:119]
	v_mfma_f32_16x16x32_bf16 v[116:119], v[168:171], v[186:189], v[116:119]
	v_mfma_f32_16x16x32_bf16 v[112:115], v[172:175], v[182:185], v[112:115]
	v_mfma_f32_16x16x32_bf16 v[112:115], v[176:179], v[186:189], v[112:115]
	v_mfma_f32_16x16x32_bf16 v[100:103], v[164:167], v[190:193], v[100:103]
	v_mfma_f32_16x16x32_bf16 v[100:103], v[168:171], v[194:197], v[100:103]
	v_mfma_f32_16x16x32_bf16 v[96:99], v[172:175], v[190:193], v[96:99]
	v_mfma_f32_16x16x32_bf16 v[96:99], v[176:179], v[194:197], v[96:99]
	v_mfma_f32_16x16x32_bf16 v[84:87], v[164:167], v[198:201], v[84:87]
	v_mfma_f32_16x16x32_bf16 v[84:87], v[168:171], v[202:205], v[84:87]
	v_mfma_f32_16x16x32_bf16 v[80:83], v[172:175], v[198:201], v[80:83]
	v_mfma_f32_16x16x32_bf16 v[80:83], v[176:179], v[202:205], v[80:83]
	v_mfma_f32_16x16x32_bf16 v[68:71], v[164:167], v[206:209], v[68:71]
	v_mfma_f32_16x16x32_bf16 v[68:71], v[168:171], v[210:213], v[68:71]
	v_mfma_f32_16x16x32_bf16 v[64:67], v[172:175], v[206:209], v[64:67]
	v_mfma_f32_16x16x32_bf16 v[64:67], v[176:179], v[210:213], v[64:67]
	s_setprio 0
	s_barrier
	s_add_i32 s66, s52, s35
	v_lshl_add_u64 v[214:215], s[28:29], 0, v[132:133]
	s_mov_b32 m0, s66
	ds_read_b128 v[182:185], v147 offset:16384
	ds_read_b128 v[186:189], v147 offset:17408
	ds_read_b128 v[190:193], v147 offset:18432
	ds_read_b128 v[194:197], v147 offset:19456
	ds_read_b128 v[198:201], v147 offset:20480
	ds_read_b128 v[202:205], v147 offset:21504
	ds_read_b128 v[206:209], v147 offset:22528
	ds_read_b128 v[210:213], v147 offset:23552
	global_load_lds_dwordx4 v[214:215], off
	s_add_i32 m0, s66, 0x2000
	s_add_u32 s66, s28, 0x100000
	v_lshl_add_u64 v[216:217], s[28:29], 0, v[128:129]
	s_addc_u32 s67, s29, 0
	s_add_i32 s68, s53, s35
	global_load_lds_dwordx4 v[216:217], off
	v_lshl_add_u64 v[218:219], s[66:67], 0, v[132:133]
	s_mov_b32 m0, s68
	v_lshl_add_u64 v[220:221], s[30:31], 0, v[130:131]
	global_load_lds_dwordx4 v[218:219], off
	v_lshl_add_u64 v[218:219], s[66:67], 0, v[128:129]
	s_add_i32 m0, s68, 0x2000
	s_nop 0
	global_load_lds_dwordx4 v[218:219], off
	v_lshl_add_u64 v[218:219], s[30:31], 0, v[134:135]
	s_mov_b32 m0, s38
	s_nop 0
	global_load_lds_dwordx4 v[218:219], off
	s_mov_b32 m0, s39
	s_nop 0
	global_load_lds_dwordx4 v[220:221], off
	s_waitcnt vmcnt(8)
	s_waitcnt lgkmcnt(0)
	s_setprio 1
	s_barrier
; #define PG8_STAGE(bufoff, gbase, voff) do { _Pragma("unroll") for (int _i = 0; _i < 2; ++_i) \
;         __builtin_amdgcn_global_load_lds((const unsigned*)((const char*)(gbase) + (voff)[_i]), (LAS unsigned*)(lds + (bufoff) + ldsw + _i * 8192), 16, 0, 0); } while (0)
; #define PG8_LDA(dst, b, h) do { _Pragma("unroll") for (int m = 0; m < 4; ++m) _Pragma("unroll") for (int k = 0; k < 2; ++k) dst[m][k] = *(const LAS bf16x8*)(lds + PG8_SA(b, h) + aoff + m * 2048 + k * 1024); } while (0)
; #define PG8_LDB(dst, b, h) do { _Pragma("unroll") for (int n = 0; n < 2; ++n) _Pragma("unroll") for (int k = 0; k < 2; ++k) dst[n][k] = *(const LAS bf16x8*)(lds + PG8_SB(b, h) + boff + n * 2048 + k * 1024); } while (0)
; #define PG8_MMA(ai, bj, At, Bt) do { __builtin_amdgcn_s_setprio(1); _Pragma("unroll") for (int m = 0; m < 4; ++m) _Pragma("unroll") for (int n = 0; n < 2; ++n) _Pragma("unroll") for (int k = 0; k < 2; ++k) \
;         acc[ai][bj][m][n] = __builtin_amdgcn_mfma_f32_16x16x32_bf16(Bt[n][k], At[m][k], acc[ai][bj][m][n], 0, 0, 0); __builtin_amdgcn_s_setprio(0); } while (0)
; #define PG8_WAIT_V(n) asm volatile("s_waitcnt vmcnt(" #n ")" ::: "memory")
; #define PG8_WAIT_L(n) asm volatile("s_waitcnt lgkmcnt(" #n ")" ::: "memory")
; template <class Epi>
; DI void gemm_phase(LAS unsigned char* lds, const Gemm g, const StaticOrder& S, const Epi& E) {
;     ...
;             PG8_LDB(B0, 0, 0); PG8_LDB(B1, 0, 1); PG8_SCHED; PG8_LDA(At, 0, 0); PG8_STAGE(PG8_SA(1, 1), a1 + hstepA, voffA);
;             PG8_WAIT_V(8); PG8_WAIT_L(0); PG8_BAR; PG8_MMA(0, 0, At, B0); PG8_MMA(0, 1, At, B1); PG8_BAR; PG8_SCHED;
;             PG8_LDA(At, 0, 1); PG8_STAGE(PG8_SB(0, 0), b2, voffB); PG8_STAGE(PG8_SB(0, 1), b2 + hstepB, voffB); PG8_STAGE(PG8_SA(0, 0), a2, voffA);
;             PG8_WAIT_V(8); PG8_WAIT_L(0); PG8_BAR; PG8_MMA(1, 0, At, B0); PG8_MMA(1, 1, At, B1); PG8_BAR; PG8_SCHED;
;             PG8_LDB(B0, 1, 0); PG8_LDB(B1, 1, 1); PG8_SCHED; PG8_LDA(At, 1, 0); PG8_STAGE(PG8_SA(0, 1), a2 + hstepA, voffA);
;             PG8_WAIT_V(8); PG8_WAIT_L(0); PG8_BAR; PG8_MMA(0, 0, At, B0); PG8_MMA(0, 1, At, B1); PG8_BAR; PG8_SCHED;
;             PG8_LDA(At, 1, 1); PG8_STAGE(PG8_SB(1, 0), b3, voffB); PG8_STAGE(PG8_SB(1, 1), b3 + hstepB, voffB); PG8_STAGE(PG8_SA(1, 0), a3, voffA);
;             PG8_WAIT_V(8); PG8_WAIT_L(0); PG8_BAR; PG8_MMA(1, 0, At, B0); PG8_MMA(1, 1, At, B1); PG8_BAR; PG8_SCHED;
	v_mfma_f32_16x16x32_bf16 v[60:63], v[148:151], v[182:185], v[60:63]
	v_mfma_f32_16x16x32_bf16 v[60:63], v[152:155], v[186:189], v[60:63]
	v_mfma_f32_16x16x32_bf16 v[56:59], v[156:159], v[182:185], v[56:59]
	v_mfma_f32_16x16x32_bf16 v[56:59], v[160:163], v[186:189], v[56:59]
	v_mfma_f32_16x16x32_bf16 v[44:47], v[148:151], v[190:193], v[44:47]
	v_mfma_f32_16x16x32_bf16 v[44:47], v[152:155], v[194:197], v[44:47]
	v_mfma_f32_16x16x32_bf16 v[40:43], v[156:159], v[190:193], v[40:43]
	v_mfma_f32_16x16x32_bf16 v[40:43], v[160:163], v[194:197], v[40:43]
	v_mfma_f32_16x16x32_bf16 v[28:31], v[148:151], v[198:201], v[28:31]
	v_mfma_f32_16x16x32_bf16 v[28:31], v[152:155], v[202:205], v[28:31]
	v_mfma_f32_16x16x32_bf16 v[24:27], v[156:159], v[198:201], v[24:27]
	v_mfma_f32_16x16x32_bf16 v[24:27], v[160:163], v[202:205], v[24:27]
	v_mfma_f32_16x16x32_bf16 v[12:15], v[148:151], v[206:209], v[12:15]
	v_mfma_f32_16x16x32_bf16 v[12:15], v[152:155], v[210:213], v[12:15]
	v_mfma_f32_16x16x32_bf16 v[8:11], v[156:159], v[206:209], v[8:11]
	v_mfma_f32_16x16x32_bf16 v[8:11], v[160:163], v[210:213], v[8:11]
	s_setprio 0
	s_setprio 1
	v_mfma_f32_16x16x32_bf16 v[52:55], v[164:167], v[182:185], v[52:55]
	v_mfma_f32_16x16x32_bf16 v[52:55], v[168:171], v[186:189], v[52:55]
	v_mfma_f32_16x16x32_bf16 v[48:51], v[172:175], v[182:185], v[48:51]
	v_mfma_f32_16x16x32_bf16 v[48:51], v[176:179], v[186:189], v[48:51]
	v_mfma_f32_16x16x32_bf16 v[36:39], v[164:167], v[190:193], v[36:39]
	v_mfma_f32_16x16x32_bf16 v[36:39], v[168:171], v[194:197], v[36:39]
	v_mfma_f32_16x16x32_bf16 v[32:35], v[172:175], v[190:193], v[32:35]
	v_mfma_f32_16x16x32_bf16 v[32:35], v[176:179], v[194:197], v[32:35]
	v_mfma_f32_16x16x32_bf16 v[20:23], v[164:167], v[198:201], v[20:23]
	v_mfma_f32_16x16x32_bf16 v[20:23], v[168:171], v[202:205], v[20:23]
	v_mfma_f32_16x16x32_bf16 v[16:19], v[172:175], v[198:201], v[16:19]
	v_mfma_f32_16x16x32_bf16 v[16:19], v[176:179], v[202:205], v[16:19]
	v_mfma_f32_16x16x32_bf16 v[4:7], v[164:167], v[206:209], v[4:7]
	v_mfma_f32_16x16x32_bf16 v[4:7], v[168:171], v[210:213], v[4:7]
	v_mfma_f32_16x16x32_bf16 v[0:3], v[172:175], v[206:209], v[0:3]
	v_mfma_f32_16x16x32_bf16 v[0:3], v[176:179], v[210:213], v[0:3]
	s_setprio 0
	s_barrier
	s_add_i32 s66, 0, 0x18000
	v_add_u32_e32 v136, s66, v143
	s_add_i32 s67, 0, 0x1c000
	ds_read_b128 v[148:151], v136
	ds_read_b128 v[152:155], v136 offset:1024
	ds_read_b128 v[156:159], v136 offset:2048
	ds_read_b128 v[160:163], v136 offset:3072
	v_add_u32_e32 v136, s67, v143
	ds_read_b128 v[164:167], v136
	ds_read_b128 v[168:171], v136 offset:1024
	ds_read_b128 v[172:175], v136 offset:2048
	ds_read_b128 v[176:179], v136 offset:3072
	s_add_u32 s30, s30, 0x100000
	s_addc_u32 s31, s31, 0
	s_mov_b32 m0, s40
	v_lshl_add_u64 v[222:223], s[30:31], 0, v[134:135]
	ds_read_b128 v[182:185], v147 offset:32768
	ds_read_b128 v[186:189], v147 offset:33792
	ds_read_b128 v[190:193], v147 offset:34816
	ds_read_b128 v[194:197], v147 offset:35840
	ds_read_b128 v[198:201], v147 offset:36864
	ds_read_b128 v[202:205], v147 offset:37888
	ds_read_b128 v[206:209], v147 offset:38912
	ds_read_b128 v[210:213], v147 offset:39936
	global_load_lds_dwordx4 v[222:223], off
	v_lshl_add_u64 v[222:223], s[30:31], 0, v[130:131]
	s_mov_b32 m0, s41
	s_nop 0
	global_load_lds_dwordx4 v[222:223], off
	s_waitcnt vmcnt(8)
	s_waitcnt lgkmcnt(0)
	s_setprio 1
	s_barrier
	v_mfma_f32_16x16x32_bf16 v[120:123], v[148:151], v[182:185], v[120:123]
	v_mfma_f32_16x16x32_bf16 v[120:123], v[152:155], v[186:189], v[120:123]
	v_mfma_f32_16x16x32_bf16 v[124:127], v[156:159], v[182:185], v[124:127]
	v_mfma_f32_16x16x32_bf16 v[124:127], v[160:163], v[186:189], v[124:127]
	v_mfma_f32_16x16x32_bf16 v[108:111], v[148:151], v[190:193], v[108:111]
	v_mfma_f32_16x16x32_bf16 v[108:111], v[152:155], v[194:197], v[108:111]
	v_mfma_f32_16x16x32_bf16 v[104:107], v[156:159], v[190:193], v[104:107]
	v_mfma_f32_16x16x32_bf16 v[104:107], v[160:163], v[194:197], v[104:107]
	v_mfma_f32_16x16x32_bf16 v[92:95], v[148:151], v[198:201], v[92:95]
	v_mfma_f32_16x16x32_bf16 v[92:95], v[152:155], v[202:205], v[92:95]
	v_mfma_f32_16x16x32_bf16 v[88:91], v[156:159], v[198:201], v[88:91]
	v_mfma_f32_16x16x32_bf16 v[88:91], v[160:163], v[202:205], v[88:91]
	v_mfma_f32_16x16x32_bf16 v[76:79], v[148:151], v[206:209], v[76:79]
	v_mfma_f32_16x16x32_bf16 v[76:79], v[152:155], v[210:213], v[76:79]
	v_mfma_f32_16x16x32_bf16 v[72:75], v[156:159], v[206:209], v[72:75]
	v_mfma_f32_16x16x32_bf16 v[72:75], v[160:163], v[210:213], v[72:75]
	s_setprio 0
	s_setprio 1
	v_mfma_f32_16x16x32_bf16 v[116:119], v[164:167], v[182:185], v[116:119]
	v_mfma_f32_16x16x32_bf16 v[116:119], v[168:171], v[186:189], v[116:119]
	v_mfma_f32_16x16x32_bf16 v[112:115], v[172:175], v[182:185], v[112:115]
	v_mfma_f32_16x16x32_bf16 v[112:115], v[176:179], v[186:189], v[112:115]
	v_mfma_f32_16x16x32_bf16 v[100:103], v[164:167], v[190:193], v[100:103]
	v_mfma_f32_16x16x32_bf16 v[100:103], v[168:171], v[194:197], v[100:103]
	v_mfma_f32_16x16x32_bf16 v[96:99], v[172:175], v[190:193], v[96:99]
	v_mfma_f32_16x16x32_bf16 v[96:99], v[176:179], v[194:197], v[96:99]
	v_mfma_f32_16x16x32_bf16 v[84:87], v[164:167], v[198:201], v[84:87]
	v_mfma_f32_16x16x32_bf16 v[84:87], v[168:171], v[202:205], v[84:87]
	v_mfma_f32_16x16x32_bf16 v[80:83], v[172:175], v[198:201], v[80:83]
	v_mfma_f32_16x16x32_bf16 v[80:83], v[176:179], v[202:205], v[80:83]
	v_mfma_f32_16x16x32_bf16 v[68:71], v[164:167], v[206:209], v[68:71]
	v_mfma_f32_16x16x32_bf16 v[68:71], v[168:171], v[210:213], v[68:71]
	v_mfma_f32_16x16x32_bf16 v[64:67], v[172:175], v[206:209], v[64:67]
	v_mfma_f32_16x16x32_bf16 v[64:67], v[176:179], v[210:213], v[64:67]
	s_setprio 0
	s_barrier
; #define PG8_STAGE(bufoff, gbase, voff) do { _Pragma("unroll") for (int _i = 0; _i < 2; ++_i) \
;         __builtin_amdgcn_global_load_lds((const unsigned*)((const char*)(gbase) + (voff)[_i]), (LAS unsigned*)(lds + (bufoff) + ldsw + _i * 8192), 16, 0, 0); } while (0)
; #define PG8_LDA(dst, b, h) do { _Pragma("unroll") for (int m = 0; m < 4; ++m) _Pragma("unroll") for (int k = 0; k < 2; ++k) dst[m][k] = *(const LAS bf16x8*)(lds + PG8_SA(b, h) + aoff + m * 2048 + k * 1024); } while (0)
; #define PG8_MMA(ai, bj, At, Bt) do { __builtin_amdgcn_s_setprio(1); _Pragma("unroll") for (int m = 0; m < 4; ++m) _Pragma("unroll") for (int n = 0; n < 2; ++n) _Pragma("unroll") for (int k = 0; k < 2; ++k) \
;         acc[ai][bj][m][n] = __builtin_amdgcn_mfma_f32_16x16x32_bf16(Bt[n][k], At[m][k], acc[ai][bj][m][n], 0, 0, 0); __builtin_amdgcn_s_setprio(0); } while (0)
; #define PG8_WAIT_V(n) asm volatile("s_waitcnt vmcnt(" #n ")" ::: "memory")
; #define PG8_WAIT_L(n) asm volatile("s_waitcnt lgkmcnt(" #n ")" ::: "memory")
; #define PG8_BAR __builtin_amdgcn_s_barrier()
; #define PG8_SCHED __builtin_amdgcn_sched_barrier(0)
; template <class Epi>
; DI void gemm_phase(LAS unsigned char* lds, const Gemm g, const StaticOrder& S, const Epi& E) {
;     ...
;         for (int t = 0; t < nt; t += 2) {
;     ...
;             PG8_LDA(At, 1, 1); PG8_STAGE(PG8_SB(1, 0), b3, voffB); PG8_STAGE(PG8_SB(1, 1), b3 + hstepB, voffB); PG8_STAGE(PG8_SA(1, 0), a3, voffA);
;             PG8_WAIT_V(8); PG8_WAIT_L(0); PG8_BAR; PG8_MMA(1, 0, At, B0); PG8_MMA(1, 1, At, B1); PG8_BAR; PG8_SCHED;
	s_add_i32 s30, s66, s35
	v_lshl_add_u64 v[214:215], v[214:215], 0, s[10:11]
	s_mov_b32 m0, s30
	ds_read_b128 v[182:185], v147 offset:49152
	ds_read_b128 v[186:189], v147 offset:50176
	ds_read_b128 v[190:193], v147 offset:51200
	ds_read_b128 v[194:197], v147 offset:52224
	ds_read_b128 v[198:201], v147 offset:53248
	ds_read_b128 v[202:205], v147 offset:54272
	ds_read_b128 v[206:209], v147 offset:55296
	ds_read_b128 v[210:213], v147 offset:56320
	global_load_lds_dwordx4 v[214:215], off
	s_add_i32 m0, s30, 0x2000
	s_add_u32 s28, s28, 0x100080
	v_lshl_add_u64 v[214:215], v[216:217], 0, s[10:11]
	s_addc_u32 s29, s29, 0
	s_add_i32 s30, s67, s35
	global_load_lds_dwordx4 v[214:215], off
	v_lshl_add_u64 v[214:215], s[28:29], 0, v[132:133]
	s_mov_b32 m0, s30
	s_nop 0
	global_load_lds_dwordx4 v[214:215], off
	v_lshl_add_u64 v[214:215], s[28:29], 0, v[128:129]
	s_add_i32 m0, s30, 0x2000
	s_nop 0
	global_load_lds_dwordx4 v[214:215], off
	v_lshl_add_u64 v[214:215], v[218:219], 0, s[10:11]
	s_mov_b32 m0, s46
	s_nop 0
	global_load_lds_dwordx4 v[214:215], off
	v_lshl_add_u64 v[214:215], v[220:221], 0, s[10:11]
	s_mov_b32 m0, s47
	s_nop 0
	global_load_lds_dwordx4 v[214:215], off
	s_waitcnt vmcnt(8)
	s_waitcnt lgkmcnt(0)
	s_setprio 1
	s_barrier
	v_mfma_f32_16x16x32_bf16 v[60:63], v[148:151], v[182:185], v[60:63]
	v_mfma_f32_16x16x32_bf16 v[60:63], v[152:155], v[186:189], v[60:63]
	v_mfma_f32_16x16x32_bf16 v[56:59], v[156:159], v[182:185], v[56:59]
	v_mfma_f32_16x16x32_bf16 v[56:59], v[160:163], v[186:189], v[56:59]
	v_mfma_f32_16x16x32_bf16 v[44:47], v[148:151], v[190:193], v[44:47]
	v_mfma_f32_16x16x32_bf16 v[44:47], v[152:155], v[194:197], v[44:47]
	v_mfma_f32_16x16x32_bf16 v[40:43], v[156:159], v[190:193], v[40:43]
	v_mfma_f32_16x16x32_bf16 v[40:43], v[160:163], v[194:197], v[40:43]
	v_mfma_f32_16x16x32_bf16 v[28:31], v[148:151], v[198:201], v[28:31]
	v_mfma_f32_16x16x32_bf16 v[28:31], v[152:155], v[202:205], v[28:31]
	v_mfma_f32_16x16x32_bf16 v[24:27], v[156:159], v[198:201], v[24:27]
	v_mfma_f32_16x16x32_bf16 v[24:27], v[160:163], v[202:205], v[24:27]
	v_mfma_f32_16x16x32_bf16 v[12:15], v[148:151], v[206:209], v[12:15]
	v_mfma_f32_16x16x32_bf16 v[12:15], v[152:155], v[210:213], v[12:15]
	v_mfma_f32_16x16x32_bf16 v[8:11], v[156:159], v[206:209], v[8:11]
	v_mfma_f32_16x16x32_bf16 v[8:11], v[160:163], v[210:213], v[8:11]
	s_setprio 0
	s_setprio 1
	v_mfma_f32_16x16x32_bf16 v[52:55], v[164:167], v[182:185], v[52:55]
	v_mfma_f32_16x16x32_bf16 v[52:55], v[168:171], v[186:189], v[52:55]
	v_mfma_f32_16x16x32_bf16 v[48:51], v[172:175], v[182:185], v[48:51]
	v_mfma_f32_16x16x32_bf16 v[48:51], v[176:179], v[186:189], v[48:51]
	v_mfma_f32_16x16x32_bf16 v[36:39], v[164:167], v[190:193], v[36:39]
	v_mfma_f32_16x16x32_bf16 v[36:39], v[168:171], v[194:197], v[36:39]
	v_mfma_f32_16x16x32_bf16 v[32:35], v[172:175], v[190:193], v[32:35]
	v_mfma_f32_16x16x32_bf16 v[32:35], v[176:179], v[194:197], v[32:35]
	v_mfma_f32_16x16x32_bf16 v[20:23], v[164:167], v[198:201], v[20:23]
	v_mfma_f32_16x16x32_bf16 v[20:23], v[168:171], v[202:205], v[20:23]
	v_mfma_f32_16x16x32_bf16 v[16:19], v[172:175], v[198:201], v[16:19]
	v_mfma_f32_16x16x32_bf16 v[16:19], v[176:179], v[202:205], v[16:19]
	v_mfma_f32_16x16x32_bf16 v[4:7], v[164:167], v[206:209], v[4:7]
	v_mfma_f32_16x16x32_bf16 v[4:7], v[168:171], v[210:213], v[4:7]
	v_mfma_f32_16x16x32_bf16 v[0:3], v[172:175], v[206:209], v[0:3]
	v_mfma_f32_16x16x32_bf16 v[0:3], v[176:179], v[210:213], v[0:3]
	s_setprio 0
	s_barrier
	s_add_u32 s26, s26, 0x100
	s_addc_u32 s27, s27, 0
	s_add_u32 s63, s63, 0x100
	s_addc_u32 s64, s64, 0
	s_cmp_ge_i32 s65, s43
	s_mov_b32 s28, s65
	s_cbranch_scc0 .LBB0_201

; #define PG8_STAGE(bufoff, gbase, voff) do { _Pragma("unroll") for (int _i = 0; _i < 2; ++_i) \
;         __builtin_amdgcn_global_load_lds((const unsigned*)((const char*)(gbase) + (voff)[_i]), (LAS unsigned*)(lds + (bufoff) + ldsw + _i * 8192), 16, 0, 0); } while (0)
; #define PG8_LDA(dst, b, h) do { _Pragma("unroll") for (int m = 0; m < 4; ++m) _Pragma("unroll") for (int k = 0; k < 2; ++k) dst[m][k] = *(const LAS bf16x8*)(lds + PG8_SA(b, h) + aoff + m * 2048 + k * 1024); } while (0)
; #define PG8_WAIT_V(n) asm volatile("s_waitcnt vmcnt(" #n ")" ::: "memory")
; #define PG8_BAR __builtin_amdgcn_s_barrier()
; template <class Epi>
; DI void gemm_phase(LAS unsigned char* lds, const Gemm g, const StaticOrder& S, const Epi& E) {
;     ...
;         for (int t = 0; t < nt; t += 2) {
;             const bool last = (t == nt - 2);
;             const char* a1 = cA + (size_t)(t + 1) * kstep;
;             const char* a2 = last ? nA : cA + (size_t)(t + 2) * kstep; const char* b2 = last ? nB : cB + (size_t)(t + 2) * kstep;
;             const char* a3 = a2 + kstep; const char* b3 = b2 + kstep;
;             PG8_LDB(B0, 0, 0); PG8_LDB(B1, 0, 1); PG8_SCHED; PG8_LDA(At, 0, 0); PG8_STAGE(PG8_SA(1, 1), a1 + hstepA, voffA);
;             PG8_WAIT_V(8); PG8_WAIT_L(0); PG8_BAR; PG8_MMA(0, 0, At, B0); PG8_MMA(0, 1, At, B1); PG8_BAR; PG8_SCHED;
;             PG8_LDA(At, 0, 1); PG8_STAGE(PG8_SB(0, 0), b2, voffB); PG8_STAGE(PG8_SB(0, 1), b2 + hstepB, voffB); PG8_STAGE(PG8_SA(0, 0), a2, voffA);
;             PG8_WAIT_V(8); PG8_WAIT_L(0); PG8_BAR; PG8_MMA(1, 0, At, B0); PG8_MMA(1, 1, At, B1); PG8_BAR; PG8_SCHED;
;             PG8_LDB(B0, 1, 0); PG8_LDB(B1, 1, 1); PG8_SCHED; PG8_LDA(At, 1, 0); PG8_STAGE(PG8_SA(0, 1), a2 + hstepA, voffA);
;             PG8_WAIT_V(8); PG8_WAIT_L(0); PG8_BAR; PG8_MMA(0, 0, At, B0); PG8_MMA(0, 1, At, B1); PG8_BAR; PG8_SCHED;
;     DI void operator()(AccRef acc, const Unit& u, int wr, int wc, int fr, int fq) const {
;         if (wc >= 2) return;
;         const int row0 = u.pm * 256 + wr * 64 + fr, lc0 = wc * 32 + 8 * fq;
; #pragma unroll
;         for (int ai = 0; ai < 2; ++ai)
; #pragma unroll
;             for (int m = 0; m < 4; ++m) {
;                 float* rp = krp + ((size_t)u.half * T + row0 + ai * 128 + m * 16) * 64 + lc0;
;                 *(f32x4*)rp = acc[ai][0][m][0]; *(f32x4*)(rp + 4) = acc[ai][0][m][1];
;             }
;     }
.LBB0_220:
	ds_read_b128 v[88:91], v86
	ds_read_b128 v[92:95], v86 offset:1024
	ds_read_b128 v[96:99], v86 offset:2048
	ds_read_b128 v[100:103], v86 offset:3072
	s_add_i32 s43, s50, 2
	s_add_u32 s51, s46, 0xfff00080
	s_addc_u32 s52, s47, -1
	s_cmp_eq_u32 s72, s50
	s_cselect_b32 s50, s8, s13
	s_cselect_b32 s53, s39, s52
	s_cselect_b32 s52, s38, s51
	s_cselect_b32 s51, s9, s41
	v_lshl_add_u64 v[136:137], s[46:47], 0, v[76:77]
	s_add_i32 m0, s15, 0xc000
	ds_read_b128 v[104:107], v87
	ds_read_b128 v[108:111], v87 offset:1024
	ds_read_b128 v[112:115], v87 offset:2048
	ds_read_b128 v[116:119], v87 offset:3072
	ds_read_b128 v[120:123], v87 offset:4096
	ds_read_b128 v[124:127], v87 offset:5120
	ds_read_b128 v[128:131], v87 offset:6144
	ds_read_b128 v[132:135], v87 offset:7168
	global_load_lds_dwordx4 v[136:137], off
	v_lshl_add_u64 v[136:137], s[46:47], 0, v[78:79]
	s_add_i32 m0, s15, 0xe000
	s_nop 0
	global_load_lds_dwordx4 v[136:137], off
	s_waitcnt vmcnt(8)
	s_waitcnt lgkmcnt(0)
	s_setprio 1
	s_barrier
	v_mfma_f32_16x16x32_bf16 v[60:63], v[88:91], v[104:107], v[60:63]
	v_mfma_f32_16x16x32_bf16 v[56:59], v[96:99], v[104:107], v[56:59]
	v_mfma_f32_16x16x32_bf16 v[52:55], v[88:91], v[112:115], v[52:55]
	v_mfma_f32_16x16x32_bf16 v[48:51], v[96:99], v[112:115], v[48:51]
	v_mfma_f32_16x16x32_bf16 v[44:47], v[88:91], v[120:123], v[44:47]
	v_mfma_f32_16x16x32_bf16 v[40:43], v[96:99], v[120:123], v[40:43]
	v_mfma_f32_16x16x32_bf16 v[36:39], v[88:91], v[128:131], v[36:39]
	v_mfma_f32_16x16x32_bf16 v[32:35], v[96:99], v[128:131], v[32:35]
	v_mfma_f32_16x16x32_bf16 v[60:63], v[92:95], v[108:111], v[60:63]
	v_mfma_f32_16x16x32_bf16 v[56:59], v[100:103], v[108:111], v[56:59]
	v_mfma_f32_16x16x32_bf16 v[52:55], v[92:95], v[116:119], v[52:55]
	v_mfma_f32_16x16x32_bf16 v[48:51], v[100:103], v[116:119], v[48:51]
	v_mfma_f32_16x16x32_bf16 v[44:47], v[92:95], v[124:127], v[44:47]
	v_mfma_f32_16x16x32_bf16 v[40:43], v[100:103], v[124:127], v[40:43]
	v_mfma_f32_16x16x32_bf16 v[36:39], v[92:95], v[132:135], v[36:39]
	v_mfma_f32_16x16x32_bf16 v[32:35], v[100:103], v[132:135], v[32:35]
	s_setprio 0
	s_setprio 1
	s_setprio 0
	s_barrier
	s_add_i32 s76, s73, s57
	v_lshl_add_u64 v[136:137], s[50:51], 0, v[68:69]
	s_mov_b32 m0, s76
	ds_read_b128 v[104:107], v87 offset:16384
	ds_read_b128 v[108:111], v87 offset:17408
	ds_read_b128 v[112:115], v87 offset:18432
	ds_read_b128 v[116:119], v87 offset:19456
	ds_read_b128 v[120:123], v87 offset:20480
	ds_read_b128 v[124:127], v87 offset:21504
	ds_read_b128 v[128:131], v87 offset:22528
	ds_read_b128 v[132:135], v87 offset:23552
	global_load_lds_dwordx4 v[136:137], off
	s_add_i32 m0, s76, 0x2000
	s_add_u32 s76, s50, 0x100000
	v_lshl_add_u64 v[138:139], s[50:51], 0, v[64:65]
	s_addc_u32 s77, s51, 0
	global_load_lds_dwordx4 v[138:139], off
	v_lshl_add_u64 v[140:141], s[76:77], 0, v[68:69]
	s_mov_b32 m0, s60
	v_lshl_add_u64 v[142:143], s[52:53], 0, v[66:67]
	global_load_lds_dwordx4 v[140:141], off
	v_lshl_add_u64 v[140:141], s[76:77], 0, v[64:65]
	s_mov_b32 m0, s61
	s_nop 0
	global_load_lds_dwordx4 v[140:141], off
	v_lshl_add_u64 v[140:141], s[52:53], 0, v[70:71]
	s_mov_b32 m0, s15
	s_nop 0
	global_load_lds_dwordx4 v[140:141], off
	s_mov_b32 m0, s62
	s_nop 0
	global_load_lds_dwordx4 v[142:143], off
	s_waitcnt vmcnt(8)
	s_waitcnt lgkmcnt(0)
	s_setprio 1
	s_barrier
	v_mfma_f32_16x16x32_bf16 v[28:31], v[88:91], v[104:107], v[28:31]
	v_mfma_f32_16x16x32_bf16 v[24:27], v[96:99], v[104:107], v[24:27]
	v_mfma_f32_16x16x32_bf16 v[20:23], v[88:91], v[112:115], v[20:23]
	v_mfma_f32_16x16x32_bf16 v[16:19], v[96:99], v[112:115], v[16:19]
	v_mfma_f32_16x16x32_bf16 v[12:15], v[88:91], v[120:123], v[12:15]
	v_mfma_f32_16x16x32_bf16 v[8:11], v[96:99], v[120:123], v[8:11]
	v_mfma_f32_16x16x32_bf16 v[4:7], v[88:91], v[128:131], v[4:7]
	v_mfma_f32_16x16x32_bf16 v[0:3], v[96:99], v[128:131], v[0:3]
	v_mfma_f32_16x16x32_bf16 v[28:31], v[92:95], v[108:111], v[28:31]
	v_mfma_f32_16x16x32_bf16 v[24:27], v[100:103], v[108:111], v[24:27]
	v_mfma_f32_16x16x32_bf16 v[20:23], v[92:95], v[116:119], v[20:23]
	v_mfma_f32_16x16x32_bf16 v[16:19], v[100:103], v[116:119], v[16:19]
	v_mfma_f32_16x16x32_bf16 v[12:15], v[92:95], v[124:127], v[12:15]
	v_mfma_f32_16x16x32_bf16 v[8:11], v[100:103], v[124:127], v[8:11]
	v_mfma_f32_16x16x32_bf16 v[4:7], v[92:95], v[132:135], v[4:7]
	v_mfma_f32_16x16x32_bf16 v[0:3], v[100:103], v[132:135], v[0:3]
	s_setprio 0
	s_setprio 1
	s_setprio 0
	s_barrier
; #define PG8_STAGE(bufoff, gbase, voff) do { _Pragma("unroll") for (int _i = 0; _i < 2; ++_i) \
;         __builtin_amdgcn_global_load_lds((const unsigned*)((const char*)(gbase) + (voff)[_i]), (LAS unsigned*)(lds + (bufoff) + ldsw + _i * 8192), 16, 0, 0); } while (0)
; #define PG8_LDA(dst, b, h) do { _Pragma("unroll") for (int m = 0; m < 4; ++m) _Pragma("unroll") for (int k = 0; k < 2; ++k) dst[m][k] = *(const LAS bf16x8*)(lds + PG8_SA(b, h) + aoff + m * 2048 + k * 1024); } while (0)
; #define PG8_LDB(dst, b, h) do { _Pragma("unroll") for (int n = 0; n < 2; ++n) _Pragma("unroll") for (int k = 0; k < 2; ++k) dst[n][k] = *(const LAS bf16x8*)(lds + PG8_SB(b, h) + boff + n * 2048 + k * 1024); } while (0)
; #define PG8_MMA(ai, bj, At, Bt) do { __builtin_amdgcn_s_setprio(1); _Pragma("unroll") for (int m = 0; m < 4; ++m) _Pragma("unroll") for (int n = 0; n < 2; ++n) _Pragma("unroll") for (int k = 0; k < 2; ++k) \
;         acc[ai][bj][m][n] = __builtin_amdgcn_mfma_f32_16x16x32_bf16(Bt[n][k], At[m][k], acc[ai][bj][m][n], 0, 0, 0); __builtin_amdgcn_s_setprio(0); } while (0)
; #define PG8_WAIT_V(n) asm volatile("s_waitcnt vmcnt(" #n ")" ::: "memory")
; #define PG8_WAIT_L(n) asm volatile("s_waitcnt lgkmcnt(" #n ")" ::: "memory")
; template <class Epi>
; DI void gemm_phase(LAS unsigned char* lds, const Gemm g, const StaticOrder& S, const Epi& E) {
;     ...
;             PG8_LDB(B0, 0, 0); PG8_LDB(B1, 0, 1); PG8_SCHED; PG8_LDA(At, 0, 0); PG8_STAGE(PG8_SA(1, 1), a1 + hstepA, voffA);
;             PG8_WAIT_V(8); PG8_WAIT_L(0); PG8_BAR; PG8_MMA(0, 0, At, B0); PG8_MMA(0, 1, At, B1); PG8_BAR; PG8_SCHED;
;             PG8_LDA(At, 0, 1); PG8_STAGE(PG8_SB(0, 0), b2, voffB); PG8_STAGE(PG8_SB(0, 1), b2 + hstepB, voffB); PG8_STAGE(PG8_SA(0, 0), a2, voffA);
;             PG8_WAIT_V(8); PG8_WAIT_L(0); PG8_BAR; PG8_MMA(1, 0, At, B0); PG8_MMA(1, 1, At, B1); PG8_BAR; PG8_SCHED;
;             PG8_LDB(B0, 1, 0); PG8_LDB(B1, 1, 1); PG8_SCHED; PG8_LDA(At, 1, 0); PG8_STAGE(PG8_SA(0, 1), a2 + hstepA, voffA);
;             PG8_WAIT_V(8); PG8_WAIT_L(0); PG8_BAR; PG8_MMA(0, 0, At, B0); PG8_MMA(0, 1, At, B1); PG8_BAR; PG8_SCHED;
;             PG8_LDA(At, 1, 1); PG8_STAGE(PG8_SB(1, 0), b3, voffB); PG8_STAGE(PG8_SB(1, 1), b3 + hstepB, voffB); PG8_STAGE(PG8_SA(1, 0), a3, voffA);
;             PG8_WAIT_V(8); PG8_WAIT_L(0); PG8_BAR; PG8_MMA(1, 0, At, B0); PG8_MMA(1, 1, At, B1); PG8_BAR; PG8_SCHED;
	s_add_i32 s76, 0, 0x18000
	v_add_u32_e32 v100, s76, v85
	ds_read_b128 v[88:91], v100
	ds_read_b128 v[92:95], v100 offset:1024
	ds_read_b128 v[96:99], v100 offset:2048
	ds_read_b128 v[100:103], v100 offset:3072
	s_add_u32 s52, s52, 0x100000
	s_addc_u32 s53, s53, 0
	s_mov_b32 m0, s63
	v_lshl_add_u64 v[144:145], s[52:53], 0, v[70:71]
	ds_read_b128 v[104:107], v87 offset:32768
	ds_read_b128 v[108:111], v87 offset:33792
	ds_read_b128 v[112:115], v87 offset:34816
	ds_read_b128 v[116:119], v87 offset:35840
	ds_read_b128 v[120:123], v87 offset:36864
	ds_read_b128 v[124:127], v87 offset:37888
	ds_read_b128 v[128:131], v87 offset:38912
	ds_read_b128 v[132:135], v87 offset:39936
	global_load_lds_dwordx4 v[144:145], off
	v_lshl_add_u64 v[144:145], s[52:53], 0, v[66:67]
	s_mov_b32 m0, s65
	s_nop 0
	global_load_lds_dwordx4 v[144:145], off
	s_waitcnt vmcnt(8)
	s_waitcnt lgkmcnt(0)
	s_setprio 1
	s_barrier
	v_mfma_f32_16x16x32_bf16 v[60:63], v[88:91], v[104:107], v[60:63]
	v_mfma_f32_16x16x32_bf16 v[56:59], v[96:99], v[104:107], v[56:59]
	v_mfma_f32_16x16x32_bf16 v[52:55], v[88:91], v[112:115], v[52:55]
	v_mfma_f32_16x16x32_bf16 v[48:51], v[96:99], v[112:115], v[48:51]
	v_mfma_f32_16x16x32_bf16 v[44:47], v[88:91], v[120:123], v[44:47]
	v_mfma_f32_16x16x32_bf16 v[40:43], v[96:99], v[120:123], v[40:43]
	v_mfma_f32_16x16x32_bf16 v[36:39], v[88:91], v[128:131], v[36:39]
	v_mfma_f32_16x16x32_bf16 v[32:35], v[96:99], v[128:131], v[32:35]
	v_mfma_f32_16x16x32_bf16 v[60:63], v[92:95], v[108:111], v[60:63]
	v_mfma_f32_16x16x32_bf16 v[56:59], v[100:103], v[108:111], v[56:59]
	v_mfma_f32_16x16x32_bf16 v[52:55], v[92:95], v[116:119], v[52:55]
	v_mfma_f32_16x16x32_bf16 v[48:51], v[100:103], v[116:119], v[48:51]
	v_mfma_f32_16x16x32_bf16 v[44:47], v[92:95], v[124:127], v[44:47]
	v_mfma_f32_16x16x32_bf16 v[40:43], v[100:103], v[124:127], v[40:43]
	v_mfma_f32_16x16x32_bf16 v[36:39], v[92:95], v[132:135], v[36:39]
	v_mfma_f32_16x16x32_bf16 v[32:35], v[100:103], v[132:135], v[32:35]
	s_setprio 0
	s_setprio 1
	s_setprio 0
	s_barrier
	s_add_i32 s52, s76, s57
	v_lshl_add_u64 v[136:137], v[136:137], 0, s[20:21]
	s_mov_b32 m0, s52
	ds_read_b128 v[104:107], v87 offset:49152
	ds_read_b128 v[108:111], v87 offset:50176
	ds_read_b128 v[112:115], v87 offset:51200
	ds_read_b128 v[116:119], v87 offset:52224
	ds_read_b128 v[120:123], v87 offset:53248
	ds_read_b128 v[124:127], v87 offset:54272
	ds_read_b128 v[128:131], v87 offset:55296
	ds_read_b128 v[132:135], v87 offset:56320
	global_load_lds_dwordx4 v[136:137], off
	s_add_i32 m0, s52, 0x2000
	s_add_u32 s50, s50, 0x100080
	v_lshl_add_u64 v[136:137], v[138:139], 0, s[20:21]
	s_addc_u32 s51, s51, 0
	global_load_lds_dwordx4 v[136:137], off
	v_lshl_add_u64 v[136:137], s[50:51], 0, v[68:69]
	s_mov_b32 m0, s69
	s_nop 0
	global_load_lds_dwordx4 v[136:137], off
	v_lshl_add_u64 v[136:137], s[50:51], 0, v[64:65]
	s_mov_b32 m0, s70
	s_nop 0
	global_load_lds_dwordx4 v[136:137], off
	v_lshl_add_u64 v[136:137], v[140:141], 0, s[20:21]
	s_mov_b32 m0, s67
	s_nop 0
	global_load_lds_dwordx4 v[136:137], off
	v_lshl_add_u64 v[136:137], v[142:143], 0, s[20:21]
	s_mov_b32 m0, s68
	s_nop 0
	global_load_lds_dwordx4 v[136:137], off
	s_waitcnt vmcnt(8)
	s_waitcnt lgkmcnt(0)
	s_setprio 1
	s_barrier
	v_mfma_f32_16x16x32_bf16 v[28:31], v[88:91], v[104:107], v[28:31]
	v_mfma_f32_16x16x32_bf16 v[24:27], v[96:99], v[104:107], v[24:27]
	v_mfma_f32_16x16x32_bf16 v[20:23], v[88:91], v[112:115], v[20:23]
	v_mfma_f32_16x16x32_bf16 v[16:19], v[96:99], v[112:115], v[16:19]
	v_mfma_f32_16x16x32_bf16 v[12:15], v[88:91], v[120:123], v[12:15]
	v_mfma_f32_16x16x32_bf16 v[8:11], v[96:99], v[120:123], v[8:11]
	v_mfma_f32_16x16x32_bf16 v[4:7], v[88:91], v[128:131], v[4:7]
	v_mfma_f32_16x16x32_bf16 v[0:3], v[96:99], v[128:131], v[0:3]
	v_mfma_f32_16x16x32_bf16 v[28:31], v[92:95], v[108:111], v[28:31]
	v_mfma_f32_16x16x32_bf16 v[24:27], v[100:103], v[108:111], v[24:27]
	v_mfma_f32_16x16x32_bf16 v[20:23], v[92:95], v[116:119], v[20:23]
	v_mfma_f32_16x16x32_bf16 v[16:19], v[100:103], v[116:119], v[16:19]
	v_mfma_f32_16x16x32_bf16 v[12:15], v[92:95], v[124:127], v[12:15]
	v_mfma_f32_16x16x32_bf16 v[8:11], v[100:103], v[124:127], v[8:11]
	v_mfma_f32_16x16x32_bf16 v[4:7], v[92:95], v[132:135], v[4:7]
	v_mfma_f32_16x16x32_bf16 v[0:3], v[100:103], v[132:135], v[0:3]
	s_setprio 0
	s_setprio 1
	s_setprio 0
	s_barrier
	s_add_u32 s46, s46, 0x100
	s_addc_u32 s47, s47, 0
	s_add_u32 s13, s13, 0x100
	s_addc_u32 s41, s41, 0
	s_cmp_ge_i32 s43, s66
	s_mov_b32 s50, s43
	s_cbranch_scc0 .LBB0_220

; #define PG8_STAGE(bufoff, gbase, voff) do { _Pragma("unroll") for (int _i = 0; _i < 2; ++_i) \
;         __builtin_amdgcn_global_load_lds((const unsigned*)((const char*)(gbase) + (voff)[_i]), (LAS unsigned*)(lds + (bufoff) + ldsw + _i * 8192), 16, 0, 0); } while (0)
; #define PG8_LDA(dst, b, h) do { _Pragma("unroll") for (int m = 0; m < 4; ++m) _Pragma("unroll") for (int k = 0; k < 2; ++k) dst[m][k] = *(const LAS bf16x8*)(lds + PG8_SA(b, h) + aoff + m * 2048 + k * 1024); } while (0)
; #define PG8_LDB(dst, b, h) do { _Pragma("unroll") for (int n = 0; n < 2; ++n) _Pragma("unroll") for (int k = 0; k < 2; ++k) dst[n][k] = *(const LAS bf16x8*)(lds + PG8_SB(b, h) + boff + n * 2048 + k * 1024); } while (0)
; #define PG8_MMA(ai, bj, At, Bt) do { __builtin_amdgcn_s_setprio(1); _Pragma("unroll") for (int m = 0; m < 4; ++m) _Pragma("unroll") for (int n = 0; n < 2; ++n) _Pragma("unroll") for (int k = 0; k < 2; ++k) \
;         acc[ai][bj][m][n] = __builtin_amdgcn_mfma_f32_16x16x32_bf16(Bt[n][k], At[m][k], acc[ai][bj][m][n], 0, 0, 0); __builtin_amdgcn_s_setprio(0); } while (0)
; #define PG8_WAIT_V(n) asm volatile("s_waitcnt vmcnt(" #n ")" ::: "memory")
; template <class Epi>
; DI void gemm_phase(LAS unsigned char* lds, const Gemm g, const StaticOrder& S, const Epi& E) {
;     ...
;         for (int t = 0; t < nt; t += 2) {
;             const bool last = (t == nt - 2);
;             const char* a1 = cA + (size_t)(t + 1) * kstep;
;             const char* a2 = last ? nA : cA + (size_t)(t + 2) * kstep; const char* b2 = last ? nB : cB + (size_t)(t + 2) * kstep;
;             const char* a3 = a2 + kstep; const char* b3 = b2 + kstep;
;             PG8_LDB(B0, 0, 0); PG8_LDB(B1, 0, 1); PG8_SCHED; PG8_LDA(At, 0, 0); PG8_STAGE(PG8_SA(1, 1), a1 + hstepA, voffA);
;             PG8_WAIT_V(8); PG8_WAIT_L(0); PG8_BAR; PG8_MMA(0, 0, At, B0); PG8_MMA(0, 1, At, B1); PG8_BAR; PG8_SCHED;
;             PG8_LDA(At, 0, 1); PG8_STAGE(PG8_SB(0, 0), b2, voffB); PG8_STAGE(PG8_SB(0, 1), b2 + hstepB, voffB); PG8_STAGE(PG8_SA(0, 0), a2, voffA);
;             PG8_WAIT_V(8); PG8_WAIT_L(0); PG8_BAR; PG8_MMA(1, 0, At, B0); PG8_MMA(1, 1, At, B1); PG8_BAR; PG8_SCHED;
;             PG8_LDB(B0, 1, 0); PG8_LDB(B1, 1, 1); PG8_SCHED; PG8_LDA(At, 1, 0); PG8_STAGE(PG8_SA(0, 1), a2 + hstepA, voffA);
;             PG8_WAIT_V(8); PG8_WAIT_L(0); PG8_BAR; PG8_MMA(0, 0, At, B0); PG8_MMA(0, 1, At, B1); PG8_BAR; PG8_SCHED;
.LBB0_302:
	ds_read_b128 v[128:131], v174
	ds_read_b128 v[132:135], v174 offset:1024
	ds_read_b128 v[156:159], v174 offset:2048
	ds_read_b128 v[160:163], v174 offset:3072
	ds_read_b128 v[164:167], v175
	ds_read_b128 v[168:171], v175 offset:1024
	ds_read_b128 v[182:185], v175 offset:2048
	ds_read_b128 v[186:189], v175 offset:3072
	s_add_i32 s30, s10, 2
	s_add_u32 s6, s8, 0x100
	s_addc_u32 s7, s9, 0
	s_cmp_eq_u32 s68, s10
	s_cselect_b32 s10, s17, s18
	s_cselect_b32 s13, s43, s7
	s_cselect_b32 s12, s42, s6
	s_cselect_b32 s11, s16, s19
	v_lshl_add_u64 v[178:179], s[8:9], 0, v[148:149]
	s_add_i32 m0, s61, 0xc000
	ds_read_b128 v[190:193], v176
	ds_read_b128 v[194:197], v176 offset:1024
	ds_read_b128 v[198:201], v176 offset:2048
	ds_read_b128 v[202:205], v176 offset:3072
	ds_read_b128 v[206:209], v176 offset:4096
	ds_read_b128 v[210:213], v176 offset:5120
	ds_read_b128 v[214:217], v176 offset:6144
	ds_read_b128 v[218:221], v176 offset:7168
	global_load_lds_dwordx4 v[178:179], off
	v_lshl_add_u64 v[178:179], s[8:9], 0, v[150:151]
	s_add_i32 m0, s61, 0xe000
	s_nop 0
	global_load_lds_dwordx4 v[178:179], off
	s_waitcnt vmcnt(8)
	s_waitcnt lgkmcnt(0)
	s_setprio 1
	s_barrier
	v_mfma_f32_16x16x32_bf16 v[120:123], v[128:131], v[190:193], v[120:123]
	v_mfma_f32_16x16x32_bf16 v[120:123], v[132:135], v[194:197], v[120:123]
	v_mfma_f32_16x16x32_bf16 v[124:127], v[156:159], v[190:193], v[124:127]
	v_mfma_f32_16x16x32_bf16 v[124:127], v[160:163], v[194:197], v[124:127]
	v_mfma_f32_16x16x32_bf16 v[108:111], v[128:131], v[198:201], v[108:111]
	v_mfma_f32_16x16x32_bf16 v[108:111], v[132:135], v[202:205], v[108:111]
	v_mfma_f32_16x16x32_bf16 v[104:107], v[156:159], v[198:201], v[104:107]
	v_mfma_f32_16x16x32_bf16 v[104:107], v[160:163], v[202:205], v[104:107]
	v_mfma_f32_16x16x32_bf16 v[92:95], v[128:131], v[206:209], v[92:95]
	v_mfma_f32_16x16x32_bf16 v[92:95], v[132:135], v[210:213], v[92:95]
	v_mfma_f32_16x16x32_bf16 v[88:91], v[156:159], v[206:209], v[88:91]
	v_mfma_f32_16x16x32_bf16 v[88:91], v[160:163], v[210:213], v[88:91]
	v_mfma_f32_16x16x32_bf16 v[76:79], v[128:131], v[214:217], v[76:79]
	v_mfma_f32_16x16x32_bf16 v[76:79], v[132:135], v[218:221], v[76:79]
	v_mfma_f32_16x16x32_bf16 v[72:75], v[156:159], v[214:217], v[72:75]
	v_mfma_f32_16x16x32_bf16 v[72:75], v[160:163], v[218:221], v[72:75]
	s_setprio 0
	s_setprio 1
	v_mfma_f32_16x16x32_bf16 v[116:119], v[164:167], v[190:193], v[116:119]
	v_mfma_f32_16x16x32_bf16 v[116:119], v[168:171], v[194:197], v[116:119]
	v_mfma_f32_16x16x32_bf16 v[112:115], v[182:185], v[190:193], v[112:115]
	v_mfma_f32_16x16x32_bf16 v[112:115], v[186:189], v[194:197], v[112:115]
	v_mfma_f32_16x16x32_bf16 v[100:103], v[164:167], v[198:201], v[100:103]
	v_mfma_f32_16x16x32_bf16 v[100:103], v[168:171], v[202:205], v[100:103]
	v_mfma_f32_16x16x32_bf16 v[96:99], v[182:185], v[198:201], v[96:99]
	v_mfma_f32_16x16x32_bf16 v[96:99], v[186:189], v[202:205], v[96:99]
	v_mfma_f32_16x16x32_bf16 v[84:87], v[164:167], v[206:209], v[84:87]
	v_mfma_f32_16x16x32_bf16 v[84:87], v[168:171], v[210:213], v[84:87]
	v_mfma_f32_16x16x32_bf16 v[80:83], v[182:185], v[206:209], v[80:83]
	v_mfma_f32_16x16x32_bf16 v[80:83], v[186:189], v[210:213], v[80:83]
	v_mfma_f32_16x16x32_bf16 v[68:71], v[164:167], v[214:217], v[68:71]
	v_mfma_f32_16x16x32_bf16 v[68:71], v[168:171], v[218:221], v[68:71]
	v_mfma_f32_16x16x32_bf16 v[64:67], v[182:185], v[214:217], v[64:67]
	v_mfma_f32_16x16x32_bf16 v[64:67], v[186:189], v[218:221], v[64:67]
	s_setprio 0
	s_barrier
	s_add_i32 s8, s69, s59
	v_lshl_add_u64 v[178:179], s[10:11], 0, v[140:141]
	s_mov_b32 m0, s8
	ds_read_b128 v[190:193], v176 offset:16384
	ds_read_b128 v[194:197], v176 offset:17408
	ds_read_b128 v[198:201], v176 offset:18432
	ds_read_b128 v[202:205], v176 offset:19456
	ds_read_b128 v[206:209], v176 offset:20480
	ds_read_b128 v[210:213], v176 offset:21504
	ds_read_b128 v[214:217], v176 offset:22528
	ds_read_b128 v[218:221], v176 offset:23552
	global_load_lds_dwordx4 v[178:179], off
	s_add_i32 m0, s8, 0x2000
	s_add_u32 s8, s10, 0x40000
	v_lshl_add_u64 v[222:223], s[10:11], 0, v[136:137]
	s_addc_u32 s9, s11, 0
	s_add_i32 s41, s70, s59
	global_load_lds_dwordx4 v[222:223], off
	v_lshl_add_u64 v[224:225], s[8:9], 0, v[140:141]
	s_mov_b32 m0, s41
	v_lshl_add_u64 v[226:227], s[12:13], 0, v[138:139]
	global_load_lds_dwordx4 v[224:225], off
	v_lshl_add_u64 v[224:225], s[8:9], 0, v[136:137]
	s_add_i32 m0, s41, 0x2000
	s_nop 0
	global_load_lds_dwordx4 v[224:225], off
	v_lshl_add_u64 v[224:225], s[12:13], 0, v[142:143]
	s_mov_b32 m0, s61
	s_nop 0
	global_load_lds_dwordx4 v[224:225], off
	s_mov_b32 m0, s62
	s_nop 0
	global_load_lds_dwordx4 v[226:227], off
	s_waitcnt vmcnt(8)
	s_waitcnt lgkmcnt(0)
	s_setprio 1
	s_barrier
; #define PG8_STAGE(bufoff, gbase, voff) do { _Pragma("unroll") for (int _i = 0; _i < 2; ++_i) \
;         __builtin_amdgcn_global_load_lds((const unsigned*)((const char*)(gbase) + (voff)[_i]), (LAS unsigned*)(lds + (bufoff) + ldsw + _i * 8192), 16, 0, 0); } while (0)
; #define PG8_LDA(dst, b, h) do { _Pragma("unroll") for (int m = 0; m < 4; ++m) _Pragma("unroll") for (int k = 0; k < 2; ++k) dst[m][k] = *(const LAS bf16x8*)(lds + PG8_SA(b, h) + aoff + m * 2048 + k * 1024); } while (0)
; #define PG8_LDB(dst, b, h) do { _Pragma("unroll") for (int n = 0; n < 2; ++n) _Pragma("unroll") for (int k = 0; k < 2; ++k) dst[n][k] = *(const LAS bf16x8*)(lds + PG8_SB(b, h) + boff + n * 2048 + k * 1024); } while (0)
; #define PG8_MMA(ai, bj, At, Bt) do { __builtin_amdgcn_s_setprio(1); _Pragma("unroll") for (int m = 0; m < 4; ++m) _Pragma("unroll") for (int n = 0; n < 2; ++n) _Pragma("unroll") for (int k = 0; k < 2; ++k) \
;         acc[ai][bj][m][n] = __builtin_amdgcn_mfma_f32_16x16x32_bf16(Bt[n][k], At[m][k], acc[ai][bj][m][n], 0, 0, 0); __builtin_amdgcn_s_setprio(0); } while (0)
; #define PG8_WAIT_V(n) asm volatile("s_waitcnt vmcnt(" #n ")" ::: "memory")
; #define PG8_WAIT_L(n) asm volatile("s_waitcnt lgkmcnt(" #n ")" ::: "memory")
; template <class Epi>
; DI void gemm_phase(LAS unsigned char* lds, const Gemm g, const StaticOrder& S, const Epi& E) {
;     ...
;             PG8_LDB(B0, 0, 0); PG8_LDB(B1, 0, 1); PG8_SCHED; PG8_LDA(At, 0, 0); PG8_STAGE(PG8_SA(1, 1), a1 + hstepA, voffA);
;             PG8_WAIT_V(8); PG8_WAIT_L(0); PG8_BAR; PG8_MMA(0, 0, At, B0); PG8_MMA(0, 1, At, B1); PG8_BAR; PG8_SCHED;
;             PG8_LDA(At, 0, 1); PG8_STAGE(PG8_SB(0, 0), b2, voffB); PG8_STAGE(PG8_SB(0, 1), b2 + hstepB, voffB); PG8_STAGE(PG8_SA(0, 0), a2, voffA);
;             PG8_WAIT_V(8); PG8_WAIT_L(0); PG8_BAR; PG8_MMA(1, 0, At, B0); PG8_MMA(1, 1, At, B1); PG8_BAR; PG8_SCHED;
;             PG8_LDB(B0, 1, 0); PG8_LDB(B1, 1, 1); PG8_SCHED; PG8_LDA(At, 1, 0); PG8_STAGE(PG8_SA(0, 1), a2 + hstepA, voffA);
;             PG8_WAIT_V(8); PG8_WAIT_L(0); PG8_BAR; PG8_MMA(0, 0, At, B0); PG8_MMA(0, 1, At, B1); PG8_BAR; PG8_SCHED;
;             PG8_LDA(At, 1, 1); PG8_STAGE(PG8_SB(1, 0), b3, voffB); PG8_STAGE(PG8_SB(1, 1), b3 + hstepB, voffB); PG8_STAGE(PG8_SA(1, 0), a3, voffA);
;             PG8_WAIT_V(8); PG8_WAIT_L(0); PG8_BAR; PG8_MMA(1, 0, At, B0); PG8_MMA(1, 1, At, B1); PG8_BAR; PG8_SCHED;
	v_mfma_f32_16x16x32_bf16 v[60:63], v[128:131], v[190:193], v[60:63]
	v_mfma_f32_16x16x32_bf16 v[60:63], v[132:135], v[194:197], v[60:63]
	v_mfma_f32_16x16x32_bf16 v[56:59], v[156:159], v[190:193], v[56:59]
	v_mfma_f32_16x16x32_bf16 v[56:59], v[160:163], v[194:197], v[56:59]
	v_mfma_f32_16x16x32_bf16 v[44:47], v[128:131], v[198:201], v[44:47]
	v_mfma_f32_16x16x32_bf16 v[44:47], v[132:135], v[202:205], v[44:47]
	v_mfma_f32_16x16x32_bf16 v[40:43], v[156:159], v[198:201], v[40:43]
	v_mfma_f32_16x16x32_bf16 v[40:43], v[160:163], v[202:205], v[40:43]
	v_mfma_f32_16x16x32_bf16 v[28:31], v[128:131], v[206:209], v[28:31]
	v_mfma_f32_16x16x32_bf16 v[28:31], v[132:135], v[210:213], v[28:31]
	v_mfma_f32_16x16x32_bf16 v[24:27], v[156:159], v[206:209], v[24:27]
	v_mfma_f32_16x16x32_bf16 v[24:27], v[160:163], v[210:213], v[24:27]
	v_mfma_f32_16x16x32_bf16 v[12:15], v[128:131], v[214:217], v[12:15]
	v_mfma_f32_16x16x32_bf16 v[12:15], v[132:135], v[218:221], v[12:15]
	v_mfma_f32_16x16x32_bf16 v[8:11], v[156:159], v[214:217], v[8:11]
	v_mfma_f32_16x16x32_bf16 v[8:11], v[160:163], v[218:221], v[8:11]
	s_setprio 0
	s_setprio 1
	v_mfma_f32_16x16x32_bf16 v[52:55], v[164:167], v[190:193], v[52:55]
	v_mfma_f32_16x16x32_bf16 v[52:55], v[168:171], v[194:197], v[52:55]
	v_mfma_f32_16x16x32_bf16 v[48:51], v[182:185], v[190:193], v[48:51]
	v_mfma_f32_16x16x32_bf16 v[48:51], v[186:189], v[194:197], v[48:51]
	v_mfma_f32_16x16x32_bf16 v[36:39], v[164:167], v[198:201], v[36:39]
	v_mfma_f32_16x16x32_bf16 v[36:39], v[168:171], v[202:205], v[36:39]
	v_mfma_f32_16x16x32_bf16 v[32:35], v[182:185], v[198:201], v[32:35]
	v_mfma_f32_16x16x32_bf16 v[32:35], v[186:189], v[202:205], v[32:35]
	v_mfma_f32_16x16x32_bf16 v[20:23], v[164:167], v[206:209], v[20:23]
	v_mfma_f32_16x16x32_bf16 v[20:23], v[168:171], v[210:213], v[20:23]
	v_mfma_f32_16x16x32_bf16 v[16:19], v[182:185], v[206:209], v[16:19]
	v_mfma_f32_16x16x32_bf16 v[16:19], v[186:189], v[210:213], v[16:19]
	v_mfma_f32_16x16x32_bf16 v[4:7], v[164:167], v[214:217], v[4:7]
	v_mfma_f32_16x16x32_bf16 v[4:7], v[168:171], v[218:221], v[4:7]
	v_mfma_f32_16x16x32_bf16 v[0:3], v[182:185], v[214:217], v[0:3]
	v_mfma_f32_16x16x32_bf16 v[0:3], v[186:189], v[218:221], v[0:3]
	s_setprio 0
	s_barrier
	s_add_i32 s41, 0, 0x18000
	s_add_i32 s50, 0, 0x1c000
	v_add_u32_e32 v160, s41, v173
	v_add_u32_e32 v181, s50, v173
	ds_read_b128 v[128:131], v160
	ds_read_b128 v[132:135], v160 offset:1024
	ds_read_b128 v[156:159], v160 offset:2048
	ds_read_b128 v[160:163], v160 offset:3072
	ds_read_b128 v[164:167], v181
	ds_read_b128 v[168:171], v181 offset:1024
	ds_read_b128 v[182:185], v181 offset:2048
	ds_read_b128 v[186:189], v181 offset:3072
	s_add_u32 s8, s12, 0x110000
	s_addc_u32 s9, s13, 0
	s_mov_b32 m0, s63
	v_lshl_add_u64 v[228:229], s[8:9], 0, v[142:143]
	ds_read_b128 v[190:193], v176 offset:32768
	ds_read_b128 v[194:197], v176 offset:33792
	ds_read_b128 v[198:201], v176 offset:34816
	ds_read_b128 v[202:205], v176 offset:35840
	ds_read_b128 v[206:209], v176 offset:36864
	ds_read_b128 v[210:213], v176 offset:37888
	ds_read_b128 v[214:217], v176 offset:38912
	ds_read_b128 v[218:221], v176 offset:39936
	global_load_lds_dwordx4 v[228:229], off
	v_lshl_add_u64 v[228:229], s[8:9], 0, v[138:139]
	s_mov_b32 m0, s64
	s_nop 0
	global_load_lds_dwordx4 v[228:229], off
	s_waitcnt vmcnt(8)
	s_waitcnt lgkmcnt(0)
	s_setprio 1
	s_barrier
	v_mfma_f32_16x16x32_bf16 v[120:123], v[128:131], v[190:193], v[120:123]
	v_mfma_f32_16x16x32_bf16 v[120:123], v[132:135], v[194:197], v[120:123]
	v_mfma_f32_16x16x32_bf16 v[124:127], v[156:159], v[190:193], v[124:127]
	v_mfma_f32_16x16x32_bf16 v[124:127], v[160:163], v[194:197], v[124:127]
	v_mfma_f32_16x16x32_bf16 v[108:111], v[128:131], v[198:201], v[108:111]
	v_mfma_f32_16x16x32_bf16 v[108:111], v[132:135], v[202:205], v[108:111]
	v_mfma_f32_16x16x32_bf16 v[104:107], v[156:159], v[198:201], v[104:107]
	v_mfma_f32_16x16x32_bf16 v[104:107], v[160:163], v[202:205], v[104:107]
	v_mfma_f32_16x16x32_bf16 v[92:95], v[128:131], v[206:209], v[92:95]
	v_mfma_f32_16x16x32_bf16 v[92:95], v[132:135], v[210:213], v[92:95]
	v_mfma_f32_16x16x32_bf16 v[88:91], v[156:159], v[206:209], v[88:91]
	v_mfma_f32_16x16x32_bf16 v[88:91], v[160:163], v[210:213], v[88:91]
	v_mfma_f32_16x16x32_bf16 v[76:79], v[128:131], v[214:217], v[76:79]
	v_mfma_f32_16x16x32_bf16 v[76:79], v[132:135], v[218:221], v[76:79]
	v_mfma_f32_16x16x32_bf16 v[72:75], v[156:159], v[214:217], v[72:75]
	v_mfma_f32_16x16x32_bf16 v[72:75], v[160:163], v[218:221], v[72:75]
	s_setprio 0
	s_setprio 1
	v_mfma_f32_16x16x32_bf16 v[116:119], v[164:167], v[190:193], v[116:119]
	v_mfma_f32_16x16x32_bf16 v[116:119], v[168:171], v[194:197], v[116:119]
	v_mfma_f32_16x16x32_bf16 v[112:115], v[182:185], v[190:193], v[112:115]
	v_mfma_f32_16x16x32_bf16 v[112:115], v[186:189], v[194:197], v[112:115]
	v_mfma_f32_16x16x32_bf16 v[100:103], v[164:167], v[198:201], v[100:103]
	v_mfma_f32_16x16x32_bf16 v[100:103], v[168:171], v[202:205], v[100:103]
	v_mfma_f32_16x16x32_bf16 v[96:99], v[182:185], v[198:201], v[96:99]
	v_mfma_f32_16x16x32_bf16 v[96:99], v[186:189], v[202:205], v[96:99]
	v_mfma_f32_16x16x32_bf16 v[84:87], v[164:167], v[206:209], v[84:87]
	v_mfma_f32_16x16x32_bf16 v[84:87], v[168:171], v[210:213], v[84:87]
	v_mfma_f32_16x16x32_bf16 v[80:83], v[182:185], v[206:209], v[80:83]
	v_mfma_f32_16x16x32_bf16 v[80:83], v[186:189], v[210:213], v[80:83]
	v_mfma_f32_16x16x32_bf16 v[68:71], v[164:167], v[214:217], v[68:71]
	v_mfma_f32_16x16x32_bf16 v[68:71], v[168:171], v[218:221], v[68:71]
	v_mfma_f32_16x16x32_bf16 v[64:67], v[182:185], v[214:217], v[64:67]
	v_mfma_f32_16x16x32_bf16 v[64:67], v[186:189], v[218:221], v[64:67]
	s_setprio 0
	s_barrier
; #define PG8_STAGE(bufoff, gbase, voff) do { _Pragma("unroll") for (int _i = 0; _i < 2; ++_i) \
;         __builtin_amdgcn_global_load_lds((const unsigned*)((const char*)(gbase) + (voff)[_i]), (LAS unsigned*)(lds + (bufoff) + ldsw + _i * 8192), 16, 0, 0); } while (0)
; #define PG8_LDA(dst, b, h) do { _Pragma("unroll") for (int m = 0; m < 4; ++m) _Pragma("unroll") for (int k = 0; k < 2; ++k) dst[m][k] = *(const LAS bf16x8*)(lds + PG8_SA(b, h) + aoff + m * 2048 + k * 1024); } while (0)
; #define PG8_MMA(ai, bj, At, Bt) do { __builtin_amdgcn_s_setprio(1); _Pragma("unroll") for (int m = 0; m < 4; ++m) _Pragma("unroll") for (int n = 0; n < 2; ++n) _Pragma("unroll") for (int k = 0; k < 2; ++k) \
;         acc[ai][bj][m][n] = __builtin_amdgcn_mfma_f32_16x16x32_bf16(Bt[n][k], At[m][k], acc[ai][bj][m][n], 0, 0, 0); __builtin_amdgcn_s_setprio(0); } while (0)
; #define PG8_WAIT_V(n) asm volatile("s_waitcnt vmcnt(" #n ")" ::: "memory")
; #define PG8_WAIT_L(n) asm volatile("s_waitcnt lgkmcnt(" #n ")" ::: "memory")
; #define PG8_BAR __builtin_amdgcn_s_barrier()
; #define PG8_SCHED __builtin_amdgcn_sched_barrier(0)
; template <class Epi>
; DI void gemm_phase(LAS unsigned char* lds, const Gemm g, const StaticOrder& S, const Epi& E) {
;     ...
;         for (int t = 0; t < nt; t += 2) {
;     ...
;             PG8_LDA(At, 1, 1); PG8_STAGE(PG8_SB(1, 0), b3, voffB); PG8_STAGE(PG8_SB(1, 1), b3 + hstepB, voffB); PG8_STAGE(PG8_SA(1, 0), a3, voffA);
;             PG8_WAIT_V(8); PG8_WAIT_L(0); PG8_BAR; PG8_MMA(1, 0, At, B0); PG8_MMA(1, 1, At, B1); PG8_BAR; PG8_SCHED;
	s_add_i32 s8, s41, s59
	v_lshl_add_u64 v[178:179], v[178:179], 0, s[28:29]
	s_mov_b32 m0, s8
	ds_read_b128 v[190:193], v176 offset:49152
	ds_read_b128 v[194:197], v176 offset:50176
	ds_read_b128 v[198:201], v176 offset:51200
	ds_read_b128 v[202:205], v176 offset:52224
	ds_read_b128 v[206:209], v176 offset:53248
	ds_read_b128 v[210:213], v176 offset:54272
	ds_read_b128 v[214:217], v176 offset:55296
	ds_read_b128 v[218:221], v176 offset:56320
	global_load_lds_dwordx4 v[178:179], off
	s_add_i32 m0, s8, 0x2000
	s_add_u32 s8, s10, 0x40080
	v_lshl_add_u64 v[178:179], v[222:223], 0, s[28:29]
	s_addc_u32 s9, s11, 0
	s_add_i32 s10, s50, s59
	global_load_lds_dwordx4 v[178:179], off
	v_lshl_add_u64 v[178:179], s[8:9], 0, v[140:141]
	s_mov_b32 m0, s10
	s_nop 0
	global_load_lds_dwordx4 v[178:179], off
	v_lshl_add_u64 v[178:179], s[8:9], 0, v[136:137]
	s_add_i32 m0, s10, 0x2000
	s_nop 0
	global_load_lds_dwordx4 v[178:179], off
	v_lshl_add_u64 v[178:179], v[224:225], 0, s[28:29]
	s_mov_b32 m0, s66
	s_nop 0
	global_load_lds_dwordx4 v[178:179], off
	v_lshl_add_u64 v[178:179], v[226:227], 0, s[28:29]
	s_mov_b32 m0, s67
	s_nop 0
	global_load_lds_dwordx4 v[178:179], off
	s_waitcnt vmcnt(8)
	s_waitcnt lgkmcnt(0)
	s_setprio 1
	s_barrier
	v_mfma_f32_16x16x32_bf16 v[60:63], v[128:131], v[190:193], v[60:63]
	v_mfma_f32_16x16x32_bf16 v[60:63], v[132:135], v[194:197], v[60:63]
	v_mfma_f32_16x16x32_bf16 v[56:59], v[156:159], v[190:193], v[56:59]
	v_mfma_f32_16x16x32_bf16 v[56:59], v[160:163], v[194:197], v[56:59]
	v_mfma_f32_16x16x32_bf16 v[44:47], v[128:131], v[198:201], v[44:47]
	v_mfma_f32_16x16x32_bf16 v[44:47], v[132:135], v[202:205], v[44:47]
	v_mfma_f32_16x16x32_bf16 v[40:43], v[156:159], v[198:201], v[40:43]
	v_mfma_f32_16x16x32_bf16 v[40:43], v[160:163], v[202:205], v[40:43]
	v_mfma_f32_16x16x32_bf16 v[28:31], v[128:131], v[206:209], v[28:31]
	v_mfma_f32_16x16x32_bf16 v[28:31], v[132:135], v[210:213], v[28:31]
	v_mfma_f32_16x16x32_bf16 v[24:27], v[156:159], v[206:209], v[24:27]
	v_mfma_f32_16x16x32_bf16 v[24:27], v[160:163], v[210:213], v[24:27]
	v_mfma_f32_16x16x32_bf16 v[12:15], v[128:131], v[214:217], v[12:15]
	v_mfma_f32_16x16x32_bf16 v[12:15], v[132:135], v[218:221], v[12:15]
	v_mfma_f32_16x16x32_bf16 v[8:11], v[156:159], v[214:217], v[8:11]
	v_mfma_f32_16x16x32_bf16 v[8:11], v[160:163], v[218:221], v[8:11]
	s_setprio 0
	s_setprio 1
	v_mfma_f32_16x16x32_bf16 v[52:55], v[164:167], v[190:193], v[52:55]
	v_mfma_f32_16x16x32_bf16 v[52:55], v[168:171], v[194:197], v[52:55]
	v_mfma_f32_16x16x32_bf16 v[48:51], v[182:185], v[190:193], v[48:51]
	v_mfma_f32_16x16x32_bf16 v[48:51], v[186:189], v[194:197], v[48:51]
	v_mfma_f32_16x16x32_bf16 v[36:39], v[164:167], v[198:201], v[36:39]
	v_mfma_f32_16x16x32_bf16 v[36:39], v[168:171], v[202:205], v[36:39]
	v_mfma_f32_16x16x32_bf16 v[32:35], v[182:185], v[198:201], v[32:35]
	v_mfma_f32_16x16x32_bf16 v[32:35], v[186:189], v[202:205], v[32:35]
	v_mfma_f32_16x16x32_bf16 v[20:23], v[164:167], v[206:209], v[20:23]
	v_mfma_f32_16x16x32_bf16 v[20:23], v[168:171], v[210:213], v[20:23]
	v_mfma_f32_16x16x32_bf16 v[16:19], v[182:185], v[206:209], v[16:19]
	v_mfma_f32_16x16x32_bf16 v[16:19], v[186:189], v[210:213], v[16:19]
	v_mfma_f32_16x16x32_bf16 v[4:7], v[164:167], v[214:217], v[4:7]
	v_mfma_f32_16x16x32_bf16 v[4:7], v[168:171], v[218:221], v[4:7]
	v_mfma_f32_16x16x32_bf16 v[0:3], v[182:185], v[214:217], v[0:3]
	v_mfma_f32_16x16x32_bf16 v[0:3], v[186:189], v[218:221], v[0:3]
	s_setprio 0
	s_barrier
	s_add_u32 s18, s18, 0x100
	s_addc_u32 s19, s19, 0
	s_cmp_ge_i32 s30, s65
	s_mov_b64 s[8:9], s[6:7]
	s_mov_b32 s10, s30
	s_cbranch_scc0 .LBB0_302

; #define PG8_STAGE(bufoff, gbase, voff) do { _Pragma("unroll") for (int _i = 0; _i < 2; ++_i) \
;         __builtin_amdgcn_global_load_lds((const unsigned*)((const char*)(gbase) + (voff)[_i]), (LAS unsigned*)(lds + (bufoff) + ldsw + _i * 8192), 16, 0, 0); } while (0)
; #define PG8_LDA(dst, b, h) do { _Pragma("unroll") for (int m = 0; m < 4; ++m) _Pragma("unroll") for (int k = 0; k < 2; ++k) dst[m][k] = *(const LAS bf16x8*)(lds + PG8_SA(b, h) + aoff + m * 2048 + k * 1024); } while (0)
; #define PG8_LDB(dst, b, h) do { _Pragma("unroll") for (int n = 0; n < 2; ++n) _Pragma("unroll") for (int k = 0; k < 2; ++k) dst[n][k] = *(const LAS bf16x8*)(lds + PG8_SB(b, h) + boff + n * 2048 + k * 1024); } while (0)
; #define PG8_MMA(ai, bj, At, Bt) do { __builtin_amdgcn_s_setprio(1); _Pragma("unroll") for (int m = 0; m < 4; ++m) _Pragma("unroll") for (int n = 0; n < 2; ++n) _Pragma("unroll") for (int k = 0; k < 2; ++k) \
;         acc[ai][bj][m][n] = __builtin_amdgcn_mfma_f32_16x16x32_bf16(Bt[n][k], At[m][k], acc[ai][bj][m][n], 0, 0, 0); __builtin_amdgcn_s_setprio(0); } while (0)
; #define PG8_WAIT_V(n) asm volatile("s_waitcnt vmcnt(" #n ")" ::: "memory")
; template <class Epi>
; DI void gemm_phase(LAS unsigned char* lds, const Gemm g, const StaticOrder& S, const Epi& E) {
;     ...
;         for (int t = 0; t < nt; t += 2) {
;             const bool last = (t == nt - 2);
;             const char* a1 = cA + (size_t)(t + 1) * kstep;
;             const char* a2 = last ? nA : cA + (size_t)(t + 2) * kstep; const char* b2 = last ? nB : cB + (size_t)(t + 2) * kstep;
;             const char* a3 = a2 + kstep; const char* b3 = b2 + kstep;
;             PG8_LDB(B0, 0, 0); PG8_LDB(B1, 0, 1); PG8_SCHED; PG8_LDA(At, 0, 0); PG8_STAGE(PG8_SA(1, 1), a1 + hstepA, voffA);
;             PG8_WAIT_V(8); PG8_WAIT_L(0); PG8_BAR; PG8_MMA(0, 0, At, B0); PG8_MMA(0, 1, At, B1); PG8_BAR; PG8_SCHED;
;             PG8_LDA(At, 0, 1); PG8_STAGE(PG8_SB(0, 0), b2, voffB); PG8_STAGE(PG8_SB(0, 1), b2 + hstepB, voffB); PG8_STAGE(PG8_SA(0, 0), a2, voffA);
;             PG8_WAIT_V(8); PG8_WAIT_L(0); PG8_BAR; PG8_MMA(1, 0, At, B0); PG8_MMA(1, 1, At, B1); PG8_BAR; PG8_SCHED;
;             PG8_LDB(B0, 1, 0); PG8_LDB(B1, 1, 1); PG8_SCHED; PG8_LDA(At, 1, 0); PG8_STAGE(PG8_SA(0, 1), a2 + hstepA, voffA);
;             PG8_WAIT_V(8); PG8_WAIT_L(0); PG8_BAR; PG8_MMA(0, 0, At, B0); PG8_MMA(0, 1, At, B1); PG8_BAR; PG8_SCHED;
.LBB0_329:
	ds_read_b128 v[154:157], v150
	ds_read_b128 v[158:161], v150 offset:1024
	ds_read_b128 v[162:165], v150 offset:2048
	ds_read_b128 v[166:169], v150 offset:3072
	ds_read_b128 v[170:173], v151
	ds_read_b128 v[174:177], v151 offset:1024
	ds_read_b128 v[182:185], v151 offset:2048
	ds_read_b128 v[186:189], v151 offset:3072
	s_add_i32 s73, s30, 2
	s_add_u32 s6, s8, 0x100
	s_addc_u32 s7, s9, 0
	s_cmp_eq_u32 s62, s30
	s_cselect_b32 s30, s70, s71
	s_cselect_b32 s39, s27, s7
	s_cselect_b32 s38, s26, s6
	s_cselect_b32 s31, s25, s72
	v_lshl_add_u64 v[146:147], s[8:9], 0, v[138:139]
	s_add_i32 m0, s47, 0xc000
	ds_read_b128 v[190:193], v152
	ds_read_b128 v[194:197], v152 offset:1024
	ds_read_b128 v[198:201], v152 offset:2048
	ds_read_b128 v[202:205], v152 offset:3072
	ds_read_b128 v[206:209], v152 offset:4096
	ds_read_b128 v[210:213], v152 offset:5120
	ds_read_b128 v[214:217], v152 offset:6144
	ds_read_b128 v[218:221], v152 offset:7168
	global_load_lds_dwordx4 v[146:147], off
	v_lshl_add_u64 v[146:147], s[8:9], 0, v[140:141]
	s_add_i32 m0, s47, 0xe000
	s_nop 0
	global_load_lds_dwordx4 v[146:147], off
	s_waitcnt vmcnt(8)
	s_waitcnt lgkmcnt(0)
	s_setprio 1
	s_barrier
	v_mfma_f32_16x16x32_bf16 v[120:123], v[154:157], v[190:193], v[120:123]
	v_mfma_f32_16x16x32_bf16 v[120:123], v[158:161], v[194:197], v[120:123]
	v_mfma_f32_16x16x32_bf16 v[124:127], v[162:165], v[190:193], v[124:127]
	v_mfma_f32_16x16x32_bf16 v[124:127], v[166:169], v[194:197], v[124:127]
	v_mfma_f32_16x16x32_bf16 v[108:111], v[154:157], v[198:201], v[108:111]
	v_mfma_f32_16x16x32_bf16 v[108:111], v[158:161], v[202:205], v[108:111]
	v_mfma_f32_16x16x32_bf16 v[104:107], v[162:165], v[198:201], v[104:107]
	v_mfma_f32_16x16x32_bf16 v[104:107], v[166:169], v[202:205], v[104:107]
	v_mfma_f32_16x16x32_bf16 v[92:95], v[154:157], v[206:209], v[92:95]
	v_mfma_f32_16x16x32_bf16 v[92:95], v[158:161], v[210:213], v[92:95]
	v_mfma_f32_16x16x32_bf16 v[88:91], v[162:165], v[206:209], v[88:91]
	v_mfma_f32_16x16x32_bf16 v[88:91], v[166:169], v[210:213], v[88:91]
	v_mfma_f32_16x16x32_bf16 v[76:79], v[154:157], v[214:217], v[76:79]
	v_mfma_f32_16x16x32_bf16 v[76:79], v[158:161], v[218:221], v[76:79]
	v_mfma_f32_16x16x32_bf16 v[72:75], v[162:165], v[214:217], v[72:75]
	v_mfma_f32_16x16x32_bf16 v[72:75], v[166:169], v[218:221], v[72:75]
	s_setprio 0
	s_setprio 1
	v_mfma_f32_16x16x32_bf16 v[116:119], v[170:173], v[190:193], v[116:119]
	v_mfma_f32_16x16x32_bf16 v[116:119], v[174:177], v[194:197], v[116:119]
	v_mfma_f32_16x16x32_bf16 v[112:115], v[182:185], v[190:193], v[112:115]
	v_mfma_f32_16x16x32_bf16 v[112:115], v[186:189], v[194:197], v[112:115]
	v_mfma_f32_16x16x32_bf16 v[100:103], v[170:173], v[198:201], v[100:103]
	v_mfma_f32_16x16x32_bf16 v[100:103], v[174:177], v[202:205], v[100:103]
	v_mfma_f32_16x16x32_bf16 v[96:99], v[182:185], v[198:201], v[96:99]
	v_mfma_f32_16x16x32_bf16 v[96:99], v[186:189], v[202:205], v[96:99]
	v_mfma_f32_16x16x32_bf16 v[84:87], v[170:173], v[206:209], v[84:87]
	v_mfma_f32_16x16x32_bf16 v[84:87], v[174:177], v[210:213], v[84:87]
	v_mfma_f32_16x16x32_bf16 v[80:83], v[182:185], v[206:209], v[80:83]
	v_mfma_f32_16x16x32_bf16 v[80:83], v[186:189], v[210:213], v[80:83]
	v_mfma_f32_16x16x32_bf16 v[68:71], v[170:173], v[214:217], v[68:71]
	v_mfma_f32_16x16x32_bf16 v[68:71], v[174:177], v[218:221], v[68:71]
	v_mfma_f32_16x16x32_bf16 v[64:67], v[182:185], v[214:217], v[64:67]
	v_mfma_f32_16x16x32_bf16 v[64:67], v[186:189], v[218:221], v[64:67]
	s_setprio 0
	s_barrier
	s_add_i32 s8, s63, s41
	v_lshl_add_u64 v[146:147], s[30:31], 0, v[132:133]
	s_mov_b32 m0, s8
	ds_read_b128 v[190:193], v152 offset:16384
	ds_read_b128 v[194:197], v152 offset:17408
	ds_read_b128 v[198:201], v152 offset:18432
	ds_read_b128 v[202:205], v152 offset:19456
	ds_read_b128 v[206:209], v152 offset:20480
	ds_read_b128 v[210:213], v152 offset:21504
	ds_read_b128 v[214:217], v152 offset:22528
	ds_read_b128 v[218:221], v152 offset:23552
	global_load_lds_dwordx4 v[146:147], off
	s_add_i32 m0, s8, 0x2000
	s_add_u32 s8, s30, 0x20000
	v_lshl_add_u64 v[178:179], s[30:31], 0, v[128:129]
	s_addc_u32 s9, s31, 0
	s_add_i32 s74, s64, s41
	global_load_lds_dwordx4 v[178:179], off
	v_lshl_add_u64 v[222:223], s[8:9], 0, v[132:133]
	s_mov_b32 m0, s74
	v_lshl_add_u64 v[224:225], s[38:39], 0, v[130:131]
	global_load_lds_dwordx4 v[222:223], off
	v_lshl_add_u64 v[222:223], s[8:9], 0, v[128:129]
	s_add_i32 m0, s74, 0x2000
	s_nop 0
	global_load_lds_dwordx4 v[222:223], off
	v_lshl_add_u64 v[222:223], s[38:39], 0, v[134:135]
	s_mov_b32 m0, s47
	s_nop 0
	global_load_lds_dwordx4 v[222:223], off
	s_mov_b32 m0, s50
	s_nop 0
	global_load_lds_dwordx4 v[224:225], off
	s_waitcnt vmcnt(8)
	s_waitcnt lgkmcnt(0)
	s_setprio 1
	s_barrier
; #define PG8_STAGE(bufoff, gbase, voff) do { _Pragma("unroll") for (int _i = 0; _i < 2; ++_i) \
;         __builtin_amdgcn_global_load_lds((const unsigned*)((const char*)(gbase) + (voff)[_i]), (LAS unsigned*)(lds + (bufoff) + ldsw + _i * 8192), 16, 0, 0); } while (0)
; #define PG8_LDA(dst, b, h) do { _Pragma("unroll") for (int m = 0; m < 4; ++m) _Pragma("unroll") for (int k = 0; k < 2; ++k) dst[m][k] = *(const LAS bf16x8*)(lds + PG8_SA(b, h) + aoff + m * 2048 + k * 1024); } while (0)
; #define PG8_LDB(dst, b, h) do { _Pragma("unroll") for (int n = 0; n < 2; ++n) _Pragma("unroll") for (int k = 0; k < 2; ++k) dst[n][k] = *(const LAS bf16x8*)(lds + PG8_SB(b, h) + boff + n * 2048 + k * 1024); } while (0)
; #define PG8_MMA(ai, bj, At, Bt) do { __builtin_amdgcn_s_setprio(1); _Pragma("unroll") for (int m = 0; m < 4; ++m) _Pragma("unroll") for (int n = 0; n < 2; ++n) _Pragma("unroll") for (int k = 0; k < 2; ++k) \
;         acc[ai][bj][m][n] = __builtin_amdgcn_mfma_f32_16x16x32_bf16(Bt[n][k], At[m][k], acc[ai][bj][m][n], 0, 0, 0); __builtin_amdgcn_s_setprio(0); } while (0)
; #define PG8_WAIT_V(n) asm volatile("s_waitcnt vmcnt(" #n ")" ::: "memory")
; #define PG8_WAIT_L(n) asm volatile("s_waitcnt lgkmcnt(" #n ")" ::: "memory")
; template <class Epi>
; DI void gemm_phase(LAS unsigned char* lds, const Gemm g, const StaticOrder& S, const Epi& E) {
;     ...
;             PG8_LDB(B0, 0, 0); PG8_LDB(B1, 0, 1); PG8_SCHED; PG8_LDA(At, 0, 0); PG8_STAGE(PG8_SA(1, 1), a1 + hstepA, voffA);
;             PG8_WAIT_V(8); PG8_WAIT_L(0); PG8_BAR; PG8_MMA(0, 0, At, B0); PG8_MMA(0, 1, At, B1); PG8_BAR; PG8_SCHED;
;             PG8_LDA(At, 0, 1); PG8_STAGE(PG8_SB(0, 0), b2, voffB); PG8_STAGE(PG8_SB(0, 1), b2 + hstepB, voffB); PG8_STAGE(PG8_SA(0, 0), a2, voffA);
;             PG8_WAIT_V(8); PG8_WAIT_L(0); PG8_BAR; PG8_MMA(1, 0, At, B0); PG8_MMA(1, 1, At, B1); PG8_BAR; PG8_SCHED;
;             PG8_LDB(B0, 1, 0); PG8_LDB(B1, 1, 1); PG8_SCHED; PG8_LDA(At, 1, 0); PG8_STAGE(PG8_SA(0, 1), a2 + hstepA, voffA);
;             PG8_WAIT_V(8); PG8_WAIT_L(0); PG8_BAR; PG8_MMA(0, 0, At, B0); PG8_MMA(0, 1, At, B1); PG8_BAR; PG8_SCHED;
;             PG8_LDA(At, 1, 1); PG8_STAGE(PG8_SB(1, 0), b3, voffB); PG8_STAGE(PG8_SB(1, 1), b3 + hstepB, voffB); PG8_STAGE(PG8_SA(1, 0), a3, voffA);
;             PG8_WAIT_V(8); PG8_WAIT_L(0); PG8_BAR; PG8_MMA(1, 0, At, B0); PG8_MMA(1, 1, At, B1); PG8_BAR; PG8_SCHED;
	v_mfma_f32_16x16x32_bf16 v[60:63], v[154:157], v[190:193], v[60:63]
	v_mfma_f32_16x16x32_bf16 v[60:63], v[158:161], v[194:197], v[60:63]
	v_mfma_f32_16x16x32_bf16 v[56:59], v[162:165], v[190:193], v[56:59]
	v_mfma_f32_16x16x32_bf16 v[56:59], v[166:169], v[194:197], v[56:59]
	v_mfma_f32_16x16x32_bf16 v[44:47], v[154:157], v[198:201], v[44:47]
	v_mfma_f32_16x16x32_bf16 v[44:47], v[158:161], v[202:205], v[44:47]
	v_mfma_f32_16x16x32_bf16 v[40:43], v[162:165], v[198:201], v[40:43]
	v_mfma_f32_16x16x32_bf16 v[40:43], v[166:169], v[202:205], v[40:43]
	v_mfma_f32_16x16x32_bf16 v[28:31], v[154:157], v[206:209], v[28:31]
	v_mfma_f32_16x16x32_bf16 v[28:31], v[158:161], v[210:213], v[28:31]
	v_mfma_f32_16x16x32_bf16 v[24:27], v[162:165], v[206:209], v[24:27]
	v_mfma_f32_16x16x32_bf16 v[24:27], v[166:169], v[210:213], v[24:27]
	v_mfma_f32_16x16x32_bf16 v[12:15], v[154:157], v[214:217], v[12:15]
	v_mfma_f32_16x16x32_bf16 v[12:15], v[158:161], v[218:221], v[12:15]
	v_mfma_f32_16x16x32_bf16 v[8:11], v[162:165], v[214:217], v[8:11]
	v_mfma_f32_16x16x32_bf16 v[8:11], v[166:169], v[218:221], v[8:11]
	s_setprio 0
	s_setprio 1
	v_mfma_f32_16x16x32_bf16 v[52:55], v[170:173], v[190:193], v[52:55]
	v_mfma_f32_16x16x32_bf16 v[52:55], v[174:177], v[194:197], v[52:55]
	v_mfma_f32_16x16x32_bf16 v[48:51], v[182:185], v[190:193], v[48:51]
	v_mfma_f32_16x16x32_bf16 v[48:51], v[186:189], v[194:197], v[48:51]
	v_mfma_f32_16x16x32_bf16 v[36:39], v[170:173], v[198:201], v[36:39]
	v_mfma_f32_16x16x32_bf16 v[36:39], v[174:177], v[202:205], v[36:39]
	v_mfma_f32_16x16x32_bf16 v[32:35], v[182:185], v[198:201], v[32:35]
	v_mfma_f32_16x16x32_bf16 v[32:35], v[186:189], v[202:205], v[32:35]
	v_mfma_f32_16x16x32_bf16 v[20:23], v[170:173], v[206:209], v[20:23]
	v_mfma_f32_16x16x32_bf16 v[20:23], v[174:177], v[210:213], v[20:23]
	v_mfma_f32_16x16x32_bf16 v[16:19], v[182:185], v[206:209], v[16:19]
	v_mfma_f32_16x16x32_bf16 v[16:19], v[186:189], v[210:213], v[16:19]
	v_mfma_f32_16x16x32_bf16 v[4:7], v[170:173], v[214:217], v[4:7]
	v_mfma_f32_16x16x32_bf16 v[4:7], v[174:177], v[218:221], v[4:7]
	v_mfma_f32_16x16x32_bf16 v[0:3], v[182:185], v[214:217], v[0:3]
	v_mfma_f32_16x16x32_bf16 v[0:3], v[186:189], v[218:221], v[0:3]
	s_setprio 0
	s_barrier
	s_add_i32 s74, 0, 0x18000
	s_add_i32 s75, 0, 0x1c000
	v_add_u32_e32 v166, s74, v149
	v_add_u32_e32 v181, s75, v149
	ds_read_b128 v[154:157], v166
	ds_read_b128 v[158:161], v166 offset:1024
	ds_read_b128 v[162:165], v166 offset:2048
	ds_read_b128 v[166:169], v166 offset:3072
	ds_read_b128 v[170:173], v181
	ds_read_b128 v[174:177], v181 offset:1024
	ds_read_b128 v[182:185], v181 offset:2048
	ds_read_b128 v[186:189], v181 offset:3072
	s_add_u32 s8, s38, 0x110000
	s_addc_u32 s9, s39, 0
	s_mov_b32 m0, s51
	v_lshl_add_u64 v[226:227], s[8:9], 0, v[134:135]
	ds_read_b128 v[190:193], v152 offset:32768
	ds_read_b128 v[194:197], v152 offset:33792
	ds_read_b128 v[198:201], v152 offset:34816
	ds_read_b128 v[202:205], v152 offset:35840
	ds_read_b128 v[206:209], v152 offset:36864
	ds_read_b128 v[210:213], v152 offset:37888
	ds_read_b128 v[214:217], v152 offset:38912
	ds_read_b128 v[218:221], v152 offset:39936
	global_load_lds_dwordx4 v[226:227], off
	v_lshl_add_u64 v[226:227], s[8:9], 0, v[130:131]
	s_mov_b32 m0, s56
	s_nop 0
	global_load_lds_dwordx4 v[226:227], off
	s_waitcnt vmcnt(8)
	s_waitcnt lgkmcnt(0)
	s_setprio 1
	s_barrier
	v_mfma_f32_16x16x32_bf16 v[120:123], v[154:157], v[190:193], v[120:123]
	v_mfma_f32_16x16x32_bf16 v[120:123], v[158:161], v[194:197], v[120:123]
	v_mfma_f32_16x16x32_bf16 v[124:127], v[162:165], v[190:193], v[124:127]
	v_mfma_f32_16x16x32_bf16 v[124:127], v[166:169], v[194:197], v[124:127]
	v_mfma_f32_16x16x32_bf16 v[108:111], v[154:157], v[198:201], v[108:111]
	v_mfma_f32_16x16x32_bf16 v[108:111], v[158:161], v[202:205], v[108:111]
	v_mfma_f32_16x16x32_bf16 v[104:107], v[162:165], v[198:201], v[104:107]
	v_mfma_f32_16x16x32_bf16 v[104:107], v[166:169], v[202:205], v[104:107]
	v_mfma_f32_16x16x32_bf16 v[92:95], v[154:157], v[206:209], v[92:95]
	v_mfma_f32_16x16x32_bf16 v[92:95], v[158:161], v[210:213], v[92:95]
	v_mfma_f32_16x16x32_bf16 v[88:91], v[162:165], v[206:209], v[88:91]
	v_mfma_f32_16x16x32_bf16 v[88:91], v[166:169], v[210:213], v[88:91]
	v_mfma_f32_16x16x32_bf16 v[76:79], v[154:157], v[214:217], v[76:79]
	v_mfma_f32_16x16x32_bf16 v[76:79], v[158:161], v[218:221], v[76:79]
	v_mfma_f32_16x16x32_bf16 v[72:75], v[162:165], v[214:217], v[72:75]
	v_mfma_f32_16x16x32_bf16 v[72:75], v[166:169], v[218:221], v[72:75]
	s_setprio 0
	s_setprio 1
	v_mfma_f32_16x16x32_bf16 v[116:119], v[170:173], v[190:193], v[116:119]
	v_mfma_f32_16x16x32_bf16 v[116:119], v[174:177], v[194:197], v[116:119]
	v_mfma_f32_16x16x32_bf16 v[112:115], v[182:185], v[190:193], v[112:115]
	v_mfma_f32_16x16x32_bf16 v[112:115], v[186:189], v[194:197], v[112:115]
	v_mfma_f32_16x16x32_bf16 v[100:103], v[170:173], v[198:201], v[100:103]
	v_mfma_f32_16x16x32_bf16 v[100:103], v[174:177], v[202:205], v[100:103]
	v_mfma_f32_16x16x32_bf16 v[96:99], v[182:185], v[198:201], v[96:99]
	v_mfma_f32_16x16x32_bf16 v[96:99], v[186:189], v[202:205], v[96:99]
	v_mfma_f32_16x16x32_bf16 v[84:87], v[170:173], v[206:209], v[84:87]
	v_mfma_f32_16x16x32_bf16 v[84:87], v[174:177], v[210:213], v[84:87]
	v_mfma_f32_16x16x32_bf16 v[80:83], v[182:185], v[206:209], v[80:83]
	v_mfma_f32_16x16x32_bf16 v[80:83], v[186:189], v[210:213], v[80:83]
	v_mfma_f32_16x16x32_bf16 v[68:71], v[170:173], v[214:217], v[68:71]
	v_mfma_f32_16x16x32_bf16 v[68:71], v[174:177], v[218:221], v[68:71]
	v_mfma_f32_16x16x32_bf16 v[64:67], v[182:185], v[214:217], v[64:67]
	v_mfma_f32_16x16x32_bf16 v[64:67], v[186:189], v[218:221], v[64:67]
	s_setprio 0
	s_barrier
; #define PG8_STAGE(bufoff, gbase, voff) do { _Pragma("unroll") for (int _i = 0; _i < 2; ++_i) \
;         __builtin_amdgcn_global_load_lds((const unsigned*)((const char*)(gbase) + (voff)[_i]), (LAS unsigned*)(lds + (bufoff) + ldsw + _i * 8192), 16, 0, 0); } while (0)
; #define PG8_LDA(dst, b, h) do { _Pragma("unroll") for (int m = 0; m < 4; ++m) _Pragma("unroll") for (int k = 0; k < 2; ++k) dst[m][k] = *(const LAS bf16x8*)(lds + PG8_SA(b, h) + aoff + m * 2048 + k * 1024); } while (0)
; #define PG8_MMA(ai, bj, At, Bt) do { __builtin_amdgcn_s_setprio(1); _Pragma("unroll") for (int m = 0; m < 4; ++m) _Pragma("unroll") for (int n = 0; n < 2; ++n) _Pragma("unroll") for (int k = 0; k < 2; ++k) \
;         acc[ai][bj][m][n] = __builtin_amdgcn_mfma_f32_16x16x32_bf16(Bt[n][k], At[m][k], acc[ai][bj][m][n], 0, 0, 0); __builtin_amdgcn_s_setprio(0); } while (0)
; #define PG8_WAIT_V(n) asm volatile("s_waitcnt vmcnt(" #n ")" ::: "memory")
; #define PG8_WAIT_L(n) asm volatile("s_waitcnt lgkmcnt(" #n ")" ::: "memory")
; #define PG8_BAR __builtin_amdgcn_s_barrier()
; #define PG8_SCHED __builtin_amdgcn_sched_barrier(0)
; template <class Epi>
; DI void gemm_phase(LAS unsigned char* lds, const Gemm g, const StaticOrder& S, const Epi& E) {
;     ...
;             PG8_LDA(At, 1, 1); PG8_STAGE(PG8_SB(1, 0), b3, voffB); PG8_STAGE(PG8_SB(1, 1), b3 + hstepB, voffB); PG8_STAGE(PG8_SA(1, 0), a3, voffA);
;             PG8_WAIT_V(8); PG8_WAIT_L(0); PG8_BAR; PG8_MMA(1, 0, At, B0); PG8_MMA(1, 1, At, B1); PG8_BAR; PG8_SCHED;
;         }
	s_add_i32 s8, s74, s41
	v_lshl_add_u64 v[146:147], v[146:147], 0, s[16:17]
	s_mov_b32 m0, s8
	ds_read_b128 v[190:193], v152 offset:49152
	ds_read_b128 v[194:197], v152 offset:50176
	ds_read_b128 v[198:201], v152 offset:51200
	ds_read_b128 v[202:205], v152 offset:52224
	ds_read_b128 v[206:209], v152 offset:53248
	ds_read_b128 v[210:213], v152 offset:54272
	ds_read_b128 v[214:217], v152 offset:55296
	ds_read_b128 v[218:221], v152 offset:56320
	global_load_lds_dwordx4 v[146:147], off
	s_add_i32 m0, s8, 0x2000
	s_add_u32 s8, s30, 0x20080
	v_lshl_add_u64 v[146:147], v[178:179], 0, s[16:17]
	s_addc_u32 s9, s31, 0
	s_add_i32 s30, s75, s41
	global_load_lds_dwordx4 v[146:147], off
	v_lshl_add_u64 v[146:147], s[8:9], 0, v[132:133]
	s_mov_b32 m0, s30
	s_nop 0
	global_load_lds_dwordx4 v[146:147], off
	v_lshl_add_u64 v[146:147], s[8:9], 0, v[128:129]
	s_add_i32 m0, s30, 0x2000
	s_nop 0
	global_load_lds_dwordx4 v[146:147], off
	v_lshl_add_u64 v[146:147], v[222:223], 0, s[16:17]
	s_mov_b32 m0, s60
	s_nop 0
	global_load_lds_dwordx4 v[146:147], off
	v_lshl_add_u64 v[146:147], v[224:225], 0, s[16:17]
	s_mov_b32 m0, s61
	s_nop 0
	global_load_lds_dwordx4 v[146:147], off
	s_waitcnt vmcnt(8)
	s_waitcnt lgkmcnt(0)
	s_setprio 1
	s_barrier
	v_mfma_f32_16x16x32_bf16 v[60:63], v[154:157], v[190:193], v[60:63]
	v_mfma_f32_16x16x32_bf16 v[60:63], v[158:161], v[194:197], v[60:63]
	v_mfma_f32_16x16x32_bf16 v[56:59], v[162:165], v[190:193], v[56:59]
	v_mfma_f32_16x16x32_bf16 v[56:59], v[166:169], v[194:197], v[56:59]
	v_mfma_f32_16x16x32_bf16 v[44:47], v[154:157], v[198:201], v[44:47]
	v_mfma_f32_16x16x32_bf16 v[44:47], v[158:161], v[202:205], v[44:47]
	v_mfma_f32_16x16x32_bf16 v[40:43], v[162:165], v[198:201], v[40:43]
	v_mfma_f32_16x16x32_bf16 v[40:43], v[166:169], v[202:205], v[40:43]
	v_mfma_f32_16x16x32_bf16 v[28:31], v[154:157], v[206:209], v[28:31]
	v_mfma_f32_16x16x32_bf16 v[28:31], v[158:161], v[210:213], v[28:31]
	v_mfma_f32_16x16x32_bf16 v[24:27], v[162:165], v[206:209], v[24:27]
	v_mfma_f32_16x16x32_bf16 v[24:27], v[166:169], v[210:213], v[24:27]
	v_mfma_f32_16x16x32_bf16 v[12:15], v[154:157], v[214:217], v[12:15]
	v_mfma_f32_16x16x32_bf16 v[12:15], v[158:161], v[218:221], v[12:15]
	v_mfma_f32_16x16x32_bf16 v[8:11], v[162:165], v[214:217], v[8:11]
	v_mfma_f32_16x16x32_bf16 v[8:11], v[166:169], v[218:221], v[8:11]
	s_setprio 0
	s_setprio 1
	v_mfma_f32_16x16x32_bf16 v[52:55], v[170:173], v[190:193], v[52:55]
	v_mfma_f32_16x16x32_bf16 v[52:55], v[174:177], v[194:197], v[52:55]
	v_mfma_f32_16x16x32_bf16 v[48:51], v[182:185], v[190:193], v[48:51]
	v_mfma_f32_16x16x32_bf16 v[48:51], v[186:189], v[194:197], v[48:51]
	v_mfma_f32_16x16x32_bf16 v[36:39], v[170:173], v[198:201], v[36:39]
	v_mfma_f32_16x16x32_bf16 v[36:39], v[174:177], v[202:205], v[36:39]
	v_mfma_f32_16x16x32_bf16 v[32:35], v[182:185], v[198:201], v[32:35]
	v_mfma_f32_16x16x32_bf16 v[32:35], v[186:189], v[202:205], v[32:35]
	v_mfma_f32_16x16x32_bf16 v[20:23], v[170:173], v[206:209], v[20:23]
	v_mfma_f32_16x16x32_bf16 v[20:23], v[174:177], v[210:213], v[20:23]
	v_mfma_f32_16x16x32_bf16 v[16:19], v[182:185], v[206:209], v[16:19]
	v_mfma_f32_16x16x32_bf16 v[16:19], v[186:189], v[210:213], v[16:19]
	v_mfma_f32_16x16x32_bf16 v[4:7], v[170:173], v[214:217], v[4:7]
	v_mfma_f32_16x16x32_bf16 v[4:7], v[174:177], v[218:221], v[4:7]
	v_mfma_f32_16x16x32_bf16 v[0:3], v[182:185], v[214:217], v[0:3]
	v_mfma_f32_16x16x32_bf16 v[0:3], v[186:189], v[218:221], v[0:3]
	s_setprio 0
	s_barrier
	s_add_u32 s71, s71, 0x100
	s_addc_u32 s72, s72, 0
	s_cmp_ge_i32 s73, s59
	s_mov_b64 s[8:9], s[6:7]
	s_mov_b32 s30, s73
	s_cbranch_scc0 .LBB0_329

; #define PG8_STAGE(bufoff, gbase, voff) do { _Pragma("unroll") for (int _i = 0; _i < 2; ++_i) \
;         __builtin_amdgcn_global_load_lds((const unsigned*)((const char*)(gbase) + (voff)[_i]), (LAS unsigned*)(lds + (bufoff) + ldsw + _i * 8192), 16, 0, 0); } while (0)
; #define PG8_LDA(dst, b, h) do { _Pragma("unroll") for (int m = 0; m < 4; ++m) _Pragma("unroll") for (int k = 0; k < 2; ++k) dst[m][k] = *(const LAS bf16x8*)(lds + PG8_SA(b, h) + aoff + m * 2048 + k * 1024); } while (0)
; #define PG8_LDB(dst, b, h) do { _Pragma("unroll") for (int n = 0; n < 2; ++n) _Pragma("unroll") for (int k = 0; k < 2; ++k) dst[n][k] = *(const LAS bf16x8*)(lds + PG8_SB(b, h) + boff + n * 2048 + k * 1024); } while (0)
; #define PG8_MMA(ai, bj, At, Bt) do { __builtin_amdgcn_s_setprio(1); _Pragma("unroll") for (int m = 0; m < 4; ++m) _Pragma("unroll") for (int n = 0; n < 2; ++n) _Pragma("unroll") for (int k = 0; k < 2; ++k) \
;         acc[ai][bj][m][n] = __builtin_amdgcn_mfma_f32_16x16x32_bf16(Bt[n][k], At[m][k], acc[ai][bj][m][n], 0, 0, 0); __builtin_amdgcn_s_setprio(0); } while (0)
; #define PG8_WAIT_V(n) asm volatile("s_waitcnt vmcnt(" #n ")" ::: "memory")
; #define PG8_WAIT_L(n) asm volatile("s_waitcnt lgkmcnt(" #n ")" ::: "memory")
; #define PG8_BAR __builtin_amdgcn_s_barrier()
; #define PG8_SCHED __builtin_amdgcn_sched_barrier(0)
; template <class Epi>
; DI void gemm_phase(LAS unsigned char* lds, const Gemm g, const StaticOrder& S, const Epi& E) {
;     ...
;             PG8_LDB(B0, 0, 0); PG8_LDB(B1, 0, 1); PG8_SCHED; PG8_LDA(At, 0, 0); PG8_STAGE(PG8_SA(1, 1), a1 + hstepA, voffA);
;             PG8_WAIT_V(8); PG8_WAIT_L(0); PG8_BAR; PG8_MMA(0, 0, At, B0); PG8_MMA(0, 1, At, B1); PG8_BAR; PG8_SCHED;
;             PG8_LDA(At, 0, 1); PG8_STAGE(PG8_SB(0, 0), b2, voffB); PG8_STAGE(PG8_SB(0, 1), b2 + hstepB, voffB); PG8_STAGE(PG8_SA(0, 0), a2, voffA);
;             PG8_WAIT_V(8); PG8_WAIT_L(0); PG8_BAR; PG8_MMA(1, 0, At, B0); PG8_MMA(1, 1, At, B1); PG8_BAR; PG8_SCHED;
.LBB0_352:
	ds_read_b128 v[146:149], v167
	ds_read_b128 v[150:153], v167 offset:1024
	ds_read_b128 v[154:157], v167 offset:2048
	ds_read_b128 v[158:161], v167 offset:3072
	ds_read_b128 v[172:175], v168
	ds_read_b128 v[176:179], v168 offset:1024
	ds_read_b128 v[182:185], v168 offset:2048
	ds_read_b128 v[186:189], v168 offset:3072
	s_add_i32 s16, s8, 2
	s_add_u32 s9, s6, 0xfffe0080
	s_addc_u32 s10, s7, -1
	s_cmp_eq_u32 s76, s8
	s_cselect_b32 s8, s60, s14
	s_cselect_b32 s11, s12, s10
	s_cselect_b32 s10, s13, s9
	s_cselect_b32 s9, s61, s15
	v_lshl_add_u64 v[162:163], s[6:7], 0, v[138:139]
	s_add_i32 m0, s65, 0xc000
	ds_read_b128 v[190:193], v169
	ds_read_b128 v[194:197], v169 offset:1024
	ds_read_b128 v[198:201], v169 offset:2048
	ds_read_b128 v[202:205], v169 offset:3072
	ds_read_b128 v[206:209], v169 offset:4096
	ds_read_b128 v[210:213], v169 offset:5120
	ds_read_b128 v[214:217], v169 offset:6144
	ds_read_b128 v[218:221], v169 offset:7168
	global_load_lds_dwordx4 v[162:163], off
	v_lshl_add_u64 v[162:163], s[6:7], 0, v[140:141]
	s_add_i32 m0, s65, 0xe000
	s_nop 0
	global_load_lds_dwordx4 v[162:163], off
	s_waitcnt vmcnt(8)
	s_waitcnt lgkmcnt(0)
	s_setprio 1
	s_barrier
	v_mfma_f32_16x16x32_bf16 v[124:127], v[146:149], v[190:193], v[124:127]
	v_mfma_f32_16x16x32_bf16 v[124:127], v[150:153], v[194:197], v[124:127]
	v_mfma_f32_16x16x32_bf16 v[120:123], v[154:157], v[190:193], v[120:123]
	v_mfma_f32_16x16x32_bf16 v[120:123], v[158:161], v[194:197], v[120:123]
	v_mfma_f32_16x16x32_bf16 v[108:111], v[146:149], v[198:201], v[108:111]
	v_mfma_f32_16x16x32_bf16 v[108:111], v[150:153], v[202:205], v[108:111]
	v_mfma_f32_16x16x32_bf16 v[104:107], v[154:157], v[198:201], v[104:107]
	v_mfma_f32_16x16x32_bf16 v[104:107], v[158:161], v[202:205], v[104:107]
	v_mfma_f32_16x16x32_bf16 v[92:95], v[146:149], v[206:209], v[92:95]
	v_mfma_f32_16x16x32_bf16 v[92:95], v[150:153], v[210:213], v[92:95]
	v_mfma_f32_16x16x32_bf16 v[88:91], v[154:157], v[206:209], v[88:91]
	v_mfma_f32_16x16x32_bf16 v[88:91], v[158:161], v[210:213], v[88:91]
	v_mfma_f32_16x16x32_bf16 v[76:79], v[146:149], v[214:217], v[76:79]
	v_mfma_f32_16x16x32_bf16 v[76:79], v[150:153], v[218:221], v[76:79]
	v_mfma_f32_16x16x32_bf16 v[72:75], v[154:157], v[214:217], v[72:75]
	v_mfma_f32_16x16x32_bf16 v[72:75], v[158:161], v[218:221], v[72:75]
	s_setprio 0
	s_setprio 1
	v_mfma_f32_16x16x32_bf16 v[116:119], v[172:175], v[190:193], v[116:119]
	v_mfma_f32_16x16x32_bf16 v[116:119], v[176:179], v[194:197], v[116:119]
	v_mfma_f32_16x16x32_bf16 v[112:115], v[182:185], v[190:193], v[112:115]
	v_mfma_f32_16x16x32_bf16 v[112:115], v[186:189], v[194:197], v[112:115]
	v_mfma_f32_16x16x32_bf16 v[100:103], v[172:175], v[198:201], v[100:103]
	v_mfma_f32_16x16x32_bf16 v[100:103], v[176:179], v[202:205], v[100:103]
	v_mfma_f32_16x16x32_bf16 v[96:99], v[182:185], v[198:201], v[96:99]
	v_mfma_f32_16x16x32_bf16 v[96:99], v[186:189], v[202:205], v[96:99]
	v_mfma_f32_16x16x32_bf16 v[84:87], v[172:175], v[206:209], v[84:87]
	v_mfma_f32_16x16x32_bf16 v[84:87], v[176:179], v[210:213], v[84:87]
	v_mfma_f32_16x16x32_bf16 v[80:83], v[182:185], v[206:209], v[80:83]
	v_mfma_f32_16x16x32_bf16 v[80:83], v[186:189], v[210:213], v[80:83]
	v_mfma_f32_16x16x32_bf16 v[68:71], v[172:175], v[214:217], v[68:71]
	v_mfma_f32_16x16x32_bf16 v[68:71], v[176:179], v[218:221], v[68:71]
	v_mfma_f32_16x16x32_bf16 v[64:67], v[182:185], v[214:217], v[64:67]
	v_mfma_f32_16x16x32_bf16 v[64:67], v[186:189], v[218:221], v[64:67]
	s_setprio 0
	s_barrier
	s_add_i32 s17, s77, s66
	v_lshl_add_u64 v[162:163], s[8:9], 0, v[132:133]
	s_mov_b32 m0, s17
	ds_read_b128 v[190:193], v169 offset:16384
	ds_read_b128 v[194:197], v169 offset:17408
	ds_read_b128 v[198:201], v169 offset:18432
	ds_read_b128 v[202:205], v169 offset:19456
	ds_read_b128 v[206:209], v169 offset:20480
	ds_read_b128 v[210:213], v169 offset:21504
	ds_read_b128 v[214:217], v169 offset:22528
	ds_read_b128 v[218:221], v169 offset:23552
	global_load_lds_dwordx4 v[162:163], off
	s_add_i32 m0, s17, 0x2000
	s_add_u32 s18, s8, 0x110000
	v_lshl_add_u64 v[222:223], s[8:9], 0, v[128:129]
	s_addc_u32 s19, s9, 0
	s_add_i32 s17, s78, s66
	global_load_lds_dwordx4 v[222:223], off
	v_lshl_add_u64 v[224:225], s[18:19], 0, v[132:133]
	s_mov_b32 m0, s17
	v_lshl_add_u64 v[226:227], s[10:11], 0, v[130:131]
	global_load_lds_dwordx4 v[224:225], off
	v_lshl_add_u64 v[224:225], s[18:19], 0, v[128:129]
	s_add_i32 m0, s17, 0x2000
	s_nop 0
	global_load_lds_dwordx4 v[224:225], off
	v_lshl_add_u64 v[224:225], s[10:11], 0, v[134:135]
	s_mov_b32 m0, s65
	s_nop 0
	global_load_lds_dwordx4 v[224:225], off
	s_mov_b32 m0, s69
	s_nop 0
	global_load_lds_dwordx4 v[226:227], off
	s_waitcnt vmcnt(8)
	s_waitcnt lgkmcnt(0)
	s_setprio 1
	s_barrier
; #define PG8_STAGE(bufoff, gbase, voff) do { _Pragma("unroll") for (int _i = 0; _i < 2; ++_i) \
;         __builtin_amdgcn_global_load_lds((const unsigned*)((const char*)(gbase) + (voff)[_i]), (LAS unsigned*)(lds + (bufoff) + ldsw + _i * 8192), 16, 0, 0); } while (0)
; #define PG8_LDA(dst, b, h) do { _Pragma("unroll") for (int m = 0; m < 4; ++m) _Pragma("unroll") for (int k = 0; k < 2; ++k) dst[m][k] = *(const LAS bf16x8*)(lds + PG8_SA(b, h) + aoff + m * 2048 + k * 1024); } while (0)
; #define PG8_LDB(dst, b, h) do { _Pragma("unroll") for (int n = 0; n < 2; ++n) _Pragma("unroll") for (int k = 0; k < 2; ++k) dst[n][k] = *(const LAS bf16x8*)(lds + PG8_SB(b, h) + boff + n * 2048 + k * 1024); } while (0)
; #define PG8_MMA(ai, bj, At, Bt) do { __builtin_amdgcn_s_setprio(1); _Pragma("unroll") for (int m = 0; m < 4; ++m) _Pragma("unroll") for (int n = 0; n < 2; ++n) _Pragma("unroll") for (int k = 0; k < 2; ++k) \
;         acc[ai][bj][m][n] = __builtin_amdgcn_mfma_f32_16x16x32_bf16(Bt[n][k], At[m][k], acc[ai][bj][m][n], 0, 0, 0); __builtin_amdgcn_s_setprio(0); } while (0)
; #define PG8_WAIT_V(n) asm volatile("s_waitcnt vmcnt(" #n ")" ::: "memory")
; #define PG8_WAIT_L(n) asm volatile("s_waitcnt lgkmcnt(" #n ")" ::: "memory")
; #define PG8_BAR __builtin_amdgcn_s_barrier()
; #define PG8_SCHED __builtin_amdgcn_sched_barrier(0)
; template <class Epi>
; DI void gemm_phase(LAS unsigned char* lds, const Gemm g, const StaticOrder& S, const Epi& E) {
;     ...
;             PG8_WAIT_V(8); PG8_WAIT_L(0); PG8_BAR; PG8_MMA(1, 0, At, B0); PG8_MMA(1, 1, At, B1); PG8_BAR; PG8_SCHED;
;             PG8_LDB(B0, 1, 0); PG8_LDB(B1, 1, 1); PG8_SCHED; PG8_LDA(At, 1, 0); PG8_STAGE(PG8_SA(0, 1), a2 + hstepA, voffA);
;             PG8_WAIT_V(8); PG8_WAIT_L(0); PG8_BAR; PG8_MMA(0, 0, At, B0); PG8_MMA(0, 1, At, B1); PG8_BAR; PG8_SCHED;
	v_mfma_f32_16x16x32_bf16 v[60:63], v[146:149], v[190:193], v[60:63]
	v_mfma_f32_16x16x32_bf16 v[60:63], v[150:153], v[194:197], v[60:63]
	v_mfma_f32_16x16x32_bf16 v[56:59], v[154:157], v[190:193], v[56:59]
	v_mfma_f32_16x16x32_bf16 v[56:59], v[158:161], v[194:197], v[56:59]
	v_mfma_f32_16x16x32_bf16 v[44:47], v[146:149], v[198:201], v[44:47]
	v_mfma_f32_16x16x32_bf16 v[44:47], v[150:153], v[202:205], v[44:47]
	v_mfma_f32_16x16x32_bf16 v[40:43], v[154:157], v[198:201], v[40:43]
	v_mfma_f32_16x16x32_bf16 v[40:43], v[158:161], v[202:205], v[40:43]
	v_mfma_f32_16x16x32_bf16 v[28:31], v[146:149], v[206:209], v[28:31]
	v_mfma_f32_16x16x32_bf16 v[28:31], v[150:153], v[210:213], v[28:31]
	v_mfma_f32_16x16x32_bf16 v[24:27], v[154:157], v[206:209], v[24:27]
	v_mfma_f32_16x16x32_bf16 v[24:27], v[158:161], v[210:213], v[24:27]
	v_mfma_f32_16x16x32_bf16 v[12:15], v[146:149], v[214:217], v[12:15]
	v_mfma_f32_16x16x32_bf16 v[12:15], v[150:153], v[218:221], v[12:15]
	v_mfma_f32_16x16x32_bf16 v[8:11], v[154:157], v[214:217], v[8:11]
	v_mfma_f32_16x16x32_bf16 v[8:11], v[158:161], v[218:221], v[8:11]
	s_setprio 0
	s_setprio 1
	v_mfma_f32_16x16x32_bf16 v[52:55], v[172:175], v[190:193], v[52:55]
	v_mfma_f32_16x16x32_bf16 v[52:55], v[176:179], v[194:197], v[52:55]
	v_mfma_f32_16x16x32_bf16 v[48:51], v[182:185], v[190:193], v[48:51]
	v_mfma_f32_16x16x32_bf16 v[48:51], v[186:189], v[194:197], v[48:51]
	v_mfma_f32_16x16x32_bf16 v[36:39], v[172:175], v[198:201], v[36:39]
	v_mfma_f32_16x16x32_bf16 v[36:39], v[176:179], v[202:205], v[36:39]
	v_mfma_f32_16x16x32_bf16 v[32:35], v[182:185], v[198:201], v[32:35]
	v_mfma_f32_16x16x32_bf16 v[32:35], v[186:189], v[202:205], v[32:35]
	v_mfma_f32_16x16x32_bf16 v[20:23], v[172:175], v[206:209], v[20:23]
	v_mfma_f32_16x16x32_bf16 v[20:23], v[176:179], v[210:213], v[20:23]
	v_mfma_f32_16x16x32_bf16 v[16:19], v[182:185], v[206:209], v[16:19]
	v_mfma_f32_16x16x32_bf16 v[16:19], v[186:189], v[210:213], v[16:19]
	v_mfma_f32_16x16x32_bf16 v[4:7], v[172:175], v[214:217], v[4:7]
	v_mfma_f32_16x16x32_bf16 v[4:7], v[176:179], v[218:221], v[4:7]
	v_mfma_f32_16x16x32_bf16 v[0:3], v[182:185], v[214:217], v[0:3]
	v_mfma_f32_16x16x32_bf16 v[0:3], v[186:189], v[218:221], v[0:3]
	s_setprio 0
	s_barrier
	s_add_i32 s17, 0, 0x18000
	v_add_u32_e32 v136, s17, v165
	s_add_i32 s18, 0, 0x1c000
	ds_read_b128 v[146:149], v136
	ds_read_b128 v[150:153], v136 offset:1024
	ds_read_b128 v[154:157], v136 offset:2048
	ds_read_b128 v[158:161], v136 offset:3072
	v_add_u32_e32 v136, s18, v165
	ds_read_b128 v[172:175], v136
	ds_read_b128 v[176:179], v136 offset:1024
	ds_read_b128 v[182:185], v136 offset:2048
	ds_read_b128 v[186:189], v136 offset:3072
	s_add_u32 s10, s10, 0x20000
	s_addc_u32 s11, s11, 0
	s_mov_b32 m0, s70
	v_lshl_add_u64 v[228:229], s[10:11], 0, v[134:135]
	ds_read_b128 v[190:193], v169 offset:32768
	ds_read_b128 v[194:197], v169 offset:33792
	ds_read_b128 v[198:201], v169 offset:34816
	ds_read_b128 v[202:205], v169 offset:35840
	ds_read_b128 v[206:209], v169 offset:36864
	ds_read_b128 v[210:213], v169 offset:37888
	ds_read_b128 v[214:217], v169 offset:38912
	ds_read_b128 v[218:221], v169 offset:39936
	global_load_lds_dwordx4 v[228:229], off
	v_lshl_add_u64 v[228:229], s[10:11], 0, v[130:131]
	s_mov_b32 m0, s71
	s_nop 0
	global_load_lds_dwordx4 v[228:229], off
	s_waitcnt vmcnt(8)
	s_waitcnt lgkmcnt(0)
	s_setprio 1
	s_barrier
	v_mfma_f32_16x16x32_bf16 v[124:127], v[146:149], v[190:193], v[124:127]
	v_mfma_f32_16x16x32_bf16 v[124:127], v[150:153], v[194:197], v[124:127]
	v_mfma_f32_16x16x32_bf16 v[120:123], v[154:157], v[190:193], v[120:123]
	v_mfma_f32_16x16x32_bf16 v[120:123], v[158:161], v[194:197], v[120:123]
	v_mfma_f32_16x16x32_bf16 v[108:111], v[146:149], v[198:201], v[108:111]
	v_mfma_f32_16x16x32_bf16 v[108:111], v[150:153], v[202:205], v[108:111]
	v_mfma_f32_16x16x32_bf16 v[104:107], v[154:157], v[198:201], v[104:107]
	v_mfma_f32_16x16x32_bf16 v[104:107], v[158:161], v[202:205], v[104:107]
	v_mfma_f32_16x16x32_bf16 v[92:95], v[146:149], v[206:209], v[92:95]
	v_mfma_f32_16x16x32_bf16 v[92:95], v[150:153], v[210:213], v[92:95]
	v_mfma_f32_16x16x32_bf16 v[88:91], v[154:157], v[206:209], v[88:91]
	v_mfma_f32_16x16x32_bf16 v[88:91], v[158:161], v[210:213], v[88:91]
	v_mfma_f32_16x16x32_bf16 v[76:79], v[146:149], v[214:217], v[76:79]
	v_mfma_f32_16x16x32_bf16 v[76:79], v[150:153], v[218:221], v[76:79]
	v_mfma_f32_16x16x32_bf16 v[72:75], v[154:157], v[214:217], v[72:75]
	v_mfma_f32_16x16x32_bf16 v[72:75], v[158:161], v[218:221], v[72:75]
	s_setprio 0
	s_setprio 1
	v_mfma_f32_16x16x32_bf16 v[116:119], v[172:175], v[190:193], v[116:119]
	v_mfma_f32_16x16x32_bf16 v[116:119], v[176:179], v[194:197], v[116:119]
	v_mfma_f32_16x16x32_bf16 v[112:115], v[182:185], v[190:193], v[112:115]
	v_mfma_f32_16x16x32_bf16 v[112:115], v[186:189], v[194:197], v[112:115]
	v_mfma_f32_16x16x32_bf16 v[100:103], v[172:175], v[198:201], v[100:103]
	v_mfma_f32_16x16x32_bf16 v[100:103], v[176:179], v[202:205], v[100:103]
	v_mfma_f32_16x16x32_bf16 v[96:99], v[182:185], v[198:201], v[96:99]
	v_mfma_f32_16x16x32_bf16 v[96:99], v[186:189], v[202:205], v[96:99]
	v_mfma_f32_16x16x32_bf16 v[84:87], v[172:175], v[206:209], v[84:87]
	v_mfma_f32_16x16x32_bf16 v[84:87], v[176:179], v[210:213], v[84:87]
	v_mfma_f32_16x16x32_bf16 v[80:83], v[182:185], v[206:209], v[80:83]
	v_mfma_f32_16x16x32_bf16 v[80:83], v[186:189], v[210:213], v[80:83]
	v_mfma_f32_16x16x32_bf16 v[68:71], v[172:175], v[214:217], v[68:71]
	v_mfma_f32_16x16x32_bf16 v[68:71], v[176:179], v[218:221], v[68:71]
	v_mfma_f32_16x16x32_bf16 v[64:67], v[182:185], v[214:217], v[64:67]
	v_mfma_f32_16x16x32_bf16 v[64:67], v[186:189], v[218:221], v[64:67]
	s_setprio 0
	s_barrier
; #define PG8_STAGE(bufoff, gbase, voff) do { _Pragma("unroll") for (int _i = 0; _i < 2; ++_i) \
;         __builtin_amdgcn_global_load_lds((const unsigned*)((const char*)(gbase) + (voff)[_i]), (LAS unsigned*)(lds + (bufoff) + ldsw + _i * 8192), 16, 0, 0); } while (0)
; #define PG8_LDA(dst, b, h) do { _Pragma("unroll") for (int m = 0; m < 4; ++m) _Pragma("unroll") for (int k = 0; k < 2; ++k) dst[m][k] = *(const LAS bf16x8*)(lds + PG8_SA(b, h) + aoff + m * 2048 + k * 1024); } while (0)
; #define PG8_MMA(ai, bj, At, Bt) do { __builtin_amdgcn_s_setprio(1); _Pragma("unroll") for (int m = 0; m < 4; ++m) _Pragma("unroll") for (int n = 0; n < 2; ++n) _Pragma("unroll") for (int k = 0; k < 2; ++k) \
;         acc[ai][bj][m][n] = __builtin_amdgcn_mfma_f32_16x16x32_bf16(Bt[n][k], At[m][k], acc[ai][bj][m][n], 0, 0, 0); __builtin_amdgcn_s_setprio(0); } while (0)
; #define PG8_WAIT_V(n) asm volatile("s_waitcnt vmcnt(" #n ")" ::: "memory")
; #define PG8_WAIT_L(n) asm volatile("s_waitcnt lgkmcnt(" #n ")" ::: "memory")
; #define PG8_BAR __builtin_amdgcn_s_barrier()
; #define PG8_SCHED __builtin_amdgcn_sched_barrier(0)
; template <class Epi>
; DI void gemm_phase(LAS unsigned char* lds, const Gemm g, const StaticOrder& S, const Epi& E) {
;     ...
;             PG8_LDA(At, 1, 1); PG8_STAGE(PG8_SB(1, 0), b3, voffB); PG8_STAGE(PG8_SB(1, 1), b3 + hstepB, voffB); PG8_STAGE(PG8_SA(1, 0), a3, voffA);
;             PG8_WAIT_V(8); PG8_WAIT_L(0); PG8_BAR; PG8_MMA(1, 0, At, B0); PG8_MMA(1, 1, At, B1); PG8_BAR; PG8_SCHED;
;         }
	s_add_i32 s10, s17, s66
	v_lshl_add_u64 v[162:163], v[162:163], 0, s[42:43]
	s_mov_b32 m0, s10
	ds_read_b128 v[190:193], v169 offset:49152
	ds_read_b128 v[194:197], v169 offset:50176
	ds_read_b128 v[198:201], v169 offset:51200
	ds_read_b128 v[202:205], v169 offset:52224
	ds_read_b128 v[206:209], v169 offset:53248
	ds_read_b128 v[210:213], v169 offset:54272
	ds_read_b128 v[214:217], v169 offset:55296
	ds_read_b128 v[218:221], v169 offset:56320
	global_load_lds_dwordx4 v[162:163], off
	s_add_i32 m0, s10, 0x2000
	s_add_u32 s8, s8, 0x110080
	v_lshl_add_u64 v[162:163], v[222:223], 0, s[42:43]
	s_addc_u32 s9, s9, 0
	s_add_i32 s10, s18, s66
	global_load_lds_dwordx4 v[162:163], off
	v_lshl_add_u64 v[162:163], s[8:9], 0, v[132:133]
	s_mov_b32 m0, s10
	s_nop 0
	global_load_lds_dwordx4 v[162:163], off
	v_lshl_add_u64 v[162:163], s[8:9], 0, v[128:129]
	s_add_i32 m0, s10, 0x2000
	s_nop 0
	global_load_lds_dwordx4 v[162:163], off
	v_lshl_add_u64 v[162:163], v[224:225], 0, s[42:43]
	s_mov_b32 m0, s74
	s_nop 0
	global_load_lds_dwordx4 v[162:163], off
	v_lshl_add_u64 v[162:163], v[226:227], 0, s[42:43]
	s_mov_b32 m0, s75
	s_nop 0
	global_load_lds_dwordx4 v[162:163], off
	s_waitcnt vmcnt(8)
	s_waitcnt lgkmcnt(0)
	s_setprio 1
	s_barrier
	v_mfma_f32_16x16x32_bf16 v[60:63], v[146:149], v[190:193], v[60:63]
	v_mfma_f32_16x16x32_bf16 v[60:63], v[150:153], v[194:197], v[60:63]
	v_mfma_f32_16x16x32_bf16 v[56:59], v[154:157], v[190:193], v[56:59]
	v_mfma_f32_16x16x32_bf16 v[56:59], v[158:161], v[194:197], v[56:59]
	v_mfma_f32_16x16x32_bf16 v[44:47], v[146:149], v[198:201], v[44:47]
	v_mfma_f32_16x16x32_bf16 v[44:47], v[150:153], v[202:205], v[44:47]
	v_mfma_f32_16x16x32_bf16 v[40:43], v[154:157], v[198:201], v[40:43]
	v_mfma_f32_16x16x32_bf16 v[40:43], v[158:161], v[202:205], v[40:43]
	v_mfma_f32_16x16x32_bf16 v[28:31], v[146:149], v[206:209], v[28:31]
	v_mfma_f32_16x16x32_bf16 v[28:31], v[150:153], v[210:213], v[28:31]
	v_mfma_f32_16x16x32_bf16 v[24:27], v[154:157], v[206:209], v[24:27]
	v_mfma_f32_16x16x32_bf16 v[24:27], v[158:161], v[210:213], v[24:27]
	v_mfma_f32_16x16x32_bf16 v[12:15], v[146:149], v[214:217], v[12:15]
	v_mfma_f32_16x16x32_bf16 v[12:15], v[150:153], v[218:221], v[12:15]
	v_mfma_f32_16x16x32_bf16 v[8:11], v[154:157], v[214:217], v[8:11]
	v_mfma_f32_16x16x32_bf16 v[8:11], v[158:161], v[218:221], v[8:11]
	s_setprio 0
	s_setprio 1
	v_mfma_f32_16x16x32_bf16 v[52:55], v[172:175], v[190:193], v[52:55]
	v_mfma_f32_16x16x32_bf16 v[52:55], v[176:179], v[194:197], v[52:55]
	v_mfma_f32_16x16x32_bf16 v[48:51], v[182:185], v[190:193], v[48:51]
	v_mfma_f32_16x16x32_bf16 v[48:51], v[186:189], v[194:197], v[48:51]
	v_mfma_f32_16x16x32_bf16 v[36:39], v[172:175], v[198:201], v[36:39]
	v_mfma_f32_16x16x32_bf16 v[36:39], v[176:179], v[202:205], v[36:39]
	v_mfma_f32_16x16x32_bf16 v[32:35], v[182:185], v[198:201], v[32:35]
	v_mfma_f32_16x16x32_bf16 v[32:35], v[186:189], v[202:205], v[32:35]
	v_mfma_f32_16x16x32_bf16 v[20:23], v[172:175], v[206:209], v[20:23]
	v_mfma_f32_16x16x32_bf16 v[20:23], v[176:179], v[210:213], v[20:23]
	v_mfma_f32_16x16x32_bf16 v[16:19], v[182:185], v[206:209], v[16:19]
	v_mfma_f32_16x16x32_bf16 v[16:19], v[186:189], v[210:213], v[16:19]
	v_mfma_f32_16x16x32_bf16 v[4:7], v[172:175], v[214:217], v[4:7]
	v_mfma_f32_16x16x32_bf16 v[4:7], v[176:179], v[218:221], v[4:7]
	v_mfma_f32_16x16x32_bf16 v[0:3], v[182:185], v[214:217], v[0:3]
	v_mfma_f32_16x16x32_bf16 v[0:3], v[186:189], v[218:221], v[0:3]
	s_setprio 0
	s_barrier
	s_add_u32 s6, s6, 0x100
	s_addc_u32 s7, s7, 0
	s_add_u32 s14, s14, 0x100
	s_addc_u32 s15, s15, 0
	s_cmp_ge_i32 s16, s73
	s_mov_b32 s8, s16
	s_cbranch_scc0 .LBB0_352

; #define PG8_STAGE(bufoff, gbase, voff) do { _Pragma("unroll") for (int _i = 0; _i < 2; ++_i) \
;         __builtin_amdgcn_global_load_lds((const unsigned*)((const char*)(gbase) + (voff)[_i]), (LAS unsigned*)(lds + (bufoff) + ldsw + _i * 8192), 16, 0, 0); } while (0)
; #define PG8_LDA(dst, b, h) do { _Pragma("unroll") for (int m = 0; m < 4; ++m) _Pragma("unroll") for (int k = 0; k < 2; ++k) dst[m][k] = *(const LAS bf16x8*)(lds + PG8_SA(b, h) + aoff + m * 2048 + k * 1024); } while (0)
; #define PG8_LDB(dst, b, h) do { _Pragma("unroll") for (int n = 0; n < 2; ++n) _Pragma("unroll") for (int k = 0; k < 2; ++k) dst[n][k] = *(const LAS bf16x8*)(lds + PG8_SB(b, h) + boff + n * 2048 + k * 1024); } while (0)
; #define PG8_MMA(ai, bj, At, Bt) do { __builtin_amdgcn_s_setprio(1); _Pragma("unroll") for (int m = 0; m < 4; ++m) _Pragma("unroll") for (int n = 0; n < 2; ++n) _Pragma("unroll") for (int k = 0; k < 2; ++k) \
;         acc[ai][bj][m][n] = __builtin_amdgcn_mfma_f32_16x16x32_bf16(Bt[n][k], At[m][k], acc[ai][bj][m][n], 0, 0, 0); __builtin_amdgcn_s_setprio(0); } while (0)
; #define PG8_WAIT_V(n) asm volatile("s_waitcnt vmcnt(" #n ")" ::: "memory")
; #define PG8_WAIT_L(n) asm volatile("s_waitcnt lgkmcnt(" #n ")" ::: "memory")
; #define PG8_BAR __builtin_amdgcn_s_barrier()
; #define PG8_SCHED __builtin_amdgcn_sched_barrier(0)
; template <class Epi>
; DI void gemm_phase(LAS unsigned char* lds, const Gemm g, const StaticOrder& S, const Epi& E) {
;     ...
;             PG8_LDB(B0, 0, 0); PG8_LDB(B1, 0, 1); PG8_SCHED; PG8_LDA(At, 0, 0); PG8_STAGE(PG8_SA(1, 1), a1 + hstepA, voffA);
;             PG8_WAIT_V(8); PG8_WAIT_L(0); PG8_BAR; PG8_MMA(0, 0, At, B0); PG8_MMA(0, 1, At, B1); PG8_BAR; PG8_SCHED;
;             PG8_LDA(At, 0, 1); PG8_STAGE(PG8_SB(0, 0), b2, voffB); PG8_STAGE(PG8_SB(0, 1), b2 + hstepB, voffB); PG8_STAGE(PG8_SA(0, 0), a2, voffA);
;             PG8_WAIT_V(8); PG8_WAIT_L(0); PG8_BAR; PG8_MMA(1, 0, At, B0); PG8_MMA(1, 1, At, B1); PG8_BAR; PG8_SCHED;
.LBB0_548:
	v_add_u32_e32 v1, s65, v160
	ds_read_b128 v[148:151], v1
	ds_read_b128 v[152:155], v1 offset:1024
	ds_read_b128 v[166:169], v1 offset:2048
	ds_read_b128 v[170:173], v1 offset:3072
	v_add_u32_e32 v1, s66, v160
	ds_read_b128 v[174:177], v1
	ds_read_b128 v[182:185], v1 offset:1024
	ds_read_b128 v[186:189], v1 offset:2048
	ds_read_b128 v[190:193], v1 offset:3072
	s_add_i32 s39, s46, 2
	s_add_u32 s47, s8, 0xfff00080
	s_addc_u32 s50, s9, -1
	s_cmp_eq_u32 s64, s46
	s_cselect_b32 s46, s42, s13
	s_cselect_b32 s51, s41, s50
	s_cselect_b32 s50, s40, s47
	s_cselect_b32 s47, s43, s35
	s_waitcnt lgkmcnt(0)
	v_lshl_add_u64 v[2:3], s[8:9], 0, v[140:141]
	s_add_i32 m0, s56, 0xc000
	ds_read_b128 v[194:197], v162
	ds_read_b128 v[198:201], v162 offset:1024
	ds_read_b128 v[202:205], v162 offset:2048
	ds_read_b128 v[206:209], v162 offset:3072
	ds_read_b128 v[210:213], v162 offset:4096
	ds_read_b128 v[214:217], v162 offset:5120
	ds_read_b128 v[218:221], v162 offset:6144
	ds_read_b128 v[222:225], v162 offset:7168
	global_load_lds_dwordx4 v[2:3], off
	v_lshl_add_u64 v[2:3], s[8:9], 0, v[142:143]
	s_add_i32 m0, s56, 0xe000
	s_nop 0
	global_load_lds_dwordx4 v[2:3], off
	s_waitcnt vmcnt(8)
	s_waitcnt lgkmcnt(0)
	s_setprio 1
	s_barrier
	v_mfma_f32_16x16x32_bf16 v[128:131], v[148:151], v[194:197], v[128:131]
	v_mfma_f32_16x16x32_bf16 v[128:131], v[152:155], v[198:201], v[128:131]
	v_mfma_f32_16x16x32_bf16 v[124:127], v[166:169], v[194:197], v[124:127]
	v_mfma_f32_16x16x32_bf16 v[124:127], v[170:173], v[198:201], v[124:127]
	v_mfma_f32_16x16x32_bf16 v[120:123], v[148:151], v[202:205], v[120:123]
	v_mfma_f32_16x16x32_bf16 v[120:123], v[152:155], v[206:209], v[120:123]
	v_mfma_f32_16x16x32_bf16 v[116:119], v[166:169], v[202:205], v[116:119]
	v_mfma_f32_16x16x32_bf16 v[116:119], v[170:173], v[206:209], v[116:119]
	v_mfma_f32_16x16x32_bf16 v[112:115], v[148:151], v[210:213], v[112:115]
	v_mfma_f32_16x16x32_bf16 v[112:115], v[152:155], v[214:217], v[112:115]
	v_mfma_f32_16x16x32_bf16 v[108:111], v[166:169], v[210:213], v[108:111]
	v_mfma_f32_16x16x32_bf16 v[108:111], v[170:173], v[214:217], v[108:111]
	v_mfma_f32_16x16x32_bf16 v[104:107], v[148:151], v[218:221], v[104:107]
	v_mfma_f32_16x16x32_bf16 v[104:107], v[152:155], v[222:225], v[104:107]
	v_mfma_f32_16x16x32_bf16 v[100:103], v[166:169], v[218:221], v[100:103]
	v_mfma_f32_16x16x32_bf16 v[100:103], v[170:173], v[222:225], v[100:103]
	s_setprio 0
	s_setprio 1
	v_mfma_f32_16x16x32_bf16 v[96:99], v[174:177], v[194:197], v[96:99]
	v_mfma_f32_16x16x32_bf16 v[96:99], v[182:185], v[198:201], v[96:99]
	v_mfma_f32_16x16x32_bf16 v[92:95], v[186:189], v[194:197], v[92:95]
	v_mfma_f32_16x16x32_bf16 v[92:95], v[190:193], v[198:201], v[92:95]
	v_mfma_f32_16x16x32_bf16 v[88:91], v[174:177], v[202:205], v[88:91]
	v_mfma_f32_16x16x32_bf16 v[88:91], v[182:185], v[206:209], v[88:91]
	v_mfma_f32_16x16x32_bf16 v[84:87], v[186:189], v[202:205], v[84:87]
	v_mfma_f32_16x16x32_bf16 v[84:87], v[190:193], v[206:209], v[84:87]
	v_mfma_f32_16x16x32_bf16 v[80:83], v[174:177], v[210:213], v[80:83]
	v_mfma_f32_16x16x32_bf16 v[80:83], v[182:185], v[214:217], v[80:83]
	v_mfma_f32_16x16x32_bf16 v[76:79], v[186:189], v[210:213], v[76:79]
	v_mfma_f32_16x16x32_bf16 v[76:79], v[190:193], v[214:217], v[76:79]
	v_mfma_f32_16x16x32_bf16 v[72:75], v[174:177], v[218:221], v[72:75]
	v_mfma_f32_16x16x32_bf16 v[72:75], v[182:185], v[222:225], v[72:75]
	v_mfma_f32_16x16x32_bf16 v[68:71], v[186:189], v[218:221], v[68:71]
	v_mfma_f32_16x16x32_bf16 v[68:71], v[190:193], v[222:225], v[68:71]
	s_setprio 0
	s_barrier
	s_add_i32 s71, s65, s55
	v_lshl_add_u64 v[156:157], s[46:47], 0, v[134:135]
	s_mov_b32 m0, s71
	ds_read_b128 v[194:197], v162 offset:16384
	ds_read_b128 v[198:201], v162 offset:17408
	ds_read_b128 v[202:205], v162 offset:18432
	ds_read_b128 v[206:209], v162 offset:19456
	ds_read_b128 v[210:213], v162 offset:20480
	ds_read_b128 v[214:217], v162 offset:21504
	ds_read_b128 v[218:221], v162 offset:22528
	ds_read_b128 v[222:225], v162 offset:23552
	global_load_lds_dwordx4 v[156:157], off
	s_add_i32 m0, s71, 0x2000
	s_add_u32 s72, s46, 0x100000
	v_lshl_add_u64 v[178:179], s[46:47], 0, v[138:139]
	s_addc_u32 s73, s47, 0
	s_add_i32 s71, s66, s55
	global_load_lds_dwordx4 v[178:179], off
	v_lshl_add_u64 v[2:3], s[72:73], 0, v[134:135]
	s_mov_b32 m0, s71
	v_lshl_add_u64 v[226:227], s[50:51], 0, v[132:133]
	global_load_lds_dwordx4 v[2:3], off
	v_lshl_add_u64 v[2:3], s[72:73], 0, v[138:139]
	s_add_i32 m0, s71, 0x2000
	v_lshl_add_u64 v[228:229], s[50:51], 0, v[136:137]
	global_load_lds_dwordx4 v[2:3], off
	s_mov_b32 m0, s56
	s_nop 0
	global_load_lds_dwordx4 v[226:227], off
	s_mov_b32 m0, s57
	s_nop 0
	global_load_lds_dwordx4 v[228:229], off
	s_waitcnt vmcnt(8)
	s_waitcnt lgkmcnt(0)
	s_setprio 1
	s_barrier
; #define PG8_STAGE(bufoff, gbase, voff) do { _Pragma("unroll") for (int _i = 0; _i < 2; ++_i) \
;         __builtin_amdgcn_global_load_lds((const unsigned*)((const char*)(gbase) + (voff)[_i]), (LAS unsigned*)(lds + (bufoff) + ldsw + _i * 8192), 16, 0, 0); } while (0)
; #define PG8_LDA(dst, b, h) do { _Pragma("unroll") for (int m = 0; m < 4; ++m) _Pragma("unroll") for (int k = 0; k < 2; ++k) dst[m][k] = *(const LAS bf16x8*)(lds + PG8_SA(b, h) + aoff + m * 2048 + k * 1024); } while (0)
; #define PG8_LDB(dst, b, h) do { _Pragma("unroll") for (int n = 0; n < 2; ++n) _Pragma("unroll") for (int k = 0; k < 2; ++k) dst[n][k] = *(const LAS bf16x8*)(lds + PG8_SB(b, h) + boff + n * 2048 + k * 1024); } while (0)
; #define PG8_MMA(ai, bj, At, Bt) do { __builtin_amdgcn_s_setprio(1); _Pragma("unroll") for (int m = 0; m < 4; ++m) _Pragma("unroll") for (int n = 0; n < 2; ++n) _Pragma("unroll") for (int k = 0; k < 2; ++k) \
;         acc[ai][bj][m][n] = __builtin_amdgcn_mfma_f32_16x16x32_bf16(Bt[n][k], At[m][k], acc[ai][bj][m][n], 0, 0, 0); __builtin_amdgcn_s_setprio(0); } while (0)
; #define PG8_WAIT_V(n) asm volatile("s_waitcnt vmcnt(" #n ")" ::: "memory")
; #define PG8_WAIT_L(n) asm volatile("s_waitcnt lgkmcnt(" #n ")" ::: "memory")
; #define PG8_BAR __builtin_amdgcn_s_barrier()
; #define PG8_SCHED __builtin_amdgcn_sched_barrier(0)
; template <class Epi>
; DI void gemm_phase(LAS unsigned char* lds, const Gemm g, const StaticOrder& S, const Epi& E) {
;     ...
;             PG8_WAIT_V(8); PG8_WAIT_L(0); PG8_BAR; PG8_MMA(1, 0, At, B0); PG8_MMA(1, 1, At, B1); PG8_BAR; PG8_SCHED;
;             PG8_LDB(B0, 1, 0); PG8_LDB(B1, 1, 1); PG8_SCHED; PG8_LDA(At, 1, 0); PG8_STAGE(PG8_SA(0, 1), a2 + hstepA, voffA);
;             PG8_WAIT_V(8); PG8_WAIT_L(0); PG8_BAR; PG8_MMA(0, 0, At, B0); PG8_MMA(0, 1, At, B1); PG8_BAR; PG8_SCHED;
	v_mfma_f32_16x16x32_bf16 v[64:67], v[148:151], v[194:197], v[64:67]
	v_mfma_f32_16x16x32_bf16 v[64:67], v[152:155], v[198:201], v[64:67]
	v_mfma_f32_16x16x32_bf16 v[60:63], v[166:169], v[194:197], v[60:63]
	v_mfma_f32_16x16x32_bf16 v[60:63], v[170:173], v[198:201], v[60:63]
	v_mfma_f32_16x16x32_bf16 v[56:59], v[148:151], v[202:205], v[56:59]
	v_mfma_f32_16x16x32_bf16 v[56:59], v[152:155], v[206:209], v[56:59]
	v_mfma_f32_16x16x32_bf16 v[52:55], v[166:169], v[202:205], v[52:55]
	v_mfma_f32_16x16x32_bf16 v[52:55], v[170:173], v[206:209], v[52:55]
	v_mfma_f32_16x16x32_bf16 v[48:51], v[148:151], v[210:213], v[48:51]
	v_mfma_f32_16x16x32_bf16 v[48:51], v[152:155], v[214:217], v[48:51]
	v_mfma_f32_16x16x32_bf16 v[44:47], v[166:169], v[210:213], v[44:47]
	v_mfma_f32_16x16x32_bf16 v[44:47], v[170:173], v[214:217], v[44:47]
	v_mfma_f32_16x16x32_bf16 v[40:43], v[148:151], v[218:221], v[40:43]
	v_mfma_f32_16x16x32_bf16 v[40:43], v[152:155], v[222:225], v[40:43]
	v_mfma_f32_16x16x32_bf16 v[36:39], v[166:169], v[218:221], v[36:39]
	v_mfma_f32_16x16x32_bf16 v[36:39], v[170:173], v[222:225], v[36:39]
	s_setprio 0
	s_setprio 1
	v_mfma_f32_16x16x32_bf16 v[32:35], v[174:177], v[194:197], v[32:35]
	v_mfma_f32_16x16x32_bf16 v[32:35], v[182:185], v[198:201], v[32:35]
	v_mfma_f32_16x16x32_bf16 v[28:31], v[186:189], v[194:197], v[28:31]
	v_mfma_f32_16x16x32_bf16 v[28:31], v[190:193], v[198:201], v[28:31]
	v_mfma_f32_16x16x32_bf16 v[24:27], v[174:177], v[202:205], v[24:27]
	v_mfma_f32_16x16x32_bf16 v[24:27], v[182:185], v[206:209], v[24:27]
	v_mfma_f32_16x16x32_bf16 v[20:23], v[186:189], v[202:205], v[20:23]
	v_mfma_f32_16x16x32_bf16 v[20:23], v[190:193], v[206:209], v[20:23]
	v_mfma_f32_16x16x32_bf16 v[16:19], v[174:177], v[210:213], v[16:19]
	v_mfma_f32_16x16x32_bf16 v[16:19], v[182:185], v[214:217], v[16:19]
	v_mfma_f32_16x16x32_bf16 v[12:15], v[186:189], v[210:213], v[12:15]
	v_mfma_f32_16x16x32_bf16 v[12:15], v[190:193], v[214:217], v[12:15]
	v_mfma_f32_16x16x32_bf16 v[8:11], v[174:177], v[218:221], v[8:11]
	v_mfma_f32_16x16x32_bf16 v[8:11], v[182:185], v[222:225], v[8:11]
	v_mfma_f32_16x16x32_bf16 v[2:5], v[186:189], v[218:221], v[4:7]
	v_mfma_f32_16x16x32_bf16 v[2:5], v[190:193], v[222:225], v[2:5]
	s_setprio 0
	s_barrier
	s_add_i32 s71, 0, 0x18000
	v_add_u32_e32 v1, s71, v160
	s_add_i32 s72, 0, 0x1c000
	ds_read_b128 v[148:151], v1
	ds_read_b128 v[152:155], v1 offset:1024
	ds_read_b128 v[166:169], v1 offset:2048
	ds_read_b128 v[170:173], v1 offset:3072
	v_add_u32_e32 v1, s72, v160
	ds_read_b128 v[174:177], v1
	ds_read_b128 v[182:185], v1 offset:1024
	ds_read_b128 v[186:189], v1 offset:2048
	ds_read_b128 v[190:193], v1 offset:3072
	s_add_u32 s50, s50, 0x100000
	s_addc_u32 s51, s51, 0
	s_mov_b32 m0, s58
	v_lshl_add_u64 v[6:7], s[50:51], 0, v[132:133]
	ds_read_b128 v[194:197], v162 offset:32768
	ds_read_b128 v[198:201], v162 offset:33792
	ds_read_b128 v[202:205], v162 offset:34816
	ds_read_b128 v[206:209], v162 offset:35840
	ds_read_b128 v[210:213], v162 offset:36864
	ds_read_b128 v[214:217], v162 offset:37888
	ds_read_b128 v[218:221], v162 offset:38912
	ds_read_b128 v[222:225], v162 offset:39936
	global_load_lds_dwordx4 v[6:7], off
	v_lshl_add_u64 v[6:7], s[50:51], 0, v[136:137]
	s_mov_b32 m0, s59
	s_nop 0
	global_load_lds_dwordx4 v[6:7], off
	s_waitcnt vmcnt(8)
	s_waitcnt lgkmcnt(0)
	s_setprio 1
	s_barrier
	v_mfma_f32_16x16x32_bf16 v[128:131], v[148:151], v[194:197], v[128:131]
	v_mfma_f32_16x16x32_bf16 v[128:131], v[152:155], v[198:201], v[128:131]
	v_mfma_f32_16x16x32_bf16 v[124:127], v[166:169], v[194:197], v[124:127]
	v_mfma_f32_16x16x32_bf16 v[124:127], v[170:173], v[198:201], v[124:127]
	v_mfma_f32_16x16x32_bf16 v[120:123], v[148:151], v[202:205], v[120:123]
	v_mfma_f32_16x16x32_bf16 v[120:123], v[152:155], v[206:209], v[120:123]
	v_mfma_f32_16x16x32_bf16 v[116:119], v[166:169], v[202:205], v[116:119]
	v_mfma_f32_16x16x32_bf16 v[116:119], v[170:173], v[206:209], v[116:119]
	v_mfma_f32_16x16x32_bf16 v[112:115], v[148:151], v[210:213], v[112:115]
	v_mfma_f32_16x16x32_bf16 v[112:115], v[152:155], v[214:217], v[112:115]
	v_mfma_f32_16x16x32_bf16 v[108:111], v[166:169], v[210:213], v[108:111]
	v_mfma_f32_16x16x32_bf16 v[108:111], v[170:173], v[214:217], v[108:111]
	v_mfma_f32_16x16x32_bf16 v[104:107], v[148:151], v[218:221], v[104:107]
	v_mfma_f32_16x16x32_bf16 v[104:107], v[152:155], v[222:225], v[104:107]
	v_mfma_f32_16x16x32_bf16 v[100:103], v[166:169], v[218:221], v[100:103]
	v_mfma_f32_16x16x32_bf16 v[100:103], v[170:173], v[222:225], v[100:103]
	s_setprio 0
	s_setprio 1
	v_mfma_f32_16x16x32_bf16 v[96:99], v[174:177], v[194:197], v[96:99]
	v_mfma_f32_16x16x32_bf16 v[96:99], v[182:185], v[198:201], v[96:99]
	v_mfma_f32_16x16x32_bf16 v[92:95], v[186:189], v[194:197], v[92:95]
	v_mfma_f32_16x16x32_bf16 v[92:95], v[190:193], v[198:201], v[92:95]
	v_mfma_f32_16x16x32_bf16 v[88:91], v[174:177], v[202:205], v[88:91]
	v_mfma_f32_16x16x32_bf16 v[88:91], v[182:185], v[206:209], v[88:91]
	v_mfma_f32_16x16x32_bf16 v[84:87], v[186:189], v[202:205], v[84:87]
	v_mfma_f32_16x16x32_bf16 v[84:87], v[190:193], v[206:209], v[84:87]
	v_mfma_f32_16x16x32_bf16 v[80:83], v[174:177], v[210:213], v[80:83]
	v_mfma_f32_16x16x32_bf16 v[80:83], v[182:185], v[214:217], v[80:83]
	v_mfma_f32_16x16x32_bf16 v[76:79], v[186:189], v[210:213], v[76:79]
	v_mfma_f32_16x16x32_bf16 v[76:79], v[190:193], v[214:217], v[76:79]
	v_mfma_f32_16x16x32_bf16 v[72:75], v[174:177], v[218:221], v[72:75]
	v_mfma_f32_16x16x32_bf16 v[72:75], v[182:185], v[222:225], v[72:75]
	v_mfma_f32_16x16x32_bf16 v[68:71], v[186:189], v[218:221], v[68:71]
	v_mfma_f32_16x16x32_bf16 v[68:71], v[190:193], v[222:225], v[68:71]
	s_setprio 0
	s_barrier
; #define PG8_STAGE(bufoff, gbase, voff) do { _Pragma("unroll") for (int _i = 0; _i < 2; ++_i) \
;         __builtin_amdgcn_global_load_lds((const unsigned*)((const char*)(gbase) + (voff)[_i]), (LAS unsigned*)(lds + (bufoff) + ldsw + _i * 8192), 16, 0, 0); } while (0)
; #define PG8_LDA(dst, b, h) do { _Pragma("unroll") for (int m = 0; m < 4; ++m) _Pragma("unroll") for (int k = 0; k < 2; ++k) dst[m][k] = *(const LAS bf16x8*)(lds + PG8_SA(b, h) + aoff + m * 2048 + k * 1024); } while (0)
; #define PG8_MMA(ai, bj, At, Bt) do { __builtin_amdgcn_s_setprio(1); _Pragma("unroll") for (int m = 0; m < 4; ++m) _Pragma("unroll") for (int n = 0; n < 2; ++n) _Pragma("unroll") for (int k = 0; k < 2; ++k) \
;         acc[ai][bj][m][n] = __builtin_amdgcn_mfma_f32_16x16x32_bf16(Bt[n][k], At[m][k], acc[ai][bj][m][n], 0, 0, 0); __builtin_amdgcn_s_setprio(0); } while (0)
; #define PG8_WAIT_V(n) asm volatile("s_waitcnt vmcnt(" #n ")" ::: "memory")
; #define PG8_WAIT_L(n) asm volatile("s_waitcnt lgkmcnt(" #n ")" ::: "memory")
; #define PG8_BAR __builtin_amdgcn_s_barrier()
; #define PG8_SCHED __builtin_amdgcn_sched_barrier(0)
; template <class Epi>
; DI void gemm_phase(LAS unsigned char* lds, const Gemm g, const StaticOrder& S, const Epi& E) {
;     ...
;             PG8_LDA(At, 1, 1); PG8_STAGE(PG8_SB(1, 0), b3, voffB); PG8_STAGE(PG8_SB(1, 1), b3 + hstepB, voffB); PG8_STAGE(PG8_SA(1, 0), a3, voffA);
;             PG8_WAIT_V(8); PG8_WAIT_L(0); PG8_BAR; PG8_MMA(1, 0, At, B0); PG8_MMA(1, 1, At, B1); PG8_BAR; PG8_SCHED;
;         }
	s_add_i32 s50, s71, s55
	v_lshl_add_u64 v[6:7], v[156:157], 0, s[26:27]
	s_mov_b32 m0, s50
	ds_read_b128 v[194:197], v162 offset:49152
	ds_read_b128 v[198:201], v162 offset:50176
	ds_read_b128 v[202:205], v162 offset:51200
	ds_read_b128 v[206:209], v162 offset:52224
	ds_read_b128 v[210:213], v162 offset:53248
	ds_read_b128 v[214:217], v162 offset:54272
	ds_read_b128 v[218:221], v162 offset:55296
	ds_read_b128 v[222:225], v162 offset:56320
	global_load_lds_dwordx4 v[6:7], off
	s_add_i32 m0, s50, 0x2000
	s_add_u32 s46, s46, 0x100080
	v_lshl_add_u64 v[6:7], v[178:179], 0, s[26:27]
	s_addc_u32 s47, s47, 0
	s_add_i32 s50, s72, s55
	global_load_lds_dwordx4 v[6:7], off
	v_lshl_add_u64 v[6:7], s[46:47], 0, v[134:135]
	s_mov_b32 m0, s50
	s_nop 0
	global_load_lds_dwordx4 v[6:7], off
	v_lshl_add_u64 v[6:7], s[46:47], 0, v[138:139]
	s_add_i32 m0, s50, 0x2000
	s_nop 0
	global_load_lds_dwordx4 v[6:7], off
	v_lshl_add_u64 v[6:7], v[226:227], 0, s[26:27]
	s_mov_b32 m0, s62
	s_nop 0
	global_load_lds_dwordx4 v[6:7], off
	v_lshl_add_u64 v[6:7], v[228:229], 0, s[26:27]
	s_mov_b32 m0, s63
	s_nop 0
	global_load_lds_dwordx4 v[6:7], off
	s_waitcnt vmcnt(8)
	s_waitcnt lgkmcnt(0)
	s_setprio 1
	s_barrier
	v_mfma_f32_16x16x32_bf16 v[64:67], v[148:151], v[194:197], v[64:67]
	v_mfma_f32_16x16x32_bf16 v[64:67], v[152:155], v[198:201], v[64:67]
	v_mfma_f32_16x16x32_bf16 v[60:63], v[166:169], v[194:197], v[60:63]
	v_mfma_f32_16x16x32_bf16 v[60:63], v[170:173], v[198:201], v[60:63]
	v_mfma_f32_16x16x32_bf16 v[56:59], v[148:151], v[202:205], v[56:59]
	v_mfma_f32_16x16x32_bf16 v[56:59], v[152:155], v[206:209], v[56:59]
	v_mfma_f32_16x16x32_bf16 v[52:55], v[166:169], v[202:205], v[52:55]
	v_mfma_f32_16x16x32_bf16 v[52:55], v[170:173], v[206:209], v[52:55]
	v_mfma_f32_16x16x32_bf16 v[48:51], v[148:151], v[210:213], v[48:51]
	v_mfma_f32_16x16x32_bf16 v[48:51], v[152:155], v[214:217], v[48:51]
	v_mfma_f32_16x16x32_bf16 v[44:47], v[166:169], v[210:213], v[44:47]
	v_mfma_f32_16x16x32_bf16 v[44:47], v[170:173], v[214:217], v[44:47]
	v_mfma_f32_16x16x32_bf16 v[40:43], v[148:151], v[218:221], v[40:43]
	v_mfma_f32_16x16x32_bf16 v[40:43], v[152:155], v[222:225], v[40:43]
	v_mfma_f32_16x16x32_bf16 v[36:39], v[166:169], v[218:221], v[36:39]
	v_mfma_f32_16x16x32_bf16 v[36:39], v[170:173], v[222:225], v[36:39]
	s_setprio 0
	s_setprio 1
	v_mfma_f32_16x16x32_bf16 v[32:35], v[174:177], v[194:197], v[32:35]
	v_mfma_f32_16x16x32_bf16 v[32:35], v[182:185], v[198:201], v[32:35]
	v_mfma_f32_16x16x32_bf16 v[28:31], v[186:189], v[194:197], v[28:31]
	v_mfma_f32_16x16x32_bf16 v[28:31], v[190:193], v[198:201], v[28:31]
	v_mfma_f32_16x16x32_bf16 v[24:27], v[174:177], v[202:205], v[24:27]
	v_mfma_f32_16x16x32_bf16 v[24:27], v[182:185], v[206:209], v[24:27]
	v_mfma_f32_16x16x32_bf16 v[20:23], v[186:189], v[202:205], v[20:23]
	v_mfma_f32_16x16x32_bf16 v[20:23], v[190:193], v[206:209], v[20:23]
	v_mfma_f32_16x16x32_bf16 v[16:19], v[174:177], v[210:213], v[16:19]
	v_mfma_f32_16x16x32_bf16 v[16:19], v[182:185], v[214:217], v[16:19]
	v_mfma_f32_16x16x32_bf16 v[12:15], v[186:189], v[210:213], v[12:15]
	v_mfma_f32_16x16x32_bf16 v[12:15], v[190:193], v[214:217], v[12:15]
	v_mfma_f32_16x16x32_bf16 v[6:9], v[174:177], v[218:221], v[8:11]
	v_mfma_f32_16x16x32_bf16 v[2:5], v[186:189], v[218:221], v[2:5]
	v_mfma_f32_16x16x32_bf16 v[8:11], v[182:185], v[222:225], v[6:9]
	v_mfma_f32_16x16x32_bf16 v[4:7], v[190:193], v[222:225], v[2:5]
	s_setprio 0
	s_barrier
	s_add_u32 s8, s8, 0x100
	s_addc_u32 s9, s9, 0
	s_add_u32 s13, s13, 0x100
	s_addc_u32 s35, s35, 0
	s_cmp_ge_i32 s39, s61
	s_mov_b32 s46, s39
	s_cbranch_scc0 .LBB0_548

; #define PG8_STAGE(bufoff, gbase, voff) do { _Pragma("unroll") for (int _i = 0; _i < 2; ++_i) \
;         __builtin_amdgcn_global_load_lds((const unsigned*)((const char*)(gbase) + (voff)[_i]), (LAS unsigned*)(lds + (bufoff) + ldsw + _i * 8192), 16, 0, 0); } while (0)
; #define PG8_LDA(dst, b, h) do { _Pragma("unroll") for (int m = 0; m < 4; ++m) _Pragma("unroll") for (int k = 0; k < 2; ++k) dst[m][k] = *(const LAS bf16x8*)(lds + PG8_SA(b, h) + aoff + m * 2048 + k * 1024); } while (0)
; #define PG8_LDB(dst, b, h) do { _Pragma("unroll") for (int n = 0; n < 2; ++n) _Pragma("unroll") for (int k = 0; k < 2; ++k) dst[n][k] = *(const LAS bf16x8*)(lds + PG8_SB(b, h) + boff + n * 2048 + k * 1024); } while (0)
; #define PG8_MMA(ai, bj, At, Bt) do { __builtin_amdgcn_s_setprio(1); _Pragma("unroll") for (int m = 0; m < 4; ++m) _Pragma("unroll") for (int n = 0; n < 2; ++n) _Pragma("unroll") for (int k = 0; k < 2; ++k) \
;         acc[ai][bj][m][n] = __builtin_amdgcn_mfma_f32_16x16x32_bf16(Bt[n][k], At[m][k], acc[ai][bj][m][n], 0, 0, 0); __builtin_amdgcn_s_setprio(0); } while (0)
; #define PG8_WAIT_V(n) asm volatile("s_waitcnt vmcnt(" #n ")" ::: "memory")
; #define PG8_WAIT_L(n) asm volatile("s_waitcnt lgkmcnt(" #n ")" ::: "memory")
; #define PG8_BAR __builtin_amdgcn_s_barrier()
; #define PG8_SCHED __builtin_amdgcn_sched_barrier(0)
; template <class Epi>
; DI void gemm_phase(LAS unsigned char* lds, const Gemm g, const StaticOrder& S, const Epi& E) {
;     ...
;             PG8_LDB(B0, 0, 0); PG8_LDB(B1, 0, 1); PG8_SCHED; PG8_LDA(At, 0, 0); PG8_STAGE(PG8_SA(1, 1), a1 + hstepA, voffA);
;             PG8_WAIT_V(8); PG8_WAIT_L(0); PG8_BAR; PG8_MMA(0, 0, At, B0); PG8_MMA(0, 1, At, B1); PG8_BAR; PG8_SCHED;
;             PG8_LDA(At, 0, 1); PG8_STAGE(PG8_SB(0, 0), b2, voffB); PG8_STAGE(PG8_SB(0, 1), b2 + hstepB, voffB); PG8_STAGE(PG8_SA(0, 0), a2, voffA);
;             PG8_WAIT_V(8); PG8_WAIT_L(0); PG8_BAR; PG8_MMA(1, 0, At, B0); PG8_MMA(1, 1, At, B1); PG8_BAR; PG8_SCHED;
.LBB0_705:
	ds_read_b128 v[150:153], v147
	ds_read_b128 v[154:157], v147 offset:1024
	ds_read_b128 v[158:161], v147 offset:2048
	ds_read_b128 v[162:165], v147 offset:3072
	ds_read_b128 v[166:169], v148
	ds_read_b128 v[170:173], v148 offset:1024
	ds_read_b128 v[174:177], v148 offset:2048
	ds_read_b128 v[182:185], v148 offset:3072
	s_add_i32 s63, s28, 2
	s_add_u32 s29, s26, 0xfff00080
	s_addc_u32 s30, s27, -1
	s_cmp_eq_u32 s54, s28
	s_cselect_b32 s28, s60, s61
	s_cselect_b32 s31, s17, s30
	s_cselect_b32 s30, s19, s29
	s_cselect_b32 s29, s59, s62
	v_lshl_add_u64 v[178:179], s[26:27], 0, v[136:137]
	s_add_i32 m0, s25, 0xc000
	ds_read_b128 v[186:189], v149
	ds_read_b128 v[190:193], v149 offset:1024
	ds_read_b128 v[194:197], v149 offset:2048
	ds_read_b128 v[198:201], v149 offset:3072
	ds_read_b128 v[202:205], v149 offset:4096
	ds_read_b128 v[206:209], v149 offset:5120
	ds_read_b128 v[210:213], v149 offset:6144
	ds_read_b128 v[214:217], v149 offset:7168
	global_load_lds_dwordx4 v[178:179], off
	v_lshl_add_u64 v[178:179], s[26:27], 0, v[138:139]
	s_add_i32 m0, s25, 0xe000
	s_nop 0
	global_load_lds_dwordx4 v[178:179], off
	s_waitcnt vmcnt(8)
	s_waitcnt lgkmcnt(0)
	s_setprio 1
	s_barrier
	v_mfma_f32_16x16x32_bf16 v[124:127], v[150:153], v[186:189], v[124:127]
	v_mfma_f32_16x16x32_bf16 v[124:127], v[154:157], v[190:193], v[124:127]
	v_mfma_f32_16x16x32_bf16 v[116:119], v[158:161], v[186:189], v[116:119]
	v_mfma_f32_16x16x32_bf16 v[116:119], v[162:165], v[190:193], v[116:119]
	v_mfma_f32_16x16x32_bf16 v[108:111], v[150:153], v[194:197], v[108:111]
	v_mfma_f32_16x16x32_bf16 v[108:111], v[154:157], v[198:201], v[108:111]
	v_mfma_f32_16x16x32_bf16 v[100:103], v[158:161], v[194:197], v[100:103]
	v_mfma_f32_16x16x32_bf16 v[100:103], v[162:165], v[198:201], v[100:103]
	v_mfma_f32_16x16x32_bf16 v[92:95], v[150:153], v[202:205], v[92:95]
	v_mfma_f32_16x16x32_bf16 v[92:95], v[154:157], v[206:209], v[92:95]
	v_mfma_f32_16x16x32_bf16 v[84:87], v[158:161], v[202:205], v[84:87]
	v_mfma_f32_16x16x32_bf16 v[84:87], v[162:165], v[206:209], v[84:87]
	v_mfma_f32_16x16x32_bf16 v[76:79], v[150:153], v[210:213], v[76:79]
	v_mfma_f32_16x16x32_bf16 v[76:79], v[154:157], v[214:217], v[76:79]
	v_mfma_f32_16x16x32_bf16 v[68:71], v[158:161], v[210:213], v[68:71]
	v_mfma_f32_16x16x32_bf16 v[68:71], v[162:165], v[214:217], v[68:71]
	s_setprio 0
	s_setprio 1
	v_mfma_f32_16x16x32_bf16 v[120:123], v[166:169], v[186:189], v[120:123]
	v_mfma_f32_16x16x32_bf16 v[120:123], v[170:173], v[190:193], v[120:123]
	v_mfma_f32_16x16x32_bf16 v[112:115], v[174:177], v[186:189], v[112:115]
	v_mfma_f32_16x16x32_bf16 v[112:115], v[182:185], v[190:193], v[112:115]
	v_mfma_f32_16x16x32_bf16 v[104:107], v[166:169], v[194:197], v[104:107]
	v_mfma_f32_16x16x32_bf16 v[104:107], v[170:173], v[198:201], v[104:107]
	v_mfma_f32_16x16x32_bf16 v[96:99], v[174:177], v[194:197], v[96:99]
	v_mfma_f32_16x16x32_bf16 v[96:99], v[182:185], v[198:201], v[96:99]
	v_mfma_f32_16x16x32_bf16 v[88:91], v[166:169], v[202:205], v[88:91]
	v_mfma_f32_16x16x32_bf16 v[88:91], v[170:173], v[206:209], v[88:91]
	v_mfma_f32_16x16x32_bf16 v[80:83], v[174:177], v[202:205], v[80:83]
	v_mfma_f32_16x16x32_bf16 v[80:83], v[182:185], v[206:209], v[80:83]
	v_mfma_f32_16x16x32_bf16 v[72:75], v[166:169], v[210:213], v[72:75]
	v_mfma_f32_16x16x32_bf16 v[72:75], v[170:173], v[214:217], v[72:75]
	v_mfma_f32_16x16x32_bf16 v[64:67], v[174:177], v[210:213], v[64:67]
	v_mfma_f32_16x16x32_bf16 v[64:67], v[182:185], v[214:217], v[64:67]
	s_setprio 0
	s_barrier
	s_add_i32 s64, s55, s39
	v_lshl_add_u64 v[178:179], s[28:29], 0, v[132:133]
	s_mov_b32 m0, s64
	ds_read_b128 v[186:189], v149 offset:16384
	ds_read_b128 v[190:193], v149 offset:17408
	ds_read_b128 v[194:197], v149 offset:18432
	ds_read_b128 v[198:201], v149 offset:19456
	ds_read_b128 v[202:205], v149 offset:20480
	ds_read_b128 v[206:209], v149 offset:21504
	ds_read_b128 v[210:213], v149 offset:22528
	ds_read_b128 v[214:217], v149 offset:23552
	global_load_lds_dwordx4 v[178:179], off
	s_add_i32 m0, s64, 0x2000
	s_add_u32 s64, s28, 0x100000
	v_lshl_add_u64 v[218:219], s[28:29], 0, v[128:129]
	s_addc_u32 s65, s29, 0
	s_add_i32 s66, s56, s39
	global_load_lds_dwordx4 v[218:219], off
	v_lshl_add_u64 v[220:221], s[64:65], 0, v[132:133]
	s_mov_b32 m0, s66
	v_lshl_add_u64 v[222:223], s[30:31], 0, v[130:131]
	global_load_lds_dwordx4 v[220:221], off
	v_lshl_add_u64 v[220:221], s[64:65], 0, v[128:129]
	s_add_i32 m0, s66, 0x2000
	s_nop 0
	global_load_lds_dwordx4 v[220:221], off
	v_lshl_add_u64 v[220:221], s[30:31], 0, v[134:135]
	s_mov_b32 m0, s25
	s_nop 0
	global_load_lds_dwordx4 v[220:221], off
	s_mov_b32 m0, s42
	s_nop 0
	global_load_lds_dwordx4 v[222:223], off
	s_waitcnt vmcnt(8)
	s_waitcnt lgkmcnt(0)
	s_setprio 1
	s_barrier
; #define PG8_STAGE(bufoff, gbase, voff) do { _Pragma("unroll") for (int _i = 0; _i < 2; ++_i) \
;         __builtin_amdgcn_global_load_lds((const unsigned*)((const char*)(gbase) + (voff)[_i]), (LAS unsigned*)(lds + (bufoff) + ldsw + _i * 8192), 16, 0, 0); } while (0)
; #define PG8_LDA(dst, b, h) do { _Pragma("unroll") for (int m = 0; m < 4; ++m) _Pragma("unroll") for (int k = 0; k < 2; ++k) dst[m][k] = *(const LAS bf16x8*)(lds + PG8_SA(b, h) + aoff + m * 2048 + k * 1024); } while (0)
; #define PG8_LDB(dst, b, h) do { _Pragma("unroll") for (int n = 0; n < 2; ++n) _Pragma("unroll") for (int k = 0; k < 2; ++k) dst[n][k] = *(const LAS bf16x8*)(lds + PG8_SB(b, h) + boff + n * 2048 + k * 1024); } while (0)
; #define PG8_MMA(ai, bj, At, Bt) do { __builtin_amdgcn_s_setprio(1); _Pragma("unroll") for (int m = 0; m < 4; ++m) _Pragma("unroll") for (int n = 0; n < 2; ++n) _Pragma("unroll") for (int k = 0; k < 2; ++k) \
;         acc[ai][bj][m][n] = __builtin_amdgcn_mfma_f32_16x16x32_bf16(Bt[n][k], At[m][k], acc[ai][bj][m][n], 0, 0, 0); __builtin_amdgcn_s_setprio(0); } while (0)
; #define PG8_WAIT_V(n) asm volatile("s_waitcnt vmcnt(" #n ")" ::: "memory")
; #define PG8_WAIT_L(n) asm volatile("s_waitcnt lgkmcnt(" #n ")" ::: "memory")
; #define PG8_BAR __builtin_amdgcn_s_barrier()
; #define PG8_SCHED __builtin_amdgcn_sched_barrier(0)
; template <class Epi>
; DI void gemm_phase(LAS unsigned char* lds, const Gemm g, const StaticOrder& S, const Epi& E) {
;     ...
;             PG8_WAIT_V(8); PG8_WAIT_L(0); PG8_BAR; PG8_MMA(1, 0, At, B0); PG8_MMA(1, 1, At, B1); PG8_BAR; PG8_SCHED;
;             PG8_LDB(B0, 1, 0); PG8_LDB(B1, 1, 1); PG8_SCHED; PG8_LDA(At, 1, 0); PG8_STAGE(PG8_SA(0, 1), a2 + hstepA, voffA);
;             PG8_WAIT_V(8); PG8_WAIT_L(0); PG8_BAR; PG8_MMA(0, 0, At, B0); PG8_MMA(0, 1, At, B1); PG8_BAR; PG8_SCHED;
	v_mfma_f32_16x16x32_bf16 v[60:63], v[150:153], v[186:189], v[60:63]
	v_mfma_f32_16x16x32_bf16 v[60:63], v[154:157], v[190:193], v[60:63]
	v_mfma_f32_16x16x32_bf16 v[52:55], v[158:161], v[186:189], v[52:55]
	v_mfma_f32_16x16x32_bf16 v[52:55], v[162:165], v[190:193], v[52:55]
	v_mfma_f32_16x16x32_bf16 v[44:47], v[150:153], v[194:197], v[44:47]
	v_mfma_f32_16x16x32_bf16 v[44:47], v[154:157], v[198:201], v[44:47]
	v_mfma_f32_16x16x32_bf16 v[36:39], v[158:161], v[194:197], v[36:39]
	v_mfma_f32_16x16x32_bf16 v[36:39], v[162:165], v[198:201], v[36:39]
	v_mfma_f32_16x16x32_bf16 v[28:31], v[150:153], v[202:205], v[28:31]
	v_mfma_f32_16x16x32_bf16 v[28:31], v[154:157], v[206:209], v[28:31]
	v_mfma_f32_16x16x32_bf16 v[20:23], v[158:161], v[202:205], v[20:23]
	v_mfma_f32_16x16x32_bf16 v[20:23], v[162:165], v[206:209], v[20:23]
	v_mfma_f32_16x16x32_bf16 v[12:15], v[150:153], v[210:213], v[12:15]
	v_mfma_f32_16x16x32_bf16 v[12:15], v[154:157], v[214:217], v[12:15]
	v_mfma_f32_16x16x32_bf16 v[4:7], v[158:161], v[210:213], v[4:7]
	v_mfma_f32_16x16x32_bf16 v[4:7], v[162:165], v[214:217], v[4:7]
	s_setprio 0
	s_setprio 1
	v_mfma_f32_16x16x32_bf16 v[56:59], v[166:169], v[186:189], v[56:59]
	v_mfma_f32_16x16x32_bf16 v[56:59], v[170:173], v[190:193], v[56:59]
	v_mfma_f32_16x16x32_bf16 v[48:51], v[174:177], v[186:189], v[48:51]
	v_mfma_f32_16x16x32_bf16 v[48:51], v[182:185], v[190:193], v[48:51]
	v_mfma_f32_16x16x32_bf16 v[40:43], v[166:169], v[194:197], v[40:43]
	v_mfma_f32_16x16x32_bf16 v[40:43], v[170:173], v[198:201], v[40:43]
	v_mfma_f32_16x16x32_bf16 v[32:35], v[174:177], v[194:197], v[32:35]
	v_mfma_f32_16x16x32_bf16 v[32:35], v[182:185], v[198:201], v[32:35]
	v_mfma_f32_16x16x32_bf16 v[24:27], v[166:169], v[202:205], v[24:27]
	v_mfma_f32_16x16x32_bf16 v[24:27], v[170:173], v[206:209], v[24:27]
	v_mfma_f32_16x16x32_bf16 v[16:19], v[174:177], v[202:205], v[16:19]
	v_mfma_f32_16x16x32_bf16 v[16:19], v[182:185], v[206:209], v[16:19]
	v_mfma_f32_16x16x32_bf16 v[8:11], v[166:169], v[210:213], v[8:11]
	v_mfma_f32_16x16x32_bf16 v[8:11], v[170:173], v[214:217], v[8:11]
	v_mfma_f32_16x16x32_bf16 v[0:3], v[174:177], v[210:213], v[0:3]
	v_mfma_f32_16x16x32_bf16 v[0:3], v[182:185], v[214:217], v[0:3]
	s_setprio 0
	s_barrier
	s_add_i32 s64, 0, 0x18000
	s_add_i32 s65, 0, 0x1c000
	v_add_u32_e32 v162, s64, v145
	v_add_u32_e32 v181, s65, v145
	ds_read_b128 v[150:153], v162
	ds_read_b128 v[154:157], v162 offset:1024
	ds_read_b128 v[158:161], v162 offset:2048
	ds_read_b128 v[162:165], v162 offset:3072
	ds_read_b128 v[166:169], v181
	ds_read_b128 v[170:173], v181 offset:1024
	ds_read_b128 v[174:177], v181 offset:2048
	ds_read_b128 v[182:185], v181 offset:3072
	s_add_u32 s30, s30, 0x100000
	s_addc_u32 s31, s31, 0
	s_mov_b32 m0, s43
	v_lshl_add_u64 v[224:225], s[30:31], 0, v[134:135]
	ds_read_b128 v[186:189], v149 offset:32768
	ds_read_b128 v[190:193], v149 offset:33792
	ds_read_b128 v[194:197], v149 offset:34816
	ds_read_b128 v[198:201], v149 offset:35840
	ds_read_b128 v[202:205], v149 offset:36864
	ds_read_b128 v[206:209], v149 offset:37888
	ds_read_b128 v[210:213], v149 offset:38912
	ds_read_b128 v[214:217], v149 offset:39936
	global_load_lds_dwordx4 v[224:225], off
	v_lshl_add_u64 v[224:225], s[30:31], 0, v[130:131]
	s_mov_b32 m0, s46
	s_nop 0
	global_load_lds_dwordx4 v[224:225], off
	s_waitcnt vmcnt(8)
	s_waitcnt lgkmcnt(0)
	s_setprio 1
	s_barrier
	v_mfma_f32_16x16x32_bf16 v[124:127], v[150:153], v[186:189], v[124:127]
	v_mfma_f32_16x16x32_bf16 v[124:127], v[154:157], v[190:193], v[124:127]
	v_mfma_f32_16x16x32_bf16 v[116:119], v[158:161], v[186:189], v[116:119]
	v_mfma_f32_16x16x32_bf16 v[116:119], v[162:165], v[190:193], v[116:119]
	v_mfma_f32_16x16x32_bf16 v[108:111], v[150:153], v[194:197], v[108:111]
	v_mfma_f32_16x16x32_bf16 v[108:111], v[154:157], v[198:201], v[108:111]
	v_mfma_f32_16x16x32_bf16 v[100:103], v[158:161], v[194:197], v[100:103]
	v_mfma_f32_16x16x32_bf16 v[100:103], v[162:165], v[198:201], v[100:103]
	v_mfma_f32_16x16x32_bf16 v[92:95], v[150:153], v[202:205], v[92:95]
	v_mfma_f32_16x16x32_bf16 v[92:95], v[154:157], v[206:209], v[92:95]
	v_mfma_f32_16x16x32_bf16 v[84:87], v[158:161], v[202:205], v[84:87]
	v_mfma_f32_16x16x32_bf16 v[84:87], v[162:165], v[206:209], v[84:87]
	v_mfma_f32_16x16x32_bf16 v[76:79], v[150:153], v[210:213], v[76:79]
	v_mfma_f32_16x16x32_bf16 v[76:79], v[154:157], v[214:217], v[76:79]
	v_mfma_f32_16x16x32_bf16 v[68:71], v[158:161], v[210:213], v[68:71]
	v_mfma_f32_16x16x32_bf16 v[68:71], v[162:165], v[214:217], v[68:71]
	s_setprio 0
	s_setprio 1
	v_mfma_f32_16x16x32_bf16 v[120:123], v[166:169], v[186:189], v[120:123]
	v_mfma_f32_16x16x32_bf16 v[120:123], v[170:173], v[190:193], v[120:123]
	v_mfma_f32_16x16x32_bf16 v[112:115], v[174:177], v[186:189], v[112:115]
	v_mfma_f32_16x16x32_bf16 v[112:115], v[182:185], v[190:193], v[112:115]
	v_mfma_f32_16x16x32_bf16 v[104:107], v[166:169], v[194:197], v[104:107]
	v_mfma_f32_16x16x32_bf16 v[104:107], v[170:173], v[198:201], v[104:107]
	v_mfma_f32_16x16x32_bf16 v[96:99], v[174:177], v[194:197], v[96:99]
	v_mfma_f32_16x16x32_bf16 v[96:99], v[182:185], v[198:201], v[96:99]
	v_mfma_f32_16x16x32_bf16 v[88:91], v[166:169], v[202:205], v[88:91]
	v_mfma_f32_16x16x32_bf16 v[88:91], v[170:173], v[206:209], v[88:91]
	v_mfma_f32_16x16x32_bf16 v[80:83], v[174:177], v[202:205], v[80:83]
	v_mfma_f32_16x16x32_bf16 v[80:83], v[182:185], v[206:209], v[80:83]
	v_mfma_f32_16x16x32_bf16 v[72:75], v[166:169], v[210:213], v[72:75]
	v_mfma_f32_16x16x32_bf16 v[72:75], v[170:173], v[214:217], v[72:75]
	v_mfma_f32_16x16x32_bf16 v[64:67], v[174:177], v[210:213], v[64:67]
	v_mfma_f32_16x16x32_bf16 v[64:67], v[182:185], v[214:217], v[64:67]
	s_setprio 0
	s_barrier
; #define PG8_STAGE(bufoff, gbase, voff) do { _Pragma("unroll") for (int _i = 0; _i < 2; ++_i) \
;         __builtin_amdgcn_global_load_lds((const unsigned*)((const char*)(gbase) + (voff)[_i]), (LAS unsigned*)(lds + (bufoff) + ldsw + _i * 8192), 16, 0, 0); } while (0)
; #define PG8_LDA(dst, b, h) do { _Pragma("unroll") for (int m = 0; m < 4; ++m) _Pragma("unroll") for (int k = 0; k < 2; ++k) dst[m][k] = *(const LAS bf16x8*)(lds + PG8_SA(b, h) + aoff + m * 2048 + k * 1024); } while (0)
; #define PG8_MMA(ai, bj, At, Bt) do { __builtin_amdgcn_s_setprio(1); _Pragma("unroll") for (int m = 0; m < 4; ++m) _Pragma("unroll") for (int n = 0; n < 2; ++n) _Pragma("unroll") for (int k = 0; k < 2; ++k) \
;         acc[ai][bj][m][n] = __builtin_amdgcn_mfma_f32_16x16x32_bf16(Bt[n][k], At[m][k], acc[ai][bj][m][n], 0, 0, 0); __builtin_amdgcn_s_setprio(0); } while (0)
; #define PG8_WAIT_V(n) asm volatile("s_waitcnt vmcnt(" #n ")" ::: "memory")
; #define PG8_WAIT_L(n) asm volatile("s_waitcnt lgkmcnt(" #n ")" ::: "memory")
; #define PG8_BAR __builtin_amdgcn_s_barrier()
; #define PG8_SCHED __builtin_amdgcn_sched_barrier(0)
; template <class Epi>
; DI void gemm_phase(LAS unsigned char* lds, const Gemm g, const StaticOrder& S, const Epi& E) {
;     ...
;             PG8_LDA(At, 1, 1); PG8_STAGE(PG8_SB(1, 0), b3, voffB); PG8_STAGE(PG8_SB(1, 1), b3 + hstepB, voffB); PG8_STAGE(PG8_SA(1, 0), a3, voffA);
;             PG8_WAIT_V(8); PG8_WAIT_L(0); PG8_BAR; PG8_MMA(1, 0, At, B0); PG8_MMA(1, 1, At, B1); PG8_BAR; PG8_SCHED;
;         }
	s_add_i32 s30, s64, s39
	v_lshl_add_u64 v[178:179], v[178:179], 0, s[12:13]
	s_mov_b32 m0, s30
	ds_read_b128 v[186:189], v149 offset:49152
	ds_read_b128 v[190:193], v149 offset:50176
	ds_read_b128 v[194:197], v149 offset:51200
	ds_read_b128 v[198:201], v149 offset:52224
	ds_read_b128 v[202:205], v149 offset:53248
	ds_read_b128 v[206:209], v149 offset:54272
	ds_read_b128 v[210:213], v149 offset:55296
	ds_read_b128 v[214:217], v149 offset:56320
	global_load_lds_dwordx4 v[178:179], off
	s_add_i32 m0, s30, 0x2000
	s_add_u32 s28, s28, 0x100080
	v_lshl_add_u64 v[178:179], v[218:219], 0, s[12:13]
	s_addc_u32 s29, s29, 0
	s_add_i32 s30, s65, s39
	global_load_lds_dwordx4 v[178:179], off
	v_lshl_add_u64 v[178:179], s[28:29], 0, v[132:133]
	s_mov_b32 m0, s30
	s_nop 0
	global_load_lds_dwordx4 v[178:179], off
	v_lshl_add_u64 v[178:179], s[28:29], 0, v[128:129]
	s_add_i32 m0, s30, 0x2000
	s_nop 0
	global_load_lds_dwordx4 v[178:179], off
	v_lshl_add_u64 v[178:179], v[220:221], 0, s[12:13]
	s_mov_b32 m0, s52
	s_nop 0
	global_load_lds_dwordx4 v[178:179], off
	v_lshl_add_u64 v[178:179], v[222:223], 0, s[12:13]
	s_mov_b32 m0, s53
	s_nop 0
	global_load_lds_dwordx4 v[178:179], off
	s_waitcnt vmcnt(8)
	s_waitcnt lgkmcnt(0)
	s_setprio 1
	s_barrier
	v_mfma_f32_16x16x32_bf16 v[60:63], v[150:153], v[186:189], v[60:63]
	v_mfma_f32_16x16x32_bf16 v[60:63], v[154:157], v[190:193], v[60:63]
	v_mfma_f32_16x16x32_bf16 v[52:55], v[158:161], v[186:189], v[52:55]
	v_mfma_f32_16x16x32_bf16 v[52:55], v[162:165], v[190:193], v[52:55]
	v_mfma_f32_16x16x32_bf16 v[44:47], v[150:153], v[194:197], v[44:47]
	v_mfma_f32_16x16x32_bf16 v[44:47], v[154:157], v[198:201], v[44:47]
	v_mfma_f32_16x16x32_bf16 v[36:39], v[158:161], v[194:197], v[36:39]
	v_mfma_f32_16x16x32_bf16 v[36:39], v[162:165], v[198:201], v[36:39]
	v_mfma_f32_16x16x32_bf16 v[28:31], v[150:153], v[202:205], v[28:31]
	v_mfma_f32_16x16x32_bf16 v[28:31], v[154:157], v[206:209], v[28:31]
	v_mfma_f32_16x16x32_bf16 v[20:23], v[158:161], v[202:205], v[20:23]
	v_mfma_f32_16x16x32_bf16 v[20:23], v[162:165], v[206:209], v[20:23]
	v_mfma_f32_16x16x32_bf16 v[12:15], v[150:153], v[210:213], v[12:15]
	v_mfma_f32_16x16x32_bf16 v[12:15], v[154:157], v[214:217], v[12:15]
	v_mfma_f32_16x16x32_bf16 v[4:7], v[158:161], v[210:213], v[4:7]
	v_mfma_f32_16x16x32_bf16 v[4:7], v[162:165], v[214:217], v[4:7]
	s_setprio 0
	s_setprio 1
	v_mfma_f32_16x16x32_bf16 v[56:59], v[166:169], v[186:189], v[56:59]
	v_mfma_f32_16x16x32_bf16 v[56:59], v[170:173], v[190:193], v[56:59]
	v_mfma_f32_16x16x32_bf16 v[48:51], v[174:177], v[186:189], v[48:51]
	v_mfma_f32_16x16x32_bf16 v[48:51], v[182:185], v[190:193], v[48:51]
	v_mfma_f32_16x16x32_bf16 v[40:43], v[166:169], v[194:197], v[40:43]
	v_mfma_f32_16x16x32_bf16 v[40:43], v[170:173], v[198:201], v[40:43]
	v_mfma_f32_16x16x32_bf16 v[32:35], v[174:177], v[194:197], v[32:35]
	v_mfma_f32_16x16x32_bf16 v[32:35], v[182:185], v[198:201], v[32:35]
	v_mfma_f32_16x16x32_bf16 v[24:27], v[166:169], v[202:205], v[24:27]
	v_mfma_f32_16x16x32_bf16 v[24:27], v[170:173], v[206:209], v[24:27]
	v_mfma_f32_16x16x32_bf16 v[16:19], v[174:177], v[202:205], v[16:19]
	v_mfma_f32_16x16x32_bf16 v[16:19], v[182:185], v[206:209], v[16:19]
	v_mfma_f32_16x16x32_bf16 v[8:11], v[166:169], v[210:213], v[8:11]
	v_mfma_f32_16x16x32_bf16 v[8:11], v[170:173], v[214:217], v[8:11]
	v_mfma_f32_16x16x32_bf16 v[0:3], v[174:177], v[210:213], v[0:3]
	v_mfma_f32_16x16x32_bf16 v[0:3], v[182:185], v[214:217], v[0:3]
	s_setprio 0
	s_barrier
	s_add_u32 s26, s26, 0x100
	s_addc_u32 s27, s27, 0
	s_add_u32 s61, s61, 0x100
	s_addc_u32 s62, s62, 0
	s_cmp_ge_i32 s63, s51
	s_mov_b32 s28, s63
	s_cbranch_scc0 .LBB0_705

; #define PG8_STAGE(bufoff, gbase, voff) do { _Pragma("unroll") for (int _i = 0; _i < 2; ++_i) \
;         __builtin_amdgcn_global_load_lds((const unsigned*)((const char*)(gbase) + (voff)[_i]), (LAS unsigned*)(lds + (bufoff) + ldsw + _i * 8192), 16, 0, 0); } while (0)
; #define PG8_LDA(dst, b, h) do { _Pragma("unroll") for (int m = 0; m < 4; ++m) _Pragma("unroll") for (int k = 0; k < 2; ++k) dst[m][k] = *(const LAS bf16x8*)(lds + PG8_SA(b, h) + aoff + m * 2048 + k * 1024); } while (0)
; #define PG8_LDB(dst, b, h) do { _Pragma("unroll") for (int n = 0; n < 2; ++n) _Pragma("unroll") for (int k = 0; k < 2; ++k) dst[n][k] = *(const LAS bf16x8*)(lds + PG8_SB(b, h) + boff + n * 2048 + k * 1024); } while (0)
; #define PG8_MMA(ai, bj, At, Bt) do { __builtin_amdgcn_s_setprio(1); _Pragma("unroll") for (int m = 0; m < 4; ++m) _Pragma("unroll") for (int n = 0; n < 2; ++n) _Pragma("unroll") for (int k = 0; k < 2; ++k) \
;         acc[ai][bj][m][n] = __builtin_amdgcn_mfma_f32_16x16x32_bf16(Bt[n][k], At[m][k], acc[ai][bj][m][n], 0, 0, 0); __builtin_amdgcn_s_setprio(0); } while (0)
; #define PG8_WAIT_V(n) asm volatile("s_waitcnt vmcnt(" #n ")" ::: "memory")
; #define PG8_WAIT_L(n) asm volatile("s_waitcnt lgkmcnt(" #n ")" ::: "memory")
; #define PG8_BAR __builtin_amdgcn_s_barrier()
; #define PG8_SCHED __builtin_amdgcn_sched_barrier(0)
; template <class Epi>
; DI void gemm_phase(LAS unsigned char* lds, const Gemm g, const StaticOrder& S, const Epi& E) {
;     ...
;             PG8_LDB(B0, 0, 0); PG8_LDB(B1, 0, 1); PG8_SCHED; PG8_LDA(At, 0, 0); PG8_STAGE(PG8_SA(1, 1), a1 + hstepA, voffA);
;             PG8_WAIT_V(8); PG8_WAIT_L(0); PG8_BAR; PG8_MMA(0, 0, At, B0); PG8_MMA(0, 1, At, B1); PG8_BAR; PG8_SCHED;
;             PG8_LDA(At, 0, 1); PG8_STAGE(PG8_SB(0, 0), b2, voffB); PG8_STAGE(PG8_SB(0, 1), b2 + hstepB, voffB); PG8_STAGE(PG8_SA(0, 0), a2, voffA);
;             PG8_WAIT_V(8); PG8_WAIT_L(0); PG8_BAR; PG8_MMA(1, 0, At, B0); PG8_MMA(1, 1, At, B1); PG8_BAR; PG8_SCHED;
.LBB0_727:
	ds_read_b128 v[150:153], v147
	ds_read_b128 v[154:157], v147 offset:1024
	ds_read_b128 v[158:161], v147 offset:2048
	ds_read_b128 v[162:165], v147 offset:3072
	ds_read_b128 v[166:169], v148
	ds_read_b128 v[170:173], v148 offset:1024
	ds_read_b128 v[174:177], v148 offset:2048
	ds_read_b128 v[182:185], v148 offset:3072
	s_add_i32 s74, s38, 2
	s_add_u32 s39, s34, 0xffff0080
	s_addc_u32 s40, s35, -1
	s_cmp_eq_u32 s60, s38
	s_cselect_b32 s38, s71, s72
	s_cselect_b32 s41, s25, s40
	s_cselect_b32 s40, s27, s39
	s_cselect_b32 s39, s70, s73
	v_lshl_add_u64 v[178:179], s[34:35], 0, v[136:137]
	s_add_i32 m0, s51, 0xc000
	ds_read_b128 v[186:189], v149
	ds_read_b128 v[190:193], v149 offset:1024
	ds_read_b128 v[194:197], v149 offset:2048
	ds_read_b128 v[198:201], v149 offset:3072
	ds_read_b128 v[202:205], v149 offset:4096
	ds_read_b128 v[206:209], v149 offset:5120
	ds_read_b128 v[210:213], v149 offset:6144
	ds_read_b128 v[214:217], v149 offset:7168
	global_load_lds_dwordx4 v[178:179], off
	v_lshl_add_u64 v[178:179], s[34:35], 0, v[138:139]
	s_add_i32 m0, s51, 0xe000
	s_nop 0
	global_load_lds_dwordx4 v[178:179], off
	s_waitcnt vmcnt(8)
	s_waitcnt lgkmcnt(0)
	s_setprio 1
	s_barrier
	v_mfma_f32_16x16x32_bf16 v[120:123], v[150:153], v[186:189], v[120:123]
	v_mfma_f32_16x16x32_bf16 v[120:123], v[154:157], v[190:193], v[120:123]
	v_mfma_f32_16x16x32_bf16 v[124:127], v[158:161], v[186:189], v[124:127]
	v_mfma_f32_16x16x32_bf16 v[124:127], v[162:165], v[190:193], v[124:127]
	v_mfma_f32_16x16x32_bf16 v[108:111], v[150:153], v[194:197], v[108:111]
	v_mfma_f32_16x16x32_bf16 v[108:111], v[154:157], v[198:201], v[108:111]
	v_mfma_f32_16x16x32_bf16 v[104:107], v[158:161], v[194:197], v[104:107]
	v_mfma_f32_16x16x32_bf16 v[104:107], v[162:165], v[198:201], v[104:107]
	v_mfma_f32_16x16x32_bf16 v[92:95], v[150:153], v[202:205], v[92:95]
	v_mfma_f32_16x16x32_bf16 v[92:95], v[154:157], v[206:209], v[92:95]
	v_mfma_f32_16x16x32_bf16 v[88:91], v[158:161], v[202:205], v[88:91]
	v_mfma_f32_16x16x32_bf16 v[88:91], v[162:165], v[206:209], v[88:91]
	v_mfma_f32_16x16x32_bf16 v[76:79], v[150:153], v[210:213], v[76:79]
	v_mfma_f32_16x16x32_bf16 v[76:79], v[154:157], v[214:217], v[76:79]
	v_mfma_f32_16x16x32_bf16 v[72:75], v[158:161], v[210:213], v[72:75]
	v_mfma_f32_16x16x32_bf16 v[72:75], v[162:165], v[214:217], v[72:75]
	s_setprio 0
	s_setprio 1
	v_mfma_f32_16x16x32_bf16 v[116:119], v[166:169], v[186:189], v[116:119]
	v_mfma_f32_16x16x32_bf16 v[116:119], v[170:173], v[190:193], v[116:119]
	v_mfma_f32_16x16x32_bf16 v[112:115], v[174:177], v[186:189], v[112:115]
	v_mfma_f32_16x16x32_bf16 v[112:115], v[182:185], v[190:193], v[112:115]
	v_mfma_f32_16x16x32_bf16 v[100:103], v[166:169], v[194:197], v[100:103]
	v_mfma_f32_16x16x32_bf16 v[100:103], v[170:173], v[198:201], v[100:103]
	v_mfma_f32_16x16x32_bf16 v[96:99], v[174:177], v[194:197], v[96:99]
	v_mfma_f32_16x16x32_bf16 v[96:99], v[182:185], v[198:201], v[96:99]
	v_mfma_f32_16x16x32_bf16 v[84:87], v[166:169], v[202:205], v[84:87]
	v_mfma_f32_16x16x32_bf16 v[84:87], v[170:173], v[206:209], v[84:87]
	v_mfma_f32_16x16x32_bf16 v[80:83], v[174:177], v[202:205], v[80:83]
	v_mfma_f32_16x16x32_bf16 v[80:83], v[182:185], v[206:209], v[80:83]
	v_mfma_f32_16x16x32_bf16 v[68:71], v[166:169], v[210:213], v[68:71]
	v_mfma_f32_16x16x32_bf16 v[68:71], v[170:173], v[214:217], v[68:71]
	v_mfma_f32_16x16x32_bf16 v[64:67], v[174:177], v[210:213], v[64:67]
	v_mfma_f32_16x16x32_bf16 v[64:67], v[182:185], v[214:217], v[64:67]
	s_setprio 0
	s_barrier
	s_add_i32 s75, s62, s50
	v_lshl_add_u64 v[178:179], s[38:39], 0, v[132:133]
	s_mov_b32 m0, s75
	ds_read_b128 v[186:189], v149 offset:16384
	ds_read_b128 v[190:193], v149 offset:17408
	ds_read_b128 v[194:197], v149 offset:18432
	ds_read_b128 v[198:201], v149 offset:19456
	ds_read_b128 v[202:205], v149 offset:20480
	ds_read_b128 v[206:209], v149 offset:21504
	ds_read_b128 v[210:213], v149 offset:22528
	ds_read_b128 v[214:217], v149 offset:23552
	global_load_lds_dwordx4 v[178:179], off
	s_add_i32 m0, s75, 0x2000
	s_add_u32 s76, s38, 0x10000
	v_lshl_add_u64 v[218:219], s[38:39], 0, v[128:129]
	s_addc_u32 s77, s39, 0
	s_add_i32 s75, s63, s50
	global_load_lds_dwordx4 v[218:219], off
	v_lshl_add_u64 v[220:221], s[76:77], 0, v[132:133]
	s_mov_b32 m0, s75
	v_lshl_add_u64 v[222:223], s[40:41], 0, v[130:131]
	global_load_lds_dwordx4 v[220:221], off
	v_lshl_add_u64 v[220:221], s[76:77], 0, v[128:129]
	s_add_i32 m0, s75, 0x2000
	s_nop 0
	global_load_lds_dwordx4 v[220:221], off
	v_lshl_add_u64 v[220:221], s[40:41], 0, v[134:135]
	s_mov_b32 m0, s51
	s_nop 0
	global_load_lds_dwordx4 v[220:221], off
	s_mov_b32 m0, s52
	s_nop 0
	global_load_lds_dwordx4 v[222:223], off
	s_waitcnt vmcnt(8)
	s_waitcnt lgkmcnt(0)
	s_setprio 1
	s_barrier
; #define PG8_STAGE(bufoff, gbase, voff) do { _Pragma("unroll") for (int _i = 0; _i < 2; ++_i) \
;         __builtin_amdgcn_global_load_lds((const unsigned*)((const char*)(gbase) + (voff)[_i]), (LAS unsigned*)(lds + (bufoff) + ldsw + _i * 8192), 16, 0, 0); } while (0)
; #define PG8_LDA(dst, b, h) do { _Pragma("unroll") for (int m = 0; m < 4; ++m) _Pragma("unroll") for (int k = 0; k < 2; ++k) dst[m][k] = *(const LAS bf16x8*)(lds + PG8_SA(b, h) + aoff + m * 2048 + k * 1024); } while (0)
; #define PG8_LDB(dst, b, h) do { _Pragma("unroll") for (int n = 0; n < 2; ++n) _Pragma("unroll") for (int k = 0; k < 2; ++k) dst[n][k] = *(const LAS bf16x8*)(lds + PG8_SB(b, h) + boff + n * 2048 + k * 1024); } while (0)
; #define PG8_MMA(ai, bj, At, Bt) do { __builtin_amdgcn_s_setprio(1); _Pragma("unroll") for (int m = 0; m < 4; ++m) _Pragma("unroll") for (int n = 0; n < 2; ++n) _Pragma("unroll") for (int k = 0; k < 2; ++k) \
;         acc[ai][bj][m][n] = __builtin_amdgcn_mfma_f32_16x16x32_bf16(Bt[n][k], At[m][k], acc[ai][bj][m][n], 0, 0, 0); __builtin_amdgcn_s_setprio(0); } while (0)
; #define PG8_WAIT_V(n) asm volatile("s_waitcnt vmcnt(" #n ")" ::: "memory")
; #define PG8_WAIT_L(n) asm volatile("s_waitcnt lgkmcnt(" #n ")" ::: "memory")
; #define PG8_BAR __builtin_amdgcn_s_barrier()
; #define PG8_SCHED __builtin_amdgcn_sched_barrier(0)
; template <class Epi>
; DI void gemm_phase(LAS unsigned char* lds, const Gemm g, const StaticOrder& S, const Epi& E) {
;     ...
;             PG8_WAIT_V(8); PG8_WAIT_L(0); PG8_BAR; PG8_MMA(1, 0, At, B0); PG8_MMA(1, 1, At, B1); PG8_BAR; PG8_SCHED;
;             PG8_LDB(B0, 1, 0); PG8_LDB(B1, 1, 1); PG8_SCHED; PG8_LDA(At, 1, 0); PG8_STAGE(PG8_SA(0, 1), a2 + hstepA, voffA);
;             PG8_WAIT_V(8); PG8_WAIT_L(0); PG8_BAR; PG8_MMA(0, 0, At, B0); PG8_MMA(0, 1, At, B1); PG8_BAR; PG8_SCHED;
	v_mfma_f32_16x16x32_bf16 v[60:63], v[150:153], v[186:189], v[60:63]
	v_mfma_f32_16x16x32_bf16 v[60:63], v[154:157], v[190:193], v[60:63]
	v_mfma_f32_16x16x32_bf16 v[56:59], v[158:161], v[186:189], v[56:59]
	v_mfma_f32_16x16x32_bf16 v[56:59], v[162:165], v[190:193], v[56:59]
	v_mfma_f32_16x16x32_bf16 v[44:47], v[150:153], v[194:197], v[44:47]
	v_mfma_f32_16x16x32_bf16 v[44:47], v[154:157], v[198:201], v[44:47]
	v_mfma_f32_16x16x32_bf16 v[40:43], v[158:161], v[194:197], v[40:43]
	v_mfma_f32_16x16x32_bf16 v[40:43], v[162:165], v[198:201], v[40:43]
	v_mfma_f32_16x16x32_bf16 v[28:31], v[150:153], v[202:205], v[28:31]
	v_mfma_f32_16x16x32_bf16 v[28:31], v[154:157], v[206:209], v[28:31]
	v_mfma_f32_16x16x32_bf16 v[24:27], v[158:161], v[202:205], v[24:27]
	v_mfma_f32_16x16x32_bf16 v[24:27], v[162:165], v[206:209], v[24:27]
	v_mfma_f32_16x16x32_bf16 v[12:15], v[150:153], v[210:213], v[12:15]
	v_mfma_f32_16x16x32_bf16 v[12:15], v[154:157], v[214:217], v[12:15]
	v_mfma_f32_16x16x32_bf16 v[8:11], v[158:161], v[210:213], v[8:11]
	v_mfma_f32_16x16x32_bf16 v[8:11], v[162:165], v[214:217], v[8:11]
	s_setprio 0
	s_setprio 1
	v_mfma_f32_16x16x32_bf16 v[52:55], v[166:169], v[186:189], v[52:55]
	v_mfma_f32_16x16x32_bf16 v[52:55], v[170:173], v[190:193], v[52:55]
	v_mfma_f32_16x16x32_bf16 v[48:51], v[174:177], v[186:189], v[48:51]
	v_mfma_f32_16x16x32_bf16 v[48:51], v[182:185], v[190:193], v[48:51]
	v_mfma_f32_16x16x32_bf16 v[36:39], v[166:169], v[194:197], v[36:39]
	v_mfma_f32_16x16x32_bf16 v[36:39], v[170:173], v[198:201], v[36:39]
	v_mfma_f32_16x16x32_bf16 v[32:35], v[174:177], v[194:197], v[32:35]
	v_mfma_f32_16x16x32_bf16 v[32:35], v[182:185], v[198:201], v[32:35]
	v_mfma_f32_16x16x32_bf16 v[20:23], v[166:169], v[202:205], v[20:23]
	v_mfma_f32_16x16x32_bf16 v[20:23], v[170:173], v[206:209], v[20:23]
	v_mfma_f32_16x16x32_bf16 v[16:19], v[174:177], v[202:205], v[16:19]
	v_mfma_f32_16x16x32_bf16 v[16:19], v[182:185], v[206:209], v[16:19]
	v_mfma_f32_16x16x32_bf16 v[4:7], v[166:169], v[210:213], v[4:7]
	v_mfma_f32_16x16x32_bf16 v[4:7], v[170:173], v[214:217], v[4:7]
	v_mfma_f32_16x16x32_bf16 v[0:3], v[174:177], v[210:213], v[0:3]
	v_mfma_f32_16x16x32_bf16 v[0:3], v[182:185], v[214:217], v[0:3]
	s_setprio 0
	s_barrier
	s_add_i32 s75, 0, 0x18000
	s_add_i32 s76, 0, 0x1c000
	v_add_u32_e32 v162, s75, v145
	v_add_u32_e32 v181, s76, v145
	ds_read_b128 v[150:153], v162
	ds_read_b128 v[154:157], v162 offset:1024
	ds_read_b128 v[158:161], v162 offset:2048
	ds_read_b128 v[162:165], v162 offset:3072
	ds_read_b128 v[166:169], v181
	ds_read_b128 v[170:173], v181 offset:1024
	ds_read_b128 v[174:177], v181 offset:2048
	ds_read_b128 v[182:185], v181 offset:3072
	s_add_u32 s40, s40, 0x10000
	s_addc_u32 s41, s41, 0
	s_mov_b32 m0, s53
	v_lshl_add_u64 v[224:225], s[40:41], 0, v[134:135]
	ds_read_b128 v[186:189], v149 offset:32768
	ds_read_b128 v[190:193], v149 offset:33792
	ds_read_b128 v[194:197], v149 offset:34816
	ds_read_b128 v[198:201], v149 offset:35840
	ds_read_b128 v[202:205], v149 offset:36864
	ds_read_b128 v[206:209], v149 offset:37888
	ds_read_b128 v[210:213], v149 offset:38912
	ds_read_b128 v[214:217], v149 offset:39936
	global_load_lds_dwordx4 v[224:225], off
	v_lshl_add_u64 v[224:225], s[40:41], 0, v[130:131]
	s_mov_b32 m0, s54
	s_nop 0
	global_load_lds_dwordx4 v[224:225], off
	s_waitcnt vmcnt(8)
	s_waitcnt lgkmcnt(0)
	s_setprio 1
	s_barrier
	v_mfma_f32_16x16x32_bf16 v[120:123], v[150:153], v[186:189], v[120:123]
	v_mfma_f32_16x16x32_bf16 v[120:123], v[154:157], v[190:193], v[120:123]
	v_mfma_f32_16x16x32_bf16 v[124:127], v[158:161], v[186:189], v[124:127]
	v_mfma_f32_16x16x32_bf16 v[124:127], v[162:165], v[190:193], v[124:127]
	v_mfma_f32_16x16x32_bf16 v[108:111], v[150:153], v[194:197], v[108:111]
	v_mfma_f32_16x16x32_bf16 v[108:111], v[154:157], v[198:201], v[108:111]
	v_mfma_f32_16x16x32_bf16 v[104:107], v[158:161], v[194:197], v[104:107]
	v_mfma_f32_16x16x32_bf16 v[104:107], v[162:165], v[198:201], v[104:107]
	v_mfma_f32_16x16x32_bf16 v[92:95], v[150:153], v[202:205], v[92:95]
	v_mfma_f32_16x16x32_bf16 v[92:95], v[154:157], v[206:209], v[92:95]
	v_mfma_f32_16x16x32_bf16 v[88:91], v[158:161], v[202:205], v[88:91]
	v_mfma_f32_16x16x32_bf16 v[88:91], v[162:165], v[206:209], v[88:91]
	v_mfma_f32_16x16x32_bf16 v[76:79], v[150:153], v[210:213], v[76:79]
	v_mfma_f32_16x16x32_bf16 v[76:79], v[154:157], v[214:217], v[76:79]
	v_mfma_f32_16x16x32_bf16 v[72:75], v[158:161], v[210:213], v[72:75]
	v_mfma_f32_16x16x32_bf16 v[72:75], v[162:165], v[214:217], v[72:75]
	s_setprio 0
	s_setprio 1
	v_mfma_f32_16x16x32_bf16 v[116:119], v[166:169], v[186:189], v[116:119]
	v_mfma_f32_16x16x32_bf16 v[116:119], v[170:173], v[190:193], v[116:119]
	v_mfma_f32_16x16x32_bf16 v[112:115], v[174:177], v[186:189], v[112:115]
	v_mfma_f32_16x16x32_bf16 v[112:115], v[182:185], v[190:193], v[112:115]
	v_mfma_f32_16x16x32_bf16 v[100:103], v[166:169], v[194:197], v[100:103]
	v_mfma_f32_16x16x32_bf16 v[100:103], v[170:173], v[198:201], v[100:103]
	v_mfma_f32_16x16x32_bf16 v[96:99], v[174:177], v[194:197], v[96:99]
	v_mfma_f32_16x16x32_bf16 v[96:99], v[182:185], v[198:201], v[96:99]
	v_mfma_f32_16x16x32_bf16 v[84:87], v[166:169], v[202:205], v[84:87]
	v_mfma_f32_16x16x32_bf16 v[84:87], v[170:173], v[206:209], v[84:87]
	v_mfma_f32_16x16x32_bf16 v[80:83], v[174:177], v[202:205], v[80:83]
	v_mfma_f32_16x16x32_bf16 v[80:83], v[182:185], v[206:209], v[80:83]
	v_mfma_f32_16x16x32_bf16 v[68:71], v[166:169], v[210:213], v[68:71]
	v_mfma_f32_16x16x32_bf16 v[68:71], v[170:173], v[214:217], v[68:71]
	v_mfma_f32_16x16x32_bf16 v[64:67], v[174:177], v[210:213], v[64:67]
	v_mfma_f32_16x16x32_bf16 v[64:67], v[182:185], v[214:217], v[64:67]
	s_setprio 0
	s_barrier
; #define PG8_STAGE(bufoff, gbase, voff) do { _Pragma("unroll") for (int _i = 0; _i < 2; ++_i) \
;         __builtin_amdgcn_global_load_lds((const unsigned*)((const char*)(gbase) + (voff)[_i]), (LAS unsigned*)(lds + (bufoff) + ldsw + _i * 8192), 16, 0, 0); } while (0)
; #define PG8_LDA(dst, b, h) do { _Pragma("unroll") for (int m = 0; m < 4; ++m) _Pragma("unroll") for (int k = 0; k < 2; ++k) dst[m][k] = *(const LAS bf16x8*)(lds + PG8_SA(b, h) + aoff + m * 2048 + k * 1024); } while (0)
; #define PG8_MMA(ai, bj, At, Bt) do { __builtin_amdgcn_s_setprio(1); _Pragma("unroll") for (int m = 0; m < 4; ++m) _Pragma("unroll") for (int n = 0; n < 2; ++n) _Pragma("unroll") for (int k = 0; k < 2; ++k) \
;         acc[ai][bj][m][n] = __builtin_amdgcn_mfma_f32_16x16x32_bf16(Bt[n][k], At[m][k], acc[ai][bj][m][n], 0, 0, 0); __builtin_amdgcn_s_setprio(0); } while (0)
; #define PG8_WAIT_V(n) asm volatile("s_waitcnt vmcnt(" #n ")" ::: "memory")
; #define PG8_WAIT_L(n) asm volatile("s_waitcnt lgkmcnt(" #n ")" ::: "memory")
; #define PG8_BAR __builtin_amdgcn_s_barrier()
; #define PG8_SCHED __builtin_amdgcn_sched_barrier(0)
; template <class Epi>
; DI void gemm_phase(LAS unsigned char* lds, const Gemm g, const StaticOrder& S, const Epi& E) {
;     ...
;             PG8_LDA(At, 1, 1); PG8_STAGE(PG8_SB(1, 0), b3, voffB); PG8_STAGE(PG8_SB(1, 1), b3 + hstepB, voffB); PG8_STAGE(PG8_SA(1, 0), a3, voffA);
;             PG8_WAIT_V(8); PG8_WAIT_L(0); PG8_BAR; PG8_MMA(1, 0, At, B0); PG8_MMA(1, 1, At, B1); PG8_BAR; PG8_SCHED;
;         }
	s_add_i32 s40, s75, s50
	v_lshl_add_u64 v[178:179], v[178:179], 0, s[10:11]
	s_mov_b32 m0, s40
	ds_read_b128 v[186:189], v149 offset:49152
	ds_read_b128 v[190:193], v149 offset:50176
	ds_read_b128 v[194:197], v149 offset:51200
	ds_read_b128 v[198:201], v149 offset:52224
	ds_read_b128 v[202:205], v149 offset:53248
	ds_read_b128 v[206:209], v149 offset:54272
	ds_read_b128 v[210:213], v149 offset:55296
	ds_read_b128 v[214:217], v149 offset:56320
	global_load_lds_dwordx4 v[178:179], off
	s_add_i32 m0, s40, 0x2000
	s_add_u32 s38, s38, 0x10080
	v_lshl_add_u64 v[178:179], v[218:219], 0, s[10:11]
	s_addc_u32 s39, s39, 0
	s_add_i32 s40, s76, s50
	global_load_lds_dwordx4 v[178:179], off
	v_lshl_add_u64 v[178:179], s[38:39], 0, v[132:133]
	s_mov_b32 m0, s40
	s_nop 0
	global_load_lds_dwordx4 v[178:179], off
	v_lshl_add_u64 v[178:179], s[38:39], 0, v[128:129]
	s_add_i32 m0, s40, 0x2000
	s_nop 0
	global_load_lds_dwordx4 v[178:179], off
	v_lshl_add_u64 v[178:179], v[220:221], 0, s[10:11]
	s_mov_b32 m0, s58
	s_nop 0
	global_load_lds_dwordx4 v[178:179], off
	v_lshl_add_u64 v[178:179], v[222:223], 0, s[10:11]
	s_mov_b32 m0, s59
	s_nop 0
	global_load_lds_dwordx4 v[178:179], off
	s_waitcnt vmcnt(8)
	s_waitcnt lgkmcnt(0)
	s_setprio 1
	s_barrier
	v_mfma_f32_16x16x32_bf16 v[60:63], v[150:153], v[186:189], v[60:63]
	v_mfma_f32_16x16x32_bf16 v[60:63], v[154:157], v[190:193], v[60:63]
	v_mfma_f32_16x16x32_bf16 v[56:59], v[158:161], v[186:189], v[56:59]
	v_mfma_f32_16x16x32_bf16 v[56:59], v[162:165], v[190:193], v[56:59]
	v_mfma_f32_16x16x32_bf16 v[44:47], v[150:153], v[194:197], v[44:47]
	v_mfma_f32_16x16x32_bf16 v[44:47], v[154:157], v[198:201], v[44:47]
	v_mfma_f32_16x16x32_bf16 v[40:43], v[158:161], v[194:197], v[40:43]
	v_mfma_f32_16x16x32_bf16 v[40:43], v[162:165], v[198:201], v[40:43]
	v_mfma_f32_16x16x32_bf16 v[28:31], v[150:153], v[202:205], v[28:31]
	v_mfma_f32_16x16x32_bf16 v[28:31], v[154:157], v[206:209], v[28:31]
	v_mfma_f32_16x16x32_bf16 v[24:27], v[158:161], v[202:205], v[24:27]
	v_mfma_f32_16x16x32_bf16 v[24:27], v[162:165], v[206:209], v[24:27]
	v_mfma_f32_16x16x32_bf16 v[12:15], v[150:153], v[210:213], v[12:15]
	v_mfma_f32_16x16x32_bf16 v[12:15], v[154:157], v[214:217], v[12:15]
	v_mfma_f32_16x16x32_bf16 v[8:11], v[158:161], v[210:213], v[8:11]
	v_mfma_f32_16x16x32_bf16 v[8:11], v[162:165], v[214:217], v[8:11]
	s_setprio 0
	s_setprio 1
	v_mfma_f32_16x16x32_bf16 v[52:55], v[166:169], v[186:189], v[52:55]
	v_mfma_f32_16x16x32_bf16 v[52:55], v[170:173], v[190:193], v[52:55]
	v_mfma_f32_16x16x32_bf16 v[48:51], v[174:177], v[186:189], v[48:51]
	v_mfma_f32_16x16x32_bf16 v[48:51], v[182:185], v[190:193], v[48:51]
	v_mfma_f32_16x16x32_bf16 v[36:39], v[166:169], v[194:197], v[36:39]
	v_mfma_f32_16x16x32_bf16 v[36:39], v[170:173], v[198:201], v[36:39]
	v_mfma_f32_16x16x32_bf16 v[32:35], v[174:177], v[194:197], v[32:35]
	v_mfma_f32_16x16x32_bf16 v[32:35], v[182:185], v[198:201], v[32:35]
	v_mfma_f32_16x16x32_bf16 v[20:23], v[166:169], v[202:205], v[20:23]
	v_mfma_f32_16x16x32_bf16 v[20:23], v[170:173], v[206:209], v[20:23]
	v_mfma_f32_16x16x32_bf16 v[16:19], v[174:177], v[202:205], v[16:19]
	v_mfma_f32_16x16x32_bf16 v[16:19], v[182:185], v[206:209], v[16:19]
	v_mfma_f32_16x16x32_bf16 v[4:7], v[166:169], v[210:213], v[4:7]
	v_mfma_f32_16x16x32_bf16 v[4:7], v[170:173], v[214:217], v[4:7]
	v_mfma_f32_16x16x32_bf16 v[0:3], v[174:177], v[210:213], v[0:3]
	v_mfma_f32_16x16x32_bf16 v[0:3], v[182:185], v[214:217], v[0:3]
	s_setprio 0
	s_barrier
	s_add_u32 s34, s34, 0x100
	s_addc_u32 s35, s35, 0
	s_add_u32 s72, s72, 0x100
	s_addc_u32 s73, s73, 0
	s_cmp_ge_i32 s74, s57
	s_mov_b32 s38, s74
	s_cbranch_scc0 .LBB0_727

; #define PG8_STAGE(bufoff, gbase, voff) do { _Pragma("unroll") for (int _i = 0; _i < 2; ++_i) \
;         __builtin_amdgcn_global_load_lds((const unsigned*)((const char*)(gbase) + (voff)[_i]), (LAS unsigned*)(lds + (bufoff) + ldsw + _i * 8192), 16, 0, 0); } while (0)
; #define PG8_LDA(dst, b, h) do { _Pragma("unroll") for (int m = 0; m < 4; ++m) _Pragma("unroll") for (int k = 0; k < 2; ++k) dst[m][k] = *(const LAS bf16x8*)(lds + PG8_SA(b, h) + aoff + m * 2048 + k * 1024); } while (0)
; #define PG8_LDB(dst, b, h) do { _Pragma("unroll") for (int n = 0; n < 2; ++n) _Pragma("unroll") for (int k = 0; k < 2; ++k) dst[n][k] = *(const LAS bf16x8*)(lds + PG8_SB(b, h) + boff + n * 2048 + k * 1024); } while (0)
; #define PG8_MMA(ai, bj, At, Bt) do { __builtin_amdgcn_s_setprio(1); _Pragma("unroll") for (int m = 0; m < 4; ++m) _Pragma("unroll") for (int n = 0; n < 2; ++n) _Pragma("unroll") for (int k = 0; k < 2; ++k) \
;         acc[ai][bj][m][n] = __builtin_amdgcn_mfma_f32_16x16x32_bf16(Bt[n][k], At[m][k], acc[ai][bj][m][n], 0, 0, 0); __builtin_amdgcn_s_setprio(0); } while (0)
; #define PG8_WAIT_V(n) asm volatile("s_waitcnt vmcnt(" #n ")" ::: "memory")
; #define PG8_WAIT_L(n) asm volatile("s_waitcnt lgkmcnt(" #n ")" ::: "memory")
; #define PG8_BAR __builtin_amdgcn_s_barrier()
; #define PG8_SCHED __builtin_amdgcn_sched_barrier(0)
; template <class Epi>
; DI void gemm_phase(LAS unsigned char* lds, const Gemm g, const StaticOrder& S, const Epi& E) {
;     ...
;             PG8_LDB(B0, 0, 0); PG8_LDB(B1, 0, 1); PG8_SCHED; PG8_LDA(At, 0, 0); PG8_STAGE(PG8_SA(1, 1), a1 + hstepA, voffA);
;             PG8_WAIT_V(8); PG8_WAIT_L(0); PG8_BAR; PG8_MMA(0, 0, At, B0); PG8_MMA(0, 1, At, B1); PG8_BAR; PG8_SCHED;
;             PG8_LDA(At, 0, 1); PG8_STAGE(PG8_SB(0, 0), b2, voffB); PG8_STAGE(PG8_SB(0, 1), b2 + hstepB, voffB); PG8_STAGE(PG8_SA(0, 0), a2, voffA);
;             PG8_WAIT_V(8); PG8_WAIT_L(0); PG8_BAR; PG8_MMA(1, 0, At, B0); PG8_MMA(1, 1, At, B1); PG8_BAR; PG8_SCHED;
.LBB0_813:
	ds_read_b128 v[144:147], v151
	ds_read_b128 v[156:159], v151 offset:1024
	ds_read_b128 v[160:163], v151 offset:2048
	ds_read_b128 v[164:167], v151 offset:3072
	ds_read_b128 v[168:171], v152
	ds_read_b128 v[172:175], v152 offset:1024
	ds_read_b128 v[176:179], v152 offset:2048
	ds_read_b128 v[182:185], v152 offset:3072
	s_add_i32 s63, s28, 2
	s_add_u32 s26, s24, 0x100
	s_addc_u32 s27, s25, 0
	s_cmp_eq_u32 s54, s28
	s_cselect_b32 s28, s22, s61
	s_cselect_b32 s31, s9, s27
	s_cselect_b32 s30, s8, s26
	s_cselect_b32 s29, s23, s62
	v_lshl_add_u64 v[218:219], s[24:25], 0, v[136:137]
	s_add_i32 m0, s40, 0xc000
	ds_read_b128 v[186:189], v153
	ds_read_b128 v[190:193], v153 offset:1024
	ds_read_b128 v[194:197], v153 offset:2048
	ds_read_b128 v[198:201], v153 offset:3072
	ds_read_b128 v[202:205], v153 offset:4096
	ds_read_b128 v[206:209], v153 offset:5120
	ds_read_b128 v[210:213], v153 offset:6144
	ds_read_b128 v[214:217], v153 offset:7168
	global_load_lds_dwordx4 v[218:219], off
	v_lshl_add_u64 v[218:219], s[24:25], 0, v[138:139]
	s_add_i32 m0, s40, 0xe000
	s_nop 0
	global_load_lds_dwordx4 v[218:219], off
	s_waitcnt vmcnt(8)
	s_waitcnt lgkmcnt(0)
	s_setprio 1
	s_barrier
	v_mfma_f32_16x16x32_bf16 v[124:127], v[144:147], v[186:189], v[124:127]
	v_mfma_f32_16x16x32_bf16 v[124:127], v[156:159], v[190:193], v[124:127]
	v_mfma_f32_16x16x32_bf16 v[120:123], v[160:163], v[186:189], v[120:123]
	v_mfma_f32_16x16x32_bf16 v[120:123], v[164:167], v[190:193], v[120:123]
	v_mfma_f32_16x16x32_bf16 v[108:111], v[144:147], v[194:197], v[108:111]
	v_mfma_f32_16x16x32_bf16 v[108:111], v[156:159], v[198:201], v[108:111]
	v_mfma_f32_16x16x32_bf16 v[104:107], v[160:163], v[194:197], v[104:107]
	v_mfma_f32_16x16x32_bf16 v[104:107], v[164:167], v[198:201], v[104:107]
	v_mfma_f32_16x16x32_bf16 v[92:95], v[144:147], v[202:205], v[92:95]
	v_mfma_f32_16x16x32_bf16 v[92:95], v[156:159], v[206:209], v[92:95]
	v_mfma_f32_16x16x32_bf16 v[88:91], v[160:163], v[202:205], v[88:91]
	v_mfma_f32_16x16x32_bf16 v[88:91], v[164:167], v[206:209], v[88:91]
	v_mfma_f32_16x16x32_bf16 v[76:79], v[144:147], v[210:213], v[76:79]
	v_mfma_f32_16x16x32_bf16 v[76:79], v[156:159], v[214:217], v[76:79]
	v_mfma_f32_16x16x32_bf16 v[72:75], v[160:163], v[210:213], v[72:75]
	v_mfma_f32_16x16x32_bf16 v[72:75], v[164:167], v[214:217], v[72:75]
	s_setprio 0
	s_setprio 1
	v_mfma_f32_16x16x32_bf16 v[116:119], v[168:171], v[186:189], v[116:119]
	v_mfma_f32_16x16x32_bf16 v[116:119], v[172:175], v[190:193], v[116:119]
	v_mfma_f32_16x16x32_bf16 v[112:115], v[176:179], v[186:189], v[112:115]
	v_mfma_f32_16x16x32_bf16 v[112:115], v[182:185], v[190:193], v[112:115]
	v_mfma_f32_16x16x32_bf16 v[100:103], v[168:171], v[194:197], v[100:103]
	v_mfma_f32_16x16x32_bf16 v[100:103], v[172:175], v[198:201], v[100:103]
	v_mfma_f32_16x16x32_bf16 v[96:99], v[176:179], v[194:197], v[96:99]
	v_mfma_f32_16x16x32_bf16 v[96:99], v[182:185], v[198:201], v[96:99]
	v_mfma_f32_16x16x32_bf16 v[84:87], v[168:171], v[202:205], v[84:87]
	v_mfma_f32_16x16x32_bf16 v[84:87], v[172:175], v[206:209], v[84:87]
	v_mfma_f32_16x16x32_bf16 v[80:83], v[176:179], v[202:205], v[80:83]
	v_mfma_f32_16x16x32_bf16 v[80:83], v[182:185], v[206:209], v[80:83]
	v_mfma_f32_16x16x32_bf16 v[68:71], v[168:171], v[210:213], v[68:71]
	v_mfma_f32_16x16x32_bf16 v[68:71], v[172:175], v[214:217], v[68:71]
	v_mfma_f32_16x16x32_bf16 v[64:67], v[176:179], v[210:213], v[64:67]
	v_mfma_f32_16x16x32_bf16 v[64:67], v[182:185], v[214:217], v[64:67]
	s_setprio 0
	s_barrier
	s_add_i32 s24, s55, s39
	v_lshl_add_u64 v[218:219], s[28:29], 0, v[130:131]
	s_mov_b32 m0, s24
	ds_read_b128 v[186:189], v153 offset:16384
	ds_read_b128 v[190:193], v153 offset:17408
	ds_read_b128 v[194:197], v153 offset:18432
	ds_read_b128 v[198:201], v153 offset:19456
	ds_read_b128 v[202:205], v153 offset:20480
	ds_read_b128 v[206:209], v153 offset:21504
	ds_read_b128 v[210:213], v153 offset:22528
	ds_read_b128 v[214:217], v153 offset:23552
	global_load_lds_dwordx4 v[218:219], off
	s_add_i32 m0, s24, 0x2000
	s_add_u32 s24, s28, 0x2b0000
	v_lshl_add_u64 v[220:221], s[28:29], 0, v[134:135]
	s_addc_u32 s25, s29, 0
	s_add_i32 s64, s56, s39
	global_load_lds_dwordx4 v[220:221], off
	v_lshl_add_u64 v[222:223], s[24:25], 0, v[130:131]
	s_mov_b32 m0, s64
	v_lshl_add_u64 v[224:225], s[30:31], 0, v[132:133]
	global_load_lds_dwordx4 v[222:223], off
	v_lshl_add_u64 v[222:223], s[24:25], 0, v[134:135]
	s_add_i32 m0, s64, 0x2000
	s_nop 0
	global_load_lds_dwordx4 v[222:223], off
	v_lshl_add_u64 v[222:223], s[30:31], 0, v[128:129]
	s_mov_b32 m0, s40
	s_nop 0
	global_load_lds_dwordx4 v[222:223], off
	s_mov_b32 m0, s41
	s_nop 0
	global_load_lds_dwordx4 v[224:225], off
	s_waitcnt vmcnt(8)
	s_waitcnt lgkmcnt(0)
	s_setprio 1
	s_barrier
; #define PG8_STAGE(bufoff, gbase, voff) do { _Pragma("unroll") for (int _i = 0; _i < 2; ++_i) \
;         __builtin_amdgcn_global_load_lds((const unsigned*)((const char*)(gbase) + (voff)[_i]), (LAS unsigned*)(lds + (bufoff) + ldsw + _i * 8192), 16, 0, 0); } while (0)
; #define PG8_LDA(dst, b, h) do { _Pragma("unroll") for (int m = 0; m < 4; ++m) _Pragma("unroll") for (int k = 0; k < 2; ++k) dst[m][k] = *(const LAS bf16x8*)(lds + PG8_SA(b, h) + aoff + m * 2048 + k * 1024); } while (0)
; #define PG8_LDB(dst, b, h) do { _Pragma("unroll") for (int n = 0; n < 2; ++n) _Pragma("unroll") for (int k = 0; k < 2; ++k) dst[n][k] = *(const LAS bf16x8*)(lds + PG8_SB(b, h) + boff + n * 2048 + k * 1024); } while (0)
; #define PG8_MMA(ai, bj, At, Bt) do { __builtin_amdgcn_s_setprio(1); _Pragma("unroll") for (int m = 0; m < 4; ++m) _Pragma("unroll") for (int n = 0; n < 2; ++n) _Pragma("unroll") for (int k = 0; k < 2; ++k) \
;         acc[ai][bj][m][n] = __builtin_amdgcn_mfma_f32_16x16x32_bf16(Bt[n][k], At[m][k], acc[ai][bj][m][n], 0, 0, 0); __builtin_amdgcn_s_setprio(0); } while (0)
; #define PG8_WAIT_V(n) asm volatile("s_waitcnt vmcnt(" #n ")" ::: "memory")
; #define PG8_WAIT_L(n) asm volatile("s_waitcnt lgkmcnt(" #n ")" ::: "memory")
; #define PG8_BAR __builtin_amdgcn_s_barrier()
; #define PG8_SCHED __builtin_amdgcn_sched_barrier(0)
; template <class Epi>
; DI void gemm_phase(LAS unsigned char* lds, const Gemm g, const StaticOrder& S, const Epi& E) {
;     ...
;             PG8_WAIT_V(8); PG8_WAIT_L(0); PG8_BAR; PG8_MMA(1, 0, At, B0); PG8_MMA(1, 1, At, B1); PG8_BAR; PG8_SCHED;
;             PG8_LDB(B0, 1, 0); PG8_LDB(B1, 1, 1); PG8_SCHED; PG8_LDA(At, 1, 0); PG8_STAGE(PG8_SA(0, 1), a2 + hstepA, voffA);
;             PG8_WAIT_V(8); PG8_WAIT_L(0); PG8_BAR; PG8_MMA(0, 0, At, B0); PG8_MMA(0, 1, At, B1); PG8_BAR; PG8_SCHED;
	v_mfma_f32_16x16x32_bf16 v[60:63], v[144:147], v[186:189], v[60:63]
	v_mfma_f32_16x16x32_bf16 v[60:63], v[156:159], v[190:193], v[60:63]
	v_mfma_f32_16x16x32_bf16 v[56:59], v[160:163], v[186:189], v[56:59]
	v_mfma_f32_16x16x32_bf16 v[56:59], v[164:167], v[190:193], v[56:59]
	v_mfma_f32_16x16x32_bf16 v[44:47], v[144:147], v[194:197], v[44:47]
	v_mfma_f32_16x16x32_bf16 v[44:47], v[156:159], v[198:201], v[44:47]
	v_mfma_f32_16x16x32_bf16 v[40:43], v[160:163], v[194:197], v[40:43]
	v_mfma_f32_16x16x32_bf16 v[40:43], v[164:167], v[198:201], v[40:43]
	v_mfma_f32_16x16x32_bf16 v[28:31], v[144:147], v[202:205], v[28:31]
	v_mfma_f32_16x16x32_bf16 v[28:31], v[156:159], v[206:209], v[28:31]
	v_mfma_f32_16x16x32_bf16 v[24:27], v[160:163], v[202:205], v[24:27]
	v_mfma_f32_16x16x32_bf16 v[24:27], v[164:167], v[206:209], v[24:27]
	v_mfma_f32_16x16x32_bf16 v[12:15], v[144:147], v[210:213], v[12:15]
	v_mfma_f32_16x16x32_bf16 v[12:15], v[156:159], v[214:217], v[12:15]
	v_mfma_f32_16x16x32_bf16 v[8:11], v[160:163], v[210:213], v[8:11]
	v_mfma_f32_16x16x32_bf16 v[8:11], v[164:167], v[214:217], v[8:11]
	s_setprio 0
	s_setprio 1
	v_mfma_f32_16x16x32_bf16 v[52:55], v[168:171], v[186:189], v[52:55]
	v_mfma_f32_16x16x32_bf16 v[52:55], v[172:175], v[190:193], v[52:55]
	v_mfma_f32_16x16x32_bf16 v[48:51], v[176:179], v[186:189], v[48:51]
	v_mfma_f32_16x16x32_bf16 v[48:51], v[182:185], v[190:193], v[48:51]
	v_mfma_f32_16x16x32_bf16 v[36:39], v[168:171], v[194:197], v[36:39]
	v_mfma_f32_16x16x32_bf16 v[36:39], v[172:175], v[198:201], v[36:39]
	v_mfma_f32_16x16x32_bf16 v[32:35], v[176:179], v[194:197], v[32:35]
	v_mfma_f32_16x16x32_bf16 v[32:35], v[182:185], v[198:201], v[32:35]
	v_mfma_f32_16x16x32_bf16 v[20:23], v[168:171], v[202:205], v[20:23]
	v_mfma_f32_16x16x32_bf16 v[20:23], v[172:175], v[206:209], v[20:23]
	v_mfma_f32_16x16x32_bf16 v[16:19], v[176:179], v[202:205], v[16:19]
	v_mfma_f32_16x16x32_bf16 v[16:19], v[182:185], v[206:209], v[16:19]
	v_mfma_f32_16x16x32_bf16 v[4:7], v[168:171], v[210:213], v[4:7]
	v_mfma_f32_16x16x32_bf16 v[4:7], v[172:175], v[214:217], v[4:7]
	v_mfma_f32_16x16x32_bf16 v[0:3], v[176:179], v[210:213], v[0:3]
	v_mfma_f32_16x16x32_bf16 v[0:3], v[182:185], v[214:217], v[0:3]
	s_setprio 0
	s_barrier
	s_add_i32 s64, 0, 0x18000
	v_add_u32_e32 v155, s64, v149
	s_add_i32 s65, 0, 0x1c000
	ds_read_b128 v[144:147], v155
	ds_read_b128 v[156:159], v155 offset:1024
	ds_read_b128 v[160:163], v155 offset:2048
	ds_read_b128 v[164:167], v155 offset:3072
	v_add_u32_e32 v155, s65, v149
	ds_read_b128 v[168:171], v155
	ds_read_b128 v[172:175], v155 offset:1024
	ds_read_b128 v[176:179], v155 offset:2048
	ds_read_b128 v[182:185], v155 offset:3072
	s_add_u32 s24, s30, 0x2b0000
	s_addc_u32 s25, s31, 0
	s_mov_b32 m0, s42
	v_lshl_add_u64 v[226:227], s[24:25], 0, v[128:129]
	ds_read_b128 v[186:189], v153 offset:32768
	ds_read_b128 v[190:193], v153 offset:33792
	ds_read_b128 v[194:197], v153 offset:34816
	ds_read_b128 v[198:201], v153 offset:35840
	ds_read_b128 v[202:205], v153 offset:36864
	ds_read_b128 v[206:209], v153 offset:37888
	ds_read_b128 v[210:213], v153 offset:38912
	ds_read_b128 v[214:217], v153 offset:39936
	global_load_lds_dwordx4 v[226:227], off
	v_lshl_add_u64 v[226:227], s[24:25], 0, v[132:133]
	s_mov_b32 m0, s43
	s_nop 0
	global_load_lds_dwordx4 v[226:227], off
	s_waitcnt vmcnt(8)
	s_waitcnt lgkmcnt(0)
	s_setprio 1
	s_barrier
	v_mfma_f32_16x16x32_bf16 v[124:127], v[144:147], v[186:189], v[124:127]
	v_mfma_f32_16x16x32_bf16 v[124:127], v[156:159], v[190:193], v[124:127]
	v_mfma_f32_16x16x32_bf16 v[120:123], v[160:163], v[186:189], v[120:123]
	v_mfma_f32_16x16x32_bf16 v[120:123], v[164:167], v[190:193], v[120:123]
	v_mfma_f32_16x16x32_bf16 v[108:111], v[144:147], v[194:197], v[108:111]
	v_mfma_f32_16x16x32_bf16 v[108:111], v[156:159], v[198:201], v[108:111]
	v_mfma_f32_16x16x32_bf16 v[104:107], v[160:163], v[194:197], v[104:107]
	v_mfma_f32_16x16x32_bf16 v[104:107], v[164:167], v[198:201], v[104:107]
	v_mfma_f32_16x16x32_bf16 v[92:95], v[144:147], v[202:205], v[92:95]
	v_mfma_f32_16x16x32_bf16 v[92:95], v[156:159], v[206:209], v[92:95]
	v_mfma_f32_16x16x32_bf16 v[88:91], v[160:163], v[202:205], v[88:91]
	v_mfma_f32_16x16x32_bf16 v[88:91], v[164:167], v[206:209], v[88:91]
	v_mfma_f32_16x16x32_bf16 v[76:79], v[144:147], v[210:213], v[76:79]
	v_mfma_f32_16x16x32_bf16 v[76:79], v[156:159], v[214:217], v[76:79]
	v_mfma_f32_16x16x32_bf16 v[72:75], v[160:163], v[210:213], v[72:75]
	v_mfma_f32_16x16x32_bf16 v[72:75], v[164:167], v[214:217], v[72:75]
	s_setprio 0
	s_setprio 1
	v_mfma_f32_16x16x32_bf16 v[116:119], v[168:171], v[186:189], v[116:119]
	v_mfma_f32_16x16x32_bf16 v[116:119], v[172:175], v[190:193], v[116:119]
	v_mfma_f32_16x16x32_bf16 v[112:115], v[176:179], v[186:189], v[112:115]
	v_mfma_f32_16x16x32_bf16 v[112:115], v[182:185], v[190:193], v[112:115]
	v_mfma_f32_16x16x32_bf16 v[100:103], v[168:171], v[194:197], v[100:103]
	v_mfma_f32_16x16x32_bf16 v[100:103], v[172:175], v[198:201], v[100:103]
	v_mfma_f32_16x16x32_bf16 v[96:99], v[176:179], v[194:197], v[96:99]
	v_mfma_f32_16x16x32_bf16 v[96:99], v[182:185], v[198:201], v[96:99]
	v_mfma_f32_16x16x32_bf16 v[84:87], v[168:171], v[202:205], v[84:87]
	v_mfma_f32_16x16x32_bf16 v[84:87], v[172:175], v[206:209], v[84:87]
	v_mfma_f32_16x16x32_bf16 v[80:83], v[176:179], v[202:205], v[80:83]
	v_mfma_f32_16x16x32_bf16 v[80:83], v[182:185], v[206:209], v[80:83]
	v_mfma_f32_16x16x32_bf16 v[68:71], v[168:171], v[210:213], v[68:71]
	v_mfma_f32_16x16x32_bf16 v[68:71], v[172:175], v[214:217], v[68:71]
	v_mfma_f32_16x16x32_bf16 v[64:67], v[176:179], v[210:213], v[64:67]
	v_mfma_f32_16x16x32_bf16 v[64:67], v[182:185], v[214:217], v[64:67]
	s_setprio 0
	s_barrier
; #define PG8_STAGE(bufoff, gbase, voff) do { _Pragma("unroll") for (int _i = 0; _i < 2; ++_i) \
;         __builtin_amdgcn_global_load_lds((const unsigned*)((const char*)(gbase) + (voff)[_i]), (LAS unsigned*)(lds + (bufoff) + ldsw + _i * 8192), 16, 0, 0); } while (0)
; #define PG8_LDA(dst, b, h) do { _Pragma("unroll") for (int m = 0; m < 4; ++m) _Pragma("unroll") for (int k = 0; k < 2; ++k) dst[m][k] = *(const LAS bf16x8*)(lds + PG8_SA(b, h) + aoff + m * 2048 + k * 1024); } while (0)
; #define PG8_MMA(ai, bj, At, Bt) do { __builtin_amdgcn_s_setprio(1); _Pragma("unroll") for (int m = 0; m < 4; ++m) _Pragma("unroll") for (int n = 0; n < 2; ++n) _Pragma("unroll") for (int k = 0; k < 2; ++k) \
;         acc[ai][bj][m][n] = __builtin_amdgcn_mfma_f32_16x16x32_bf16(Bt[n][k], At[m][k], acc[ai][bj][m][n], 0, 0, 0); __builtin_amdgcn_s_setprio(0); } while (0)
; #define PG8_WAIT_V(n) asm volatile("s_waitcnt vmcnt(" #n ")" ::: "memory")
; #define PG8_WAIT_L(n) asm volatile("s_waitcnt lgkmcnt(" #n ")" ::: "memory")
; #define PG8_BAR __builtin_amdgcn_s_barrier()
; #define PG8_SCHED __builtin_amdgcn_sched_barrier(0)
; template <class Epi>
; DI void gemm_phase(LAS unsigned char* lds, const Gemm g, const StaticOrder& S, const Epi& E) {
;     ...
;             PG8_LDA(At, 1, 1); PG8_STAGE(PG8_SB(1, 0), b3, voffB); PG8_STAGE(PG8_SB(1, 1), b3 + hstepB, voffB); PG8_STAGE(PG8_SA(1, 0), a3, voffA);
;             PG8_WAIT_V(8); PG8_WAIT_L(0); PG8_BAR; PG8_MMA(1, 0, At, B0); PG8_MMA(1, 1, At, B1); PG8_BAR; PG8_SCHED;
;         }
	s_add_i32 s24, s64, s39
	v_lshl_add_u64 v[218:219], v[218:219], 0, s[16:17]
	s_mov_b32 m0, s24
	ds_read_b128 v[186:189], v153 offset:49152
	ds_read_b128 v[190:193], v153 offset:50176
	ds_read_b128 v[194:197], v153 offset:51200
	ds_read_b128 v[198:201], v153 offset:52224
	ds_read_b128 v[202:205], v153 offset:53248
	ds_read_b128 v[206:209], v153 offset:54272
	ds_read_b128 v[210:213], v153 offset:55296
	ds_read_b128 v[214:217], v153 offset:56320
	global_load_lds_dwordx4 v[218:219], off
	s_add_i32 m0, s24, 0x2000
	s_add_u32 s24, s28, 0x2b0080
	v_lshl_add_u64 v[218:219], v[220:221], 0, s[16:17]
	s_addc_u32 s25, s29, 0
	s_add_i32 s28, s65, s39
	global_load_lds_dwordx4 v[218:219], off
	v_lshl_add_u64 v[218:219], s[24:25], 0, v[130:131]
	s_mov_b32 m0, s28
	s_nop 0
	global_load_lds_dwordx4 v[218:219], off
	v_lshl_add_u64 v[218:219], s[24:25], 0, v[134:135]
	s_add_i32 m0, s28, 0x2000
	s_nop 0
	global_load_lds_dwordx4 v[218:219], off
	v_lshl_add_u64 v[218:219], v[222:223], 0, s[16:17]
	s_mov_b32 m0, s52
	s_nop 0
	global_load_lds_dwordx4 v[218:219], off
	v_lshl_add_u64 v[218:219], v[224:225], 0, s[16:17]
	s_mov_b32 m0, s53
	s_nop 0
	global_load_lds_dwordx4 v[218:219], off
	s_waitcnt vmcnt(8)
	s_waitcnt lgkmcnt(0)
	s_setprio 1
	s_barrier
	v_mfma_f32_16x16x32_bf16 v[60:63], v[144:147], v[186:189], v[60:63]
	v_mfma_f32_16x16x32_bf16 v[60:63], v[156:159], v[190:193], v[60:63]
	v_mfma_f32_16x16x32_bf16 v[56:59], v[160:163], v[186:189], v[56:59]
	v_mfma_f32_16x16x32_bf16 v[56:59], v[164:167], v[190:193], v[56:59]
	v_mfma_f32_16x16x32_bf16 v[44:47], v[144:147], v[194:197], v[44:47]
	v_mfma_f32_16x16x32_bf16 v[44:47], v[156:159], v[198:201], v[44:47]
	v_mfma_f32_16x16x32_bf16 v[40:43], v[160:163], v[194:197], v[40:43]
	v_mfma_f32_16x16x32_bf16 v[40:43], v[164:167], v[198:201], v[40:43]
	v_mfma_f32_16x16x32_bf16 v[28:31], v[144:147], v[202:205], v[28:31]
	v_mfma_f32_16x16x32_bf16 v[28:31], v[156:159], v[206:209], v[28:31]
	v_mfma_f32_16x16x32_bf16 v[24:27], v[160:163], v[202:205], v[24:27]
	v_mfma_f32_16x16x32_bf16 v[24:27], v[164:167], v[206:209], v[24:27]
	v_mfma_f32_16x16x32_bf16 v[12:15], v[144:147], v[210:213], v[12:15]
	v_mfma_f32_16x16x32_bf16 v[12:15], v[156:159], v[214:217], v[12:15]
	v_mfma_f32_16x16x32_bf16 v[8:11], v[160:163], v[210:213], v[8:11]
	v_mfma_f32_16x16x32_bf16 v[8:11], v[164:167], v[214:217], v[8:11]
	s_setprio 0
	s_setprio 1
	v_mfma_f32_16x16x32_bf16 v[52:55], v[168:171], v[186:189], v[52:55]
	v_mfma_f32_16x16x32_bf16 v[52:55], v[172:175], v[190:193], v[52:55]
	v_mfma_f32_16x16x32_bf16 v[48:51], v[176:179], v[186:189], v[48:51]
	v_mfma_f32_16x16x32_bf16 v[48:51], v[182:185], v[190:193], v[48:51]
	v_mfma_f32_16x16x32_bf16 v[36:39], v[168:171], v[194:197], v[36:39]
	v_mfma_f32_16x16x32_bf16 v[36:39], v[172:175], v[198:201], v[36:39]
	v_mfma_f32_16x16x32_bf16 v[32:35], v[176:179], v[194:197], v[32:35]
	v_mfma_f32_16x16x32_bf16 v[32:35], v[182:185], v[198:201], v[32:35]
	v_mfma_f32_16x16x32_bf16 v[20:23], v[168:171], v[202:205], v[20:23]
	v_mfma_f32_16x16x32_bf16 v[20:23], v[172:175], v[206:209], v[20:23]
	v_mfma_f32_16x16x32_bf16 v[16:19], v[176:179], v[202:205], v[16:19]
	v_mfma_f32_16x16x32_bf16 v[16:19], v[182:185], v[206:209], v[16:19]
	v_mfma_f32_16x16x32_bf16 v[4:7], v[168:171], v[210:213], v[4:7]
	v_mfma_f32_16x16x32_bf16 v[4:7], v[172:175], v[214:217], v[4:7]
	v_mfma_f32_16x16x32_bf16 v[0:3], v[176:179], v[210:213], v[0:3]
	v_mfma_f32_16x16x32_bf16 v[0:3], v[182:185], v[214:217], v[0:3]
	s_setprio 0
	s_barrier
	s_add_u32 s61, s61, 0x100
	s_addc_u32 s62, s62, 0
	s_cmp_ge_i32 s63, s51
	s_mov_b64 s[24:25], s[26:27]
	s_mov_b32 s28, s63
	s_cbranch_scc0 .LBB0_813

; #define PG8_STAGE(bufoff, gbase, voff) do { _Pragma("unroll") for (int _i = 0; _i < 2; ++_i) \
;         __builtin_amdgcn_global_load_lds((const unsigned*)((const char*)(gbase) + (voff)[_i]), (LAS unsigned*)(lds + (bufoff) + ldsw + _i * 8192), 16, 0, 0); } while (0)
; #define PG8_LDA(dst, b, h) do { _Pragma("unroll") for (int m = 0; m < 4; ++m) _Pragma("unroll") for (int k = 0; k < 2; ++k) dst[m][k] = *(const LAS bf16x8*)(lds + PG8_SA(b, h) + aoff + m * 2048 + k * 1024); } while (0)
; #define PG8_LDB(dst, b, h) do { _Pragma("unroll") for (int n = 0; n < 2; ++n) _Pragma("unroll") for (int k = 0; k < 2; ++k) dst[n][k] = *(const LAS bf16x8*)(lds + PG8_SB(b, h) + boff + n * 2048 + k * 1024); } while (0)
; #define PG8_MMA(ai, bj, At, Bt) do { __builtin_amdgcn_s_setprio(1); _Pragma("unroll") for (int m = 0; m < 4; ++m) _Pragma("unroll") for (int n = 0; n < 2; ++n) _Pragma("unroll") for (int k = 0; k < 2; ++k) \
;         acc[ai][bj][m][n] = __builtin_amdgcn_mfma_f32_16x16x32_bf16(Bt[n][k], At[m][k], acc[ai][bj][m][n], 0, 0, 0); __builtin_amdgcn_s_setprio(0); } while (0)
; #define PG8_WAIT_V(n) asm volatile("s_waitcnt vmcnt(" #n ")" ::: "memory")
; #define PG8_WAIT_L(n) asm volatile("s_waitcnt lgkmcnt(" #n ")" ::: "memory")
; #define PG8_BAR __builtin_amdgcn_s_barrier()
; #define PG8_SCHED __builtin_amdgcn_sched_barrier(0)
; template <class Epi>
; DI void gemm_phase(LAS unsigned char* lds, const Gemm g, const StaticOrder& S, const Epi& E) {
;     ...
;             PG8_LDB(B0, 0, 0); PG8_LDB(B1, 0, 1); PG8_SCHED; PG8_LDA(At, 0, 0); PG8_STAGE(PG8_SA(1, 1), a1 + hstepA, voffA);
;             PG8_WAIT_V(8); PG8_WAIT_L(0); PG8_BAR; PG8_MMA(0, 0, At, B0); PG8_MMA(0, 1, At, B1); PG8_BAR; PG8_SCHED;
;             PG8_LDA(At, 0, 1); PG8_STAGE(PG8_SB(0, 0), b2, voffB); PG8_STAGE(PG8_SB(0, 1), b2 + hstepB, voffB); PG8_STAGE(PG8_SA(0, 0), a2, voffA);
;             PG8_WAIT_V(8); PG8_WAIT_L(0); PG8_BAR; PG8_MMA(1, 0, At, B0); PG8_MMA(1, 1, At, B1); PG8_BAR; PG8_SCHED;
.LBB0_972:
	ds_read_b128 v[128:131], v201
	ds_read_b128 v[132:135], v201 offset:1024
	ds_read_b128 v[136:139], v201 offset:2048
	ds_read_b128 v[140:143], v201 offset:3072
	ds_read_b128 v[144:147], v202
	ds_read_b128 v[148:151], v202 offset:1024
	ds_read_b128 v[152:155], v202 offset:2048
	ds_read_b128 v[156:159], v202 offset:3072
	s_add_i32 s55, s30, 2
	s_add_u32 s31, s28, 0xfff00080
	s_addc_u32 s34, s29, -1
	s_cmp_eq_u32 s46, s30
	s_cselect_b32 s30, s52, s53
	s_cselect_b32 s35, s19, s34
	s_cselect_b32 s34, s21, s31
	s_cselect_b32 s31, s51, s54
	v_lshl_add_u64 v[196:197], s[28:29], 0, v[180:181]
	s_add_i32 m0, s27, 0xc000
	ds_read_b128 v[160:163], v203
	ds_read_b128 v[164:167], v203 offset:1024
	ds_read_b128 v[168:171], v203 offset:2048
	ds_read_b128 v[188:191], v203 offset:3072
	ds_read_b128 v[192:195], v203 offset:4096
	ds_read_b128 v[204:207], v203 offset:5120
	ds_read_b128 v[208:211], v203 offset:6144
	ds_read_b128 v[212:215], v203 offset:7168
	global_load_lds_dwordx4 v[196:197], off
	v_lshl_add_u64 v[196:197], s[28:29], 0, v[182:183]
	s_add_i32 m0, s27, 0xe000
	s_nop 0
	global_load_lds_dwordx4 v[196:197], off
	s_waitcnt vmcnt(8)
	s_waitcnt lgkmcnt(0)
	s_setprio 1
	s_barrier
	v_mfma_f32_16x16x32_bf16 v[124:127], v[128:131], v[160:163], v[124:127]
	v_mfma_f32_16x16x32_bf16 v[124:127], v[132:135], v[164:167], v[124:127]
	v_mfma_f32_16x16x32_bf16 v[120:123], v[136:139], v[160:163], v[120:123]
	v_mfma_f32_16x16x32_bf16 v[120:123], v[140:143], v[164:167], v[120:123]
	v_mfma_f32_16x16x32_bf16 v[108:111], v[128:131], v[168:171], v[108:111]
	v_mfma_f32_16x16x32_bf16 v[108:111], v[132:135], v[188:191], v[108:111]
	v_mfma_f32_16x16x32_bf16 v[104:107], v[136:139], v[168:171], v[104:107]
	v_mfma_f32_16x16x32_bf16 v[104:107], v[140:143], v[188:191], v[104:107]
	v_mfma_f32_16x16x32_bf16 v[92:95], v[128:131], v[192:195], v[92:95]
	v_mfma_f32_16x16x32_bf16 v[92:95], v[132:135], v[204:207], v[92:95]
	v_mfma_f32_16x16x32_bf16 v[88:91], v[136:139], v[192:195], v[88:91]
	v_mfma_f32_16x16x32_bf16 v[88:91], v[140:143], v[204:207], v[88:91]
	v_mfma_f32_16x16x32_bf16 v[76:79], v[128:131], v[208:211], v[76:79]
	v_mfma_f32_16x16x32_bf16 v[76:79], v[132:135], v[212:215], v[76:79]
	v_mfma_f32_16x16x32_bf16 v[72:75], v[136:139], v[208:211], v[72:75]
	v_mfma_f32_16x16x32_bf16 v[72:75], v[140:143], v[212:215], v[72:75]
	s_setprio 0
	s_setprio 1
	v_mfma_f32_16x16x32_bf16 v[116:119], v[144:147], v[160:163], v[116:119]
	v_mfma_f32_16x16x32_bf16 v[116:119], v[148:151], v[164:167], v[116:119]
	v_mfma_f32_16x16x32_bf16 v[112:115], v[152:155], v[160:163], v[112:115]
	v_mfma_f32_16x16x32_bf16 v[112:115], v[156:159], v[164:167], v[112:115]
	v_mfma_f32_16x16x32_bf16 v[100:103], v[144:147], v[168:171], v[100:103]
	v_mfma_f32_16x16x32_bf16 v[100:103], v[148:151], v[188:191], v[100:103]
	v_mfma_f32_16x16x32_bf16 v[96:99], v[152:155], v[168:171], v[96:99]
	v_mfma_f32_16x16x32_bf16 v[96:99], v[156:159], v[188:191], v[96:99]
	v_mfma_f32_16x16x32_bf16 v[84:87], v[144:147], v[192:195], v[84:87]
	v_mfma_f32_16x16x32_bf16 v[84:87], v[148:151], v[204:207], v[84:87]
	v_mfma_f32_16x16x32_bf16 v[80:83], v[152:155], v[192:195], v[80:83]
	v_mfma_f32_16x16x32_bf16 v[80:83], v[156:159], v[204:207], v[80:83]
	v_mfma_f32_16x16x32_bf16 v[68:71], v[144:147], v[208:211], v[68:71]
	v_mfma_f32_16x16x32_bf16 v[68:71], v[148:151], v[212:215], v[68:71]
	v_mfma_f32_16x16x32_bf16 v[64:67], v[152:155], v[208:211], v[64:67]
	v_mfma_f32_16x16x32_bf16 v[64:67], v[156:159], v[212:215], v[64:67]
	s_setprio 0
	s_barrier
	s_add_i32 s56, s48, s38
	v_lshl_add_u64 v[196:197], s[30:31], 0, v[174:175]
	s_mov_b32 m0, s56
	ds_read_b128 v[160:163], v203 offset:16384
	ds_read_b128 v[164:167], v203 offset:17408
	ds_read_b128 v[168:171], v203 offset:18432
	ds_read_b128 v[188:191], v203 offset:19456
	ds_read_b128 v[192:195], v203 offset:20480
	ds_read_b128 v[204:207], v203 offset:21504
	ds_read_b128 v[208:211], v203 offset:22528
	ds_read_b128 v[212:215], v203 offset:23552
	global_load_lds_dwordx4 v[196:197], off
	s_add_i32 m0, s56, 0x2000
	s_add_u32 s56, s30, 0x100000
	v_lshl_add_u64 v[216:217], s[30:31], 0, v[178:179]
	s_addc_u32 s57, s31, 0
	s_add_i32 s58, s49, s38
	global_load_lds_dwordx4 v[216:217], off
	v_lshl_add_u64 v[218:219], s[56:57], 0, v[174:175]
	s_mov_b32 m0, s58
	v_lshl_add_u64 v[220:221], s[34:35], 0, v[176:177]
	global_load_lds_dwordx4 v[218:219], off
	v_lshl_add_u64 v[218:219], s[56:57], 0, v[178:179]
	s_add_i32 m0, s58, 0x2000
	s_nop 0
	global_load_lds_dwordx4 v[218:219], off
	v_lshl_add_u64 v[218:219], s[34:35], 0, v[172:173]
	s_mov_b32 m0, s27
	s_nop 0
	global_load_lds_dwordx4 v[218:219], off
	s_mov_b32 m0, s39
	s_nop 0
	global_load_lds_dwordx4 v[220:221], off
	s_waitcnt vmcnt(8)
	s_waitcnt lgkmcnt(0)
	s_setprio 1
	s_barrier
; #define PG8_STAGE(bufoff, gbase, voff) do { _Pragma("unroll") for (int _i = 0; _i < 2; ++_i) \
;         __builtin_amdgcn_global_load_lds((const unsigned*)((const char*)(gbase) + (voff)[_i]), (LAS unsigned*)(lds + (bufoff) + ldsw + _i * 8192), 16, 0, 0); } while (0)
; #define PG8_LDA(dst, b, h) do { _Pragma("unroll") for (int m = 0; m < 4; ++m) _Pragma("unroll") for (int k = 0; k < 2; ++k) dst[m][k] = *(const LAS bf16x8*)(lds + PG8_SA(b, h) + aoff + m * 2048 + k * 1024); } while (0)
; #define PG8_LDB(dst, b, h) do { _Pragma("unroll") for (int n = 0; n < 2; ++n) _Pragma("unroll") for (int k = 0; k < 2; ++k) dst[n][k] = *(const LAS bf16x8*)(lds + PG8_SB(b, h) + boff + n * 2048 + k * 1024); } while (0)
; #define PG8_MMA(ai, bj, At, Bt) do { __builtin_amdgcn_s_setprio(1); _Pragma("unroll") for (int m = 0; m < 4; ++m) _Pragma("unroll") for (int n = 0; n < 2; ++n) _Pragma("unroll") for (int k = 0; k < 2; ++k) \
;         acc[ai][bj][m][n] = __builtin_amdgcn_mfma_f32_16x16x32_bf16(Bt[n][k], At[m][k], acc[ai][bj][m][n], 0, 0, 0); __builtin_amdgcn_s_setprio(0); } while (0)
; #define PG8_WAIT_V(n) asm volatile("s_waitcnt vmcnt(" #n ")" ::: "memory")
; #define PG8_WAIT_L(n) asm volatile("s_waitcnt lgkmcnt(" #n ")" ::: "memory")
; #define PG8_BAR __builtin_amdgcn_s_barrier()
; #define PG8_SCHED __builtin_amdgcn_sched_barrier(0)
; template <class Epi>
; DI void gemm_phase(LAS unsigned char* lds, const Gemm g, const StaticOrder& S, const Epi& E) {
;     ...
;             PG8_WAIT_V(8); PG8_WAIT_L(0); PG8_BAR; PG8_MMA(1, 0, At, B0); PG8_MMA(1, 1, At, B1); PG8_BAR; PG8_SCHED;
;             PG8_LDB(B0, 1, 0); PG8_LDB(B1, 1, 1); PG8_SCHED; PG8_LDA(At, 1, 0); PG8_STAGE(PG8_SA(0, 1), a2 + hstepA, voffA);
;             PG8_WAIT_V(8); PG8_WAIT_L(0); PG8_BAR; PG8_MMA(0, 0, At, B0); PG8_MMA(0, 1, At, B1); PG8_BAR; PG8_SCHED;
	v_mfma_f32_16x16x32_bf16 v[60:63], v[128:131], v[160:163], v[60:63]
	v_mfma_f32_16x16x32_bf16 v[60:63], v[132:135], v[164:167], v[60:63]
	v_mfma_f32_16x16x32_bf16 v[56:59], v[136:139], v[160:163], v[56:59]
	v_mfma_f32_16x16x32_bf16 v[56:59], v[140:143], v[164:167], v[56:59]
	v_mfma_f32_16x16x32_bf16 v[44:47], v[128:131], v[168:171], v[44:47]
	v_mfma_f32_16x16x32_bf16 v[44:47], v[132:135], v[188:191], v[44:47]
	v_mfma_f32_16x16x32_bf16 v[40:43], v[136:139], v[168:171], v[40:43]
	v_mfma_f32_16x16x32_bf16 v[40:43], v[140:143], v[188:191], v[40:43]
	v_mfma_f32_16x16x32_bf16 v[28:31], v[128:131], v[192:195], v[28:31]
	v_mfma_f32_16x16x32_bf16 v[28:31], v[132:135], v[204:207], v[28:31]
	v_mfma_f32_16x16x32_bf16 v[24:27], v[136:139], v[192:195], v[24:27]
	v_mfma_f32_16x16x32_bf16 v[24:27], v[140:143], v[204:207], v[24:27]
	v_mfma_f32_16x16x32_bf16 v[12:15], v[128:131], v[208:211], v[12:15]
	v_mfma_f32_16x16x32_bf16 v[12:15], v[132:135], v[212:215], v[12:15]
	v_mfma_f32_16x16x32_bf16 v[8:11], v[136:139], v[208:211], v[8:11]
	v_mfma_f32_16x16x32_bf16 v[8:11], v[140:143], v[212:215], v[8:11]
	s_setprio 0
	s_setprio 1
	v_mfma_f32_16x16x32_bf16 v[52:55], v[144:147], v[160:163], v[52:55]
	v_mfma_f32_16x16x32_bf16 v[52:55], v[148:151], v[164:167], v[52:55]
	v_mfma_f32_16x16x32_bf16 v[48:51], v[152:155], v[160:163], v[48:51]
	v_mfma_f32_16x16x32_bf16 v[48:51], v[156:159], v[164:167], v[48:51]
	v_mfma_f32_16x16x32_bf16 v[36:39], v[144:147], v[168:171], v[36:39]
	v_mfma_f32_16x16x32_bf16 v[36:39], v[148:151], v[188:191], v[36:39]
	v_mfma_f32_16x16x32_bf16 v[32:35], v[152:155], v[168:171], v[32:35]
	v_mfma_f32_16x16x32_bf16 v[32:35], v[156:159], v[188:191], v[32:35]
	v_mfma_f32_16x16x32_bf16 v[20:23], v[144:147], v[192:195], v[20:23]
	v_mfma_f32_16x16x32_bf16 v[20:23], v[148:151], v[204:207], v[20:23]
	v_mfma_f32_16x16x32_bf16 v[16:19], v[152:155], v[192:195], v[16:19]
	v_mfma_f32_16x16x32_bf16 v[16:19], v[156:159], v[204:207], v[16:19]
	v_mfma_f32_16x16x32_bf16 v[4:7], v[144:147], v[208:211], v[4:7]
	v_mfma_f32_16x16x32_bf16 v[4:7], v[148:151], v[212:215], v[4:7]
	v_mfma_f32_16x16x32_bf16 v[0:3], v[152:155], v[208:211], v[0:3]
	v_mfma_f32_16x16x32_bf16 v[0:3], v[156:159], v[212:215], v[0:3]
	s_setprio 0
	s_barrier
	s_add_i32 s56, 0, 0x18000
	s_add_i32 s57, 0, 0x1c000
	v_add_u32_e32 v140, s56, v199
	v_add_u32_e32 v156, s57, v199
	ds_read_b128 v[128:131], v140
	ds_read_b128 v[132:135], v140 offset:1024
	ds_read_b128 v[136:139], v140 offset:2048
	ds_read_b128 v[140:143], v140 offset:3072
	ds_read_b128 v[144:147], v156
	ds_read_b128 v[148:151], v156 offset:1024
	ds_read_b128 v[152:155], v156 offset:2048
	ds_read_b128 v[156:159], v156 offset:3072
	s_add_u32 s34, s34, 0x100000
	s_addc_u32 s35, s35, 0
	s_mov_b32 m0, s40
	v_lshl_add_u64 v[222:223], s[34:35], 0, v[172:173]
	ds_read_b128 v[160:163], v203 offset:32768
	ds_read_b128 v[164:167], v203 offset:33792
	ds_read_b128 v[168:171], v203 offset:34816
	ds_read_b128 v[188:191], v203 offset:35840
	ds_read_b128 v[192:195], v203 offset:36864
	ds_read_b128 v[204:207], v203 offset:37888
	ds_read_b128 v[208:211], v203 offset:38912
	ds_read_b128 v[212:215], v203 offset:39936
	global_load_lds_dwordx4 v[222:223], off
	v_lshl_add_u64 v[222:223], s[34:35], 0, v[176:177]
	s_mov_b32 m0, s41
	s_nop 0
	global_load_lds_dwordx4 v[222:223], off
	s_waitcnt vmcnt(8)
	s_waitcnt lgkmcnt(0)
	s_setprio 1
	s_barrier
	v_mfma_f32_16x16x32_bf16 v[124:127], v[128:131], v[160:163], v[124:127]
	v_mfma_f32_16x16x32_bf16 v[124:127], v[132:135], v[164:167], v[124:127]
	v_mfma_f32_16x16x32_bf16 v[120:123], v[136:139], v[160:163], v[120:123]
	v_mfma_f32_16x16x32_bf16 v[120:123], v[140:143], v[164:167], v[120:123]
	v_mfma_f32_16x16x32_bf16 v[108:111], v[128:131], v[168:171], v[108:111]
	v_mfma_f32_16x16x32_bf16 v[108:111], v[132:135], v[188:191], v[108:111]
	v_mfma_f32_16x16x32_bf16 v[104:107], v[136:139], v[168:171], v[104:107]
	v_mfma_f32_16x16x32_bf16 v[104:107], v[140:143], v[188:191], v[104:107]
	v_mfma_f32_16x16x32_bf16 v[92:95], v[128:131], v[192:195], v[92:95]
	v_mfma_f32_16x16x32_bf16 v[92:95], v[132:135], v[204:207], v[92:95]
	v_mfma_f32_16x16x32_bf16 v[88:91], v[136:139], v[192:195], v[88:91]
	v_mfma_f32_16x16x32_bf16 v[88:91], v[140:143], v[204:207], v[88:91]
	v_mfma_f32_16x16x32_bf16 v[76:79], v[128:131], v[208:211], v[76:79]
	v_mfma_f32_16x16x32_bf16 v[76:79], v[132:135], v[212:215], v[76:79]
	v_mfma_f32_16x16x32_bf16 v[72:75], v[136:139], v[208:211], v[72:75]
	v_mfma_f32_16x16x32_bf16 v[72:75], v[140:143], v[212:215], v[72:75]
	s_setprio 0
	s_setprio 1
	v_mfma_f32_16x16x32_bf16 v[116:119], v[144:147], v[160:163], v[116:119]
	v_mfma_f32_16x16x32_bf16 v[116:119], v[148:151], v[164:167], v[116:119]
	v_mfma_f32_16x16x32_bf16 v[112:115], v[152:155], v[160:163], v[112:115]
	v_mfma_f32_16x16x32_bf16 v[112:115], v[156:159], v[164:167], v[112:115]
	v_mfma_f32_16x16x32_bf16 v[100:103], v[144:147], v[168:171], v[100:103]
	v_mfma_f32_16x16x32_bf16 v[100:103], v[148:151], v[188:191], v[100:103]
	v_mfma_f32_16x16x32_bf16 v[96:99], v[152:155], v[168:171], v[96:99]
	v_mfma_f32_16x16x32_bf16 v[96:99], v[156:159], v[188:191], v[96:99]
	v_mfma_f32_16x16x32_bf16 v[84:87], v[144:147], v[192:195], v[84:87]
	v_mfma_f32_16x16x32_bf16 v[84:87], v[148:151], v[204:207], v[84:87]
	v_mfma_f32_16x16x32_bf16 v[80:83], v[152:155], v[192:195], v[80:83]
	v_mfma_f32_16x16x32_bf16 v[80:83], v[156:159], v[204:207], v[80:83]
	v_mfma_f32_16x16x32_bf16 v[68:71], v[144:147], v[208:211], v[68:71]
	v_mfma_f32_16x16x32_bf16 v[68:71], v[148:151], v[212:215], v[68:71]
	v_mfma_f32_16x16x32_bf16 v[64:67], v[152:155], v[208:211], v[64:67]
	v_mfma_f32_16x16x32_bf16 v[64:67], v[156:159], v[212:215], v[64:67]
	s_setprio 0
	s_barrier
; #define PG8_STAGE(bufoff, gbase, voff) do { _Pragma("unroll") for (int _i = 0; _i < 2; ++_i) \
;         __builtin_amdgcn_global_load_lds((const unsigned*)((const char*)(gbase) + (voff)[_i]), (LAS unsigned*)(lds + (bufoff) + ldsw + _i * 8192), 16, 0, 0); } while (0)
; #define PG8_LDA(dst, b, h) do { _Pragma("unroll") for (int m = 0; m < 4; ++m) _Pragma("unroll") for (int k = 0; k < 2; ++k) dst[m][k] = *(const LAS bf16x8*)(lds + PG8_SA(b, h) + aoff + m * 2048 + k * 1024); } while (0)
; #define PG8_MMA(ai, bj, At, Bt) do { __builtin_amdgcn_s_setprio(1); _Pragma("unroll") for (int m = 0; m < 4; ++m) _Pragma("unroll") for (int n = 0; n < 2; ++n) _Pragma("unroll") for (int k = 0; k < 2; ++k) \
;         acc[ai][bj][m][n] = __builtin_amdgcn_mfma_f32_16x16x32_bf16(Bt[n][k], At[m][k], acc[ai][bj][m][n], 0, 0, 0); __builtin_amdgcn_s_setprio(0); } while (0)
; #define PG8_WAIT_V(n) asm volatile("s_waitcnt vmcnt(" #n ")" ::: "memory")
; #define PG8_WAIT_L(n) asm volatile("s_waitcnt lgkmcnt(" #n ")" ::: "memory")
; #define PG8_BAR __builtin_amdgcn_s_barrier()
; #define PG8_SCHED __builtin_amdgcn_sched_barrier(0)
; template <class Epi>
; DI void gemm_phase(LAS unsigned char* lds, const Gemm g, const StaticOrder& S, const Epi& E) {
;     ...
;             PG8_LDA(At, 1, 1); PG8_STAGE(PG8_SB(1, 0), b3, voffB); PG8_STAGE(PG8_SB(1, 1), b3 + hstepB, voffB); PG8_STAGE(PG8_SA(1, 0), a3, voffA);
;             PG8_WAIT_V(8); PG8_WAIT_L(0); PG8_BAR; PG8_MMA(1, 0, At, B0); PG8_MMA(1, 1, At, B1); PG8_BAR; PG8_SCHED;
;         }
	s_add_i32 s34, s56, s38
	v_lshl_add_u64 v[196:197], v[196:197], 0, s[12:13]
	s_mov_b32 m0, s34
	ds_read_b128 v[160:163], v203 offset:49152
	ds_read_b128 v[164:167], v203 offset:50176
	ds_read_b128 v[168:171], v203 offset:51200
	ds_read_b128 v[188:191], v203 offset:52224
	ds_read_b128 v[192:195], v203 offset:53248
	ds_read_b128 v[204:207], v203 offset:54272
	ds_read_b128 v[208:211], v203 offset:55296
	ds_read_b128 v[212:215], v203 offset:56320
	global_load_lds_dwordx4 v[196:197], off
	s_add_i32 m0, s34, 0x2000
	s_add_u32 s30, s30, 0x100080
	v_lshl_add_u64 v[196:197], v[216:217], 0, s[12:13]
	s_addc_u32 s31, s31, 0
	s_add_i32 s34, s57, s38
	global_load_lds_dwordx4 v[196:197], off
	v_lshl_add_u64 v[196:197], s[30:31], 0, v[174:175]
	s_mov_b32 m0, s34
	s_nop 0
	global_load_lds_dwordx4 v[196:197], off
	v_lshl_add_u64 v[196:197], s[30:31], 0, v[178:179]
	s_add_i32 m0, s34, 0x2000
	s_nop 0
	global_load_lds_dwordx4 v[196:197], off
	v_lshl_add_u64 v[196:197], v[218:219], 0, s[12:13]
	s_mov_b32 m0, s44
	s_nop 0
	global_load_lds_dwordx4 v[196:197], off
	v_lshl_add_u64 v[196:197], v[220:221], 0, s[12:13]
	s_mov_b32 m0, s45
	s_nop 0
	global_load_lds_dwordx4 v[196:197], off
	s_waitcnt vmcnt(8)
	s_waitcnt lgkmcnt(0)
	s_setprio 1
	s_barrier
	v_mfma_f32_16x16x32_bf16 v[60:63], v[128:131], v[160:163], v[60:63]
	v_mfma_f32_16x16x32_bf16 v[60:63], v[132:135], v[164:167], v[60:63]
	v_mfma_f32_16x16x32_bf16 v[56:59], v[136:139], v[160:163], v[56:59]
	v_mfma_f32_16x16x32_bf16 v[56:59], v[140:143], v[164:167], v[56:59]
	v_mfma_f32_16x16x32_bf16 v[44:47], v[128:131], v[168:171], v[44:47]
	v_mfma_f32_16x16x32_bf16 v[44:47], v[132:135], v[188:191], v[44:47]
	v_mfma_f32_16x16x32_bf16 v[40:43], v[136:139], v[168:171], v[40:43]
	v_mfma_f32_16x16x32_bf16 v[40:43], v[140:143], v[188:191], v[40:43]
	v_mfma_f32_16x16x32_bf16 v[28:31], v[128:131], v[192:195], v[28:31]
	v_mfma_f32_16x16x32_bf16 v[28:31], v[132:135], v[204:207], v[28:31]
	v_mfma_f32_16x16x32_bf16 v[24:27], v[136:139], v[192:195], v[24:27]
	v_mfma_f32_16x16x32_bf16 v[24:27], v[140:143], v[204:207], v[24:27]
	v_mfma_f32_16x16x32_bf16 v[12:15], v[128:131], v[208:211], v[12:15]
	v_mfma_f32_16x16x32_bf16 v[12:15], v[132:135], v[212:215], v[12:15]
	v_mfma_f32_16x16x32_bf16 v[8:11], v[136:139], v[208:211], v[8:11]
	v_mfma_f32_16x16x32_bf16 v[8:11], v[140:143], v[212:215], v[8:11]
	s_setprio 0
	s_setprio 1
	v_mfma_f32_16x16x32_bf16 v[52:55], v[144:147], v[160:163], v[52:55]
	v_mfma_f32_16x16x32_bf16 v[52:55], v[148:151], v[164:167], v[52:55]
	v_mfma_f32_16x16x32_bf16 v[48:51], v[152:155], v[160:163], v[48:51]
	v_mfma_f32_16x16x32_bf16 v[48:51], v[156:159], v[164:167], v[48:51]
	v_mfma_f32_16x16x32_bf16 v[36:39], v[144:147], v[168:171], v[36:39]
	v_mfma_f32_16x16x32_bf16 v[36:39], v[148:151], v[188:191], v[36:39]
	v_mfma_f32_16x16x32_bf16 v[32:35], v[152:155], v[168:171], v[32:35]
	v_mfma_f32_16x16x32_bf16 v[32:35], v[156:159], v[188:191], v[32:35]
	v_mfma_f32_16x16x32_bf16 v[20:23], v[144:147], v[192:195], v[20:23]
	v_mfma_f32_16x16x32_bf16 v[20:23], v[148:151], v[204:207], v[20:23]
	v_mfma_f32_16x16x32_bf16 v[16:19], v[152:155], v[192:195], v[16:19]
	v_mfma_f32_16x16x32_bf16 v[16:19], v[156:159], v[204:207], v[16:19]
	v_mfma_f32_16x16x32_bf16 v[4:7], v[144:147], v[208:211], v[4:7]
	v_mfma_f32_16x16x32_bf16 v[4:7], v[148:151], v[212:215], v[4:7]
	v_mfma_f32_16x16x32_bf16 v[0:3], v[152:155], v[208:211], v[0:3]
	v_mfma_f32_16x16x32_bf16 v[0:3], v[156:159], v[212:215], v[0:3]
	s_setprio 0
	s_barrier
	s_add_u32 s28, s28, 0x100
	s_addc_u32 s29, s29, 0
	s_add_u32 s53, s53, 0x100
	s_addc_u32 s54, s54, 0
	s_cmp_ge_i32 s55, s43
	s_mov_b32 s30, s55
	s_cbranch_scc0 .LBB0_972
